# combo32 + nt hint on the 160 read-once epilogue loads (EpiResid / EpiMulAdd rows) of the out, down and ple phases
# baseline (speedup 1.0000x reference)
; __device__ __forceinline__ unsigned pk2(float lo, float hi) { f32x2_t v = {lo, hi}; bf16x2_t b = __builtin_convertvector(v, bf16x2_t); return __builtin_bit_cast(unsigned, b); }
; __device__ __forceinline__ float xor16_sum(float v) { const auto r = __builtin_amdgcn_permlane16_swap(__float_as_uint(v), __float_as_uint(v), false, false); return __uint_as_float(r[0]) + __uint_as_float(r[1]); }
; __device__ __forceinline__ float xor32_sum(float v) { const auto r = __builtin_amdgcn_permlane32_swap(__float_as_uint(v), __float_as_uint(v), false, false); return __uint_as_float(r[0]) + __uint_as_float(r[1]); }
; #define BF16_LO(w) __uint_as_float((w) << 16)
; #define BF16_HI(w) __uint_as_float((w) & 0xffff0000u)
;     __device__ __forceinline__ void operator()(const f32x4 (&acc)[2][2][4][2], const Unit& u, int wr, int wc, int fr_in, int fq_in) const {
;     ...
; #pragma unroll
;         for (int ai = 0; ai < 2; ++ai)
; #pragma unroll
;             for (int m = 0; m < 4; ++m) {
;                 const int row = u.pm * BM + ai * 128 + wr * 64 + m * 16 + fr;
;                 float s = 0.f;
; #pragma unroll
;                 for (int bj = 0; bj < 2; ++bj) {
;                     const size_t off = (size_t)row * DM + u.pn * BM + bj * HALF + wc * 32 + 8 * fq;
;                     f32x4 b0, b1;
;                     if (xbase) { b0 = *(const f32x4*)(xbase + off); b1 = *(const f32x4*)(xbase + off + 4); }
;                     else { const u32x4 q = *(const u32x4*)(hb + off);
;                         b0 = (f32x4){BF16_LO(q.x), BF16_HI(q.x), BF16_LO(q.y), BF16_HI(q.y)}; b1 = (f32x4){BF16_LO(q.z), BF16_HI(q.z), BF16_LO(q.w), BF16_HI(q.w)}; }
;                     const f32x4 h0 = b0 + acc[ai][bj][m][0], h1 = b1 + acc[ai][bj][m][1];
;                     u32x4 w; w.x = pk2(h0[0], h0[1]); w.y = pk2(h0[2], h0[3]); w.z = pk2(h1[0], h1[1]); w.w = pk2(h1[2], h1[3]);
;                     *(u32x4*)(hb + off) = w;
;                     s += (h0[0] * h0[0] + h0[1] * h0[1]) + (h0[2] * h0[2] + h0[3] * h0[3]) + (h1[0] * h1[0] + h1[1] * h1[1]) + (h1[2] * h1[2] + h1[3] * h1[3]);
;                 }
;                 s = xor32_sum(xor16_sum(s));
;                 if (fq == 0) xch[(ai * 128 + wr * 64 + m * 16 + fr) * 4 + wc] = s;
.LBB0_536:
	v_mov_b32_e32 v182, v163
	v_mov_b32_e32 v184, v162
	s_lshl_b32 s36, s10, 8
	v_add_u32_e32 v183, s48, v182
	s_lshl_b32 s0, s4, 8
	v_add_u32_e32 v152, s36, v183
	s_ashr_i32 s1, s0, 31
	v_lshlrev_b32_e32 v128, 3, v184
	v_ashrrev_i32_e32 v129, 31, v128
	s_or_b64 s[0:1], s[0:1], s[18:19]
	v_ashrrev_i32_e32 v153, 31, v152
	v_lshl_add_u64 v[154:155], s[0:1], 0, v[128:129]
	v_lshlrev_b64 v[128:129], 10, v[152:153]
	v_lshl_add_u64 v[156:157], v[128:129], 0, v[154:155]
	s_and_b64 vcc, exec, s[24:25]
	v_lshl_add_u64 v[158:159], v[156:157], 2, s[6:7]
	s_cbranch_vccz .LBB0_605
	global_load_dwordx4 v[132:135], v[158:159], off offset:16 nt
	global_load_dwordx4 v[128:131], v[158:159], off nt
	v_lshl_add_u64 v[156:157], v[156:157], 1, s[16:17]
	s_cbranch_execnz .LBB0_539
.LBB0_538:
	global_load_dwordx4 v[132:135], v[156:157], off nt
	s_waitcnt vmcnt(0)
	v_lshlrev_b32_e32 v128, 16, v132
	v_and_b32_e32 v129, 0xffff0000, v132
	v_lshlrev_b32_e32 v130, 16, v133
	v_and_b32_e32 v131, 0xffff0000, v133
	v_lshlrev_b32_e32 v132, 16, v134
	v_and_b32_e32 v133, 0xffff0000, v134
	v_lshlrev_b32_e32 v134, 16, v135
	v_and_b32_e32 v135, 0xffff0000, v135
.LBB0_539:
	s_waitcnt vmcnt(0)
	v_pk_add_f32 v[130:131], v[126:127], v[130:131]
	v_pk_add_f32 v[160:161], v[124:125], v[128:129]
	v_pk_add_f32 v[128:129], v[122:123], v[134:135]
	v_pk_add_f32 v[132:133], v[120:121], v[132:133]
	v_cndmask_b32_e64 v124, 0, 1, s[24:25]
	v_cvt_pk_bf16_f32 v120, v160, v161
	v_cvt_pk_bf16_f32 v121, v130, v131
	v_cvt_pk_bf16_f32 v122, v132, v133
	v_cvt_pk_bf16_f32 v123, v128, v129
	v_cmp_ne_u32_e64 s[12:13], 1, v124
	s_andn2_b64 vcc, exec, s[24:25]
	global_store_dwordx4 v[156:157], v[120:123], off
	s_cbranch_vccnz .LBB0_606
	global_load_dwordx4 v[124:127], v[158:159], off offset:528 nt
	global_load_dwordx4 v[120:123], v[158:159], off offset:512 nt
	s_cbranch_execnz .LBB0_542
.LBB0_541:
	global_load_dwordx4 v[124:127], v[156:157], off offset:256 nt
	s_waitcnt vmcnt(0)
	v_lshlrev_b32_e32 v120, 16, v124
	v_and_b32_e32 v121, 0xffff0000, v124
	v_lshlrev_b32_e32 v122, 16, v125
	v_and_b32_e32 v123, 0xffff0000, v125
	v_lshlrev_b32_e32 v124, 16, v126
	v_and_b32_e32 v125, 0xffff0000, v126
	v_lshlrev_b32_e32 v126, 16, v127
	v_and_b32_e32 v127, 0xffff0000, v127
.LBB0_542:
	s_waitcnt vmcnt(0)
	v_pk_add_f32 v[118:119], v[118:119], v[122:123]
	v_pk_add_f32 v[116:117], v[116:117], v[120:121]
	v_pk_add_f32 v[120:121], v[114:115], v[126:127]
	v_pk_add_f32 v[122:123], v[112:113], v[124:125]
	v_cvt_pk_bf16_f32 v112, v116, v117
	v_cvt_pk_bf16_f32 v113, v118, v119
	v_cvt_pk_bf16_f32 v114, v122, v123
	v_cvt_pk_bf16_f32 v115, v120, v121
	global_store_dwordx4 v[156:157], v[112:115], off offset:256
	v_mul_f32_e32 v134, v161, v161
	v_mul_f32_e32 v131, v131, v131
	v_mul_f32_e32 v112, v117, v117
	v_mul_f32_e32 v113, v119, v119
	v_fmac_f32_e32 v112, v116, v116
	v_fmac_f32_e32 v113, v118, v118
	v_fmac_f32_e32 v134, v160, v160
	v_fmac_f32_e32 v131, v130, v130
	v_add_f32_e32 v112, v112, v113
	v_mul_f32_e32 v113, v123, v123
	v_add_f32_e32 v130, v134, v131
	v_mul_f32_e32 v131, v133, v133
	v_fmac_f32_e32 v113, v122, v122
	v_fmac_f32_e32 v131, v132, v132
	v_mul_f32_e32 v129, v129, v129
	v_add_f32_e32 v112, v113, v112
	v_mul_f32_e32 v113, v121, v121
	v_add_f32_e32 v130, v131, v130
	v_fmac_f32_e32 v129, v128, v128
	v_fmac_f32_e32 v113, v120, v120
	v_add_f32_e32 v128, v129, v130
	v_add_f32_e32 v112, v113, v112
	v_add_f32_e32 v112, v128, v112
	v_mov_b32_e32 v113, v112
	s_nop 1
	v_permlane16_swap_b32_e32 v112, v113
	v_add_f32_e32 v112, v112, v113
	v_mov_b32_e32 v113, v112
	v_cmp_eq_u32_e64 s[10:11], 0, v184
	s_nop 0
	v_permlane32_swap_b32_e32 v112, v113
	v_lshl_add_u32 v126, v183, 4, s58
	s_and_saveexec_b64 s[0:1], s[10:11]
	v_add_f32_e32 v112, v112, v113
	ds_write_b32 v126, v112
	s_or_b64 exec, exec, s[0:1]
	v_add_u32_e32 v112, 16, v152
	v_ashrrev_i32_e32 v113, 31, v112
	v_lshlrev_b64 v[112:113], 10, v[112:113]
	v_lshl_add_u64 v[120:121], v[112:113], 0, v[154:155]
	s_and_b64 vcc, exec, s[12:13]
	v_lshl_add_u64 v[122:123], v[120:121], 2, s[6:7]
	s_cbranch_vccnz .LBB0_607
	global_load_dwordx4 v[116:119], v[122:123], off offset:16 nt
	global_load_dwordx4 v[112:115], v[122:123], off nt
	v_lshl_add_u64 v[120:121], v[120:121], 1, s[16:17]
	s_cbranch_execnz .LBB0_547
.LBB0_546:
	global_load_dwordx4 v[116:119], v[120:121], off nt
	s_waitcnt vmcnt(0)
	v_lshlrev_b32_e32 v112, 16, v116
	v_and_b32_e32 v113, 0xffff0000, v116
	v_lshlrev_b32_e32 v114, 16, v117
	v_and_b32_e32 v115, 0xffff0000, v117
	v_lshlrev_b32_e32 v116, 16, v118
	v_and_b32_e32 v117, 0xffff0000, v118
	v_lshlrev_b32_e32 v118, 16, v119
	v_and_b32_e32 v119, 0xffff0000, v119
.LBB0_547:
	s_waitcnt vmcnt(0)
	v_pk_add_f32 v[114:115], v[110:111], v[114:115]
	v_pk_add_f32 v[124:125], v[108:109], v[112:113]
	v_pk_add_f32 v[112:113], v[106:107], v[118:119]
	v_pk_add_f32 v[116:117], v[104:105], v[116:117]
	v_cvt_pk_bf16_f32 v104, v124, v125
	v_cvt_pk_bf16_f32 v105, v114, v115
	v_cvt_pk_bf16_f32 v106, v116, v117
	v_cvt_pk_bf16_f32 v107, v112, v113
	s_and_b64 vcc, exec, s[12:13]
	global_store_dwordx4 v[120:121], v[104:107], off
	s_cbranch_vccnz .LBB0_608
	global_load_dwordx4 v[108:111], v[122:123], off offset:528 nt
	global_load_dwordx4 v[104:107], v[122:123], off offset:512 nt
	s_cbranch_execnz .LBB0_550
.LBB0_549:
	global_load_dwordx4 v[108:111], v[120:121], off offset:256 nt
	s_waitcnt vmcnt(0)
	v_lshlrev_b32_e32 v104, 16, v108
	v_and_b32_e32 v105, 0xffff0000, v108
	v_lshlrev_b32_e32 v106, 16, v109
	v_and_b32_e32 v107, 0xffff0000, v109
	v_lshlrev_b32_e32 v108, 16, v110
	v_and_b32_e32 v109, 0xffff0000, v110
	v_lshlrev_b32_e32 v110, 16, v111
	v_and_b32_e32 v111, 0xffff0000, v111
; __device__ __forceinline__ unsigned pk2(float lo, float hi) { f32x2_t v = {lo, hi}; bf16x2_t b = __builtin_convertvector(v, bf16x2_t); return __builtin_bit_cast(unsigned, b); }
; __device__ __forceinline__ float xor16_sum(float v) { const auto r = __builtin_amdgcn_permlane16_swap(__float_as_uint(v), __float_as_uint(v), false, false); return __uint_as_float(r[0]) + __uint_as_float(r[1]); }
; __device__ __forceinline__ float xor32_sum(float v) { const auto r = __builtin_amdgcn_permlane32_swap(__float_as_uint(v), __float_as_uint(v), false, false); return __uint_as_float(r[0]) + __uint_as_float(r[1]); }
; #define BF16_LO(w) __uint_as_float((w) << 16)
; #define BF16_HI(w) __uint_as_float((w) & 0xffff0000u)
;     __device__ __forceinline__ void operator()(const f32x4 (&acc)[2][2][4][2], const Unit& u, int wr, int wc, int fr_in, int fq_in) const {
;     ...
; #pragma unroll
;         for (int ai = 0; ai < 2; ++ai)
; #pragma unroll
;             for (int m = 0; m < 4; ++m) {
;                 const int row = u.pm * BM + ai * 128 + wr * 64 + m * 16 + fr;
;                 float s = 0.f;
; #pragma unroll
;                 for (int bj = 0; bj < 2; ++bj) {
;                     const size_t off = (size_t)row * DM + u.pn * BM + bj * HALF + wc * 32 + 8 * fq;
;                     f32x4 b0, b1;
;                     if (xbase) { b0 = *(const f32x4*)(xbase + off); b1 = *(const f32x4*)(xbase + off + 4); }
;                     else { const u32x4 q = *(const u32x4*)(hb + off);
;                         b0 = (f32x4){BF16_LO(q.x), BF16_HI(q.x), BF16_LO(q.y), BF16_HI(q.y)}; b1 = (f32x4){BF16_LO(q.z), BF16_HI(q.z), BF16_LO(q.w), BF16_HI(q.w)}; }
;                     const f32x4 h0 = b0 + acc[ai][bj][m][0], h1 = b1 + acc[ai][bj][m][1];
;                     u32x4 w; w.x = pk2(h0[0], h0[1]); w.y = pk2(h0[2], h0[3]); w.z = pk2(h1[0], h1[1]); w.w = pk2(h1[2], h1[3]);
;                     *(u32x4*)(hb + off) = w;
;                     s += (h0[0] * h0[0] + h0[1] * h0[1]) + (h0[2] * h0[2] + h0[3] * h0[3]) + (h1[0] * h1[0] + h1[1] * h1[1]) + (h1[2] * h1[2] + h1[3] * h1[3]);
;                 }
;                 s = xor32_sum(xor16_sum(s));
;                 if (fq == 0) xch[(ai * 128 + wr * 64 + m * 16 + fr) * 4 + wc] = s;
.LBB0_550:
	s_waitcnt vmcnt(0)
	v_pk_add_f32 v[102:103], v[102:103], v[106:107]
	v_pk_add_f32 v[100:101], v[100:101], v[104:105]
	v_pk_add_f32 v[104:105], v[98:99], v[110:111]
	v_pk_add_f32 v[106:107], v[96:97], v[108:109]
	v_cvt_pk_bf16_f32 v96, v100, v101
	v_cvt_pk_bf16_f32 v97, v102, v103
	v_cvt_pk_bf16_f32 v98, v106, v107
	v_cvt_pk_bf16_f32 v99, v104, v105
	global_store_dwordx4 v[120:121], v[96:99], off offset:256
	v_mul_f32_e32 v118, v125, v125
	v_mul_f32_e32 v115, v115, v115
	v_mul_f32_e32 v96, v101, v101
	v_mul_f32_e32 v97, v103, v103
	v_fmac_f32_e32 v96, v100, v100
	v_fmac_f32_e32 v97, v102, v102
	v_fmac_f32_e32 v118, v124, v124
	v_fmac_f32_e32 v115, v114, v114
	v_add_f32_e32 v96, v96, v97
	v_mul_f32_e32 v97, v107, v107
	v_add_f32_e32 v114, v118, v115
	v_mul_f32_e32 v115, v117, v117
	v_fmac_f32_e32 v97, v106, v106
	v_fmac_f32_e32 v115, v116, v116
	v_mul_f32_e32 v113, v113, v113
	v_add_f32_e32 v96, v97, v96
	v_mul_f32_e32 v97, v105, v105
	v_add_f32_e32 v114, v115, v114
	v_fmac_f32_e32 v113, v112, v112
	v_fmac_f32_e32 v97, v104, v104
	v_add_f32_e32 v112, v113, v114
	v_add_f32_e32 v96, v97, v96
	v_add_f32_e32 v96, v112, v96
	v_mov_b32_e32 v97, v96
	s_nop 1
	v_permlane16_swap_b32_e32 v96, v97
	v_add_f32_e32 v96, v96, v97
	v_mov_b32_e32 v97, v96
	s_nop 1
	v_permlane32_swap_b32_e32 v96, v97
	s_and_saveexec_b64 s[0:1], s[10:11]
	v_add_f32_e32 v96, v96, v97
	ds_write_b32 v126, v96 offset:256
	s_or_b64 exec, exec, s[0:1]
	v_add_u32_e32 v96, 32, v152
	v_ashrrev_i32_e32 v97, 31, v96
	v_lshlrev_b64 v[96:97], 10, v[96:97]
	v_lshl_add_u64 v[104:105], v[96:97], 0, v[154:155]
	s_and_b64 vcc, exec, s[12:13]
	v_lshl_add_u64 v[106:107], v[104:105], 2, s[6:7]
	s_cbranch_vccnz .LBB0_609
	global_load_dwordx4 v[100:103], v[106:107], off offset:16 nt
	global_load_dwordx4 v[96:99], v[106:107], off nt
	v_lshl_add_u64 v[104:105], v[104:105], 1, s[16:17]
	s_cbranch_execnz .LBB0_555
.LBB0_554:
	global_load_dwordx4 v[100:103], v[104:105], off nt
	s_waitcnt vmcnt(0)
	v_lshlrev_b32_e32 v96, 16, v100
	v_and_b32_e32 v97, 0xffff0000, v100
	v_lshlrev_b32_e32 v98, 16, v101
	v_and_b32_e32 v99, 0xffff0000, v101
	v_lshlrev_b32_e32 v100, 16, v102
	v_and_b32_e32 v101, 0xffff0000, v102
	v_lshlrev_b32_e32 v102, 16, v103
	v_and_b32_e32 v103, 0xffff0000, v103
.LBB0_555:
	s_waitcnt vmcnt(0)
	v_pk_add_f32 v[98:99], v[94:95], v[98:99]
	v_pk_add_f32 v[108:109], v[92:93], v[96:97]
	v_pk_add_f32 v[96:97], v[90:91], v[102:103]
	v_pk_add_f32 v[100:101], v[88:89], v[100:101]
	v_cvt_pk_bf16_f32 v88, v108, v109
	v_cvt_pk_bf16_f32 v89, v98, v99
	v_cvt_pk_bf16_f32 v90, v100, v101
	v_cvt_pk_bf16_f32 v91, v96, v97
	s_and_b64 vcc, exec, s[12:13]
	global_store_dwordx4 v[104:105], v[88:91], off
	s_cbranch_vccnz .LBB0_610
	global_load_dwordx4 v[92:95], v[106:107], off offset:528 nt
	global_load_dwordx4 v[88:91], v[106:107], off offset:512 nt
	s_cbranch_execnz .LBB0_558
.LBB0_557:
	global_load_dwordx4 v[92:95], v[104:105], off offset:256 nt
	s_waitcnt vmcnt(0)
	v_lshlrev_b32_e32 v88, 16, v92
	v_and_b32_e32 v89, 0xffff0000, v92
	v_lshlrev_b32_e32 v90, 16, v93
	v_and_b32_e32 v91, 0xffff0000, v93
	v_lshlrev_b32_e32 v92, 16, v94
	v_and_b32_e32 v93, 0xffff0000, v94
	v_lshlrev_b32_e32 v94, 16, v95
	v_and_b32_e32 v95, 0xffff0000, v95
.LBB0_558:
	s_waitcnt vmcnt(0)
	v_pk_add_f32 v[86:87], v[86:87], v[90:91]
	v_pk_add_f32 v[84:85], v[84:85], v[88:89]
	v_pk_add_f32 v[88:89], v[82:83], v[94:95]
	v_pk_add_f32 v[90:91], v[80:81], v[92:93]
	v_cvt_pk_bf16_f32 v80, v84, v85
	v_cvt_pk_bf16_f32 v81, v86, v87
	v_cvt_pk_bf16_f32 v82, v90, v91
	v_cvt_pk_bf16_f32 v83, v88, v89
	global_store_dwordx4 v[104:105], v[80:83], off offset:256
	v_mul_f32_e32 v102, v109, v109
	v_mul_f32_e32 v99, v99, v99
	v_mul_f32_e32 v80, v85, v85
	v_mul_f32_e32 v81, v87, v87
	v_fmac_f32_e32 v80, v84, v84
	v_fmac_f32_e32 v81, v86, v86
	v_fmac_f32_e32 v102, v108, v108
	v_fmac_f32_e32 v99, v98, v98
	v_add_f32_e32 v80, v80, v81
	v_mul_f32_e32 v81, v91, v91
	v_add_f32_e32 v98, v102, v99
	v_mul_f32_e32 v99, v101, v101
	v_fmac_f32_e32 v81, v90, v90
	v_fmac_f32_e32 v99, v100, v100
	v_mul_f32_e32 v97, v97, v97
	v_add_f32_e32 v80, v81, v80
	v_mul_f32_e32 v81, v89, v89
	v_add_f32_e32 v98, v99, v98
	v_fmac_f32_e32 v97, v96, v96
	v_fmac_f32_e32 v81, v88, v88
	v_add_f32_e32 v96, v97, v98
	v_add_f32_e32 v80, v81, v80
	v_add_f32_e32 v80, v96, v80
	v_mov_b32_e32 v81, v80
	s_nop 1
	v_permlane16_swap_b32_e32 v80, v81
	v_add_f32_e32 v80, v80, v81
	v_mov_b32_e32 v81, v80
	s_nop 1
	v_permlane32_swap_b32_e32 v80, v81
	s_and_saveexec_b64 s[0:1], s[10:11]
	v_add_f32_e32 v80, v80, v81
	ds_write_b32 v126, v80 offset:512
	s_or_b64 exec, exec, s[0:1]
	v_add_u32_e32 v80, 48, v152
	v_ashrrev_i32_e32 v81, 31, v80
	v_lshlrev_b64 v[80:81], 10, v[80:81]
	v_lshl_add_u64 v[88:89], v[80:81], 0, v[154:155]
	s_and_b64 vcc, exec, s[12:13]
	v_lshl_add_u64 v[90:91], v[88:89], 2, s[6:7]
	s_cbranch_vccnz .LBB0_611
	global_load_dwordx4 v[84:87], v[90:91], off offset:16 nt
	global_load_dwordx4 v[80:83], v[90:91], off nt
	v_lshl_add_u64 v[88:89], v[88:89], 1, s[16:17]
	s_cbranch_execnz .LBB0_563
.LBB0_562:
	global_load_dwordx4 v[84:87], v[88:89], off nt
	s_waitcnt vmcnt(0)
	v_lshlrev_b32_e32 v80, 16, v84
	v_and_b32_e32 v81, 0xffff0000, v84
	v_lshlrev_b32_e32 v82, 16, v85
	v_and_b32_e32 v83, 0xffff0000, v85
	v_lshlrev_b32_e32 v84, 16, v86
	v_and_b32_e32 v85, 0xffff0000, v86
	v_lshlrev_b32_e32 v86, 16, v87
	v_and_b32_e32 v87, 0xffff0000, v87
; __device__ __forceinline__ unsigned pk2(float lo, float hi) { f32x2_t v = {lo, hi}; bf16x2_t b = __builtin_convertvector(v, bf16x2_t); return __builtin_bit_cast(unsigned, b); }
; __device__ __forceinline__ float xor16_sum(float v) { const auto r = __builtin_amdgcn_permlane16_swap(__float_as_uint(v), __float_as_uint(v), false, false); return __uint_as_float(r[0]) + __uint_as_float(r[1]); }
; __device__ __forceinline__ float xor32_sum(float v) { const auto r = __builtin_amdgcn_permlane32_swap(__float_as_uint(v), __float_as_uint(v), false, false); return __uint_as_float(r[0]) + __uint_as_float(r[1]); }
; #define BF16_LO(w) __uint_as_float((w) << 16)
; #define BF16_HI(w) __uint_as_float((w) & 0xffff0000u)
;     __device__ __forceinline__ void operator()(const f32x4 (&acc)[2][2][4][2], const Unit& u, int wr, int wc, int fr_in, int fq_in) const {
;     ...
; #pragma unroll
;         for (int ai = 0; ai < 2; ++ai)
; #pragma unroll
;             for (int m = 0; m < 4; ++m) {
;                 const int row = u.pm * BM + ai * 128 + wr * 64 + m * 16 + fr;
;                 float s = 0.f;
; #pragma unroll
;                 for (int bj = 0; bj < 2; ++bj) {
;                     const size_t off = (size_t)row * DM + u.pn * BM + bj * HALF + wc * 32 + 8 * fq;
;                     f32x4 b0, b1;
;                     if (xbase) { b0 = *(const f32x4*)(xbase + off); b1 = *(const f32x4*)(xbase + off + 4); }
;                     else { const u32x4 q = *(const u32x4*)(hb + off);
;                         b0 = (f32x4){BF16_LO(q.x), BF16_HI(q.x), BF16_LO(q.y), BF16_HI(q.y)}; b1 = (f32x4){BF16_LO(q.z), BF16_HI(q.z), BF16_LO(q.w), BF16_HI(q.w)}; }
;                     const f32x4 h0 = b0 + acc[ai][bj][m][0], h1 = b1 + acc[ai][bj][m][1];
;                     u32x4 w; w.x = pk2(h0[0], h0[1]); w.y = pk2(h0[2], h0[3]); w.z = pk2(h1[0], h1[1]); w.w = pk2(h1[2], h1[3]);
;                     *(u32x4*)(hb + off) = w;
;                     s += (h0[0] * h0[0] + h0[1] * h0[1]) + (h0[2] * h0[2] + h0[3] * h0[3]) + (h1[0] * h1[0] + h1[1] * h1[1]) + (h1[2] * h1[2] + h1[3] * h1[3]);
;                 }
;                 s = xor32_sum(xor16_sum(s));
;                 if (fq == 0) xch[(ai * 128 + wr * 64 + m * 16 + fr) * 4 + wc] = s;
.LBB0_563:
	s_waitcnt vmcnt(0)
	v_pk_add_f32 v[82:83], v[78:79], v[82:83]
	v_pk_add_f32 v[92:93], v[76:77], v[80:81]
	v_pk_add_f32 v[80:81], v[74:75], v[86:87]
	v_pk_add_f32 v[84:85], v[72:73], v[84:85]
	v_cvt_pk_bf16_f32 v72, v92, v93
	v_cvt_pk_bf16_f32 v73, v82, v83
	v_cvt_pk_bf16_f32 v74, v84, v85
	v_cvt_pk_bf16_f32 v75, v80, v81
	s_and_b64 vcc, exec, s[12:13]
	global_store_dwordx4 v[88:89], v[72:75], off
	s_cbranch_vccnz .LBB0_612
	global_load_dwordx4 v[76:79], v[90:91], off offset:528 nt
	global_load_dwordx4 v[72:75], v[90:91], off offset:512 nt
	s_cbranch_execnz .LBB0_566
.LBB0_565:
	global_load_dwordx4 v[76:79], v[88:89], off offset:256 nt
	s_waitcnt vmcnt(0)
	v_lshlrev_b32_e32 v72, 16, v76
	v_and_b32_e32 v73, 0xffff0000, v76
	v_lshlrev_b32_e32 v74, 16, v77
	v_and_b32_e32 v75, 0xffff0000, v77
	v_lshlrev_b32_e32 v76, 16, v78
	v_and_b32_e32 v77, 0xffff0000, v78
	v_lshlrev_b32_e32 v78, 16, v79
	v_and_b32_e32 v79, 0xffff0000, v79
.LBB0_566:
	s_waitcnt vmcnt(0)
	v_pk_add_f32 v[70:71], v[70:71], v[74:75]
	v_pk_add_f32 v[68:69], v[68:69], v[72:73]
	v_pk_add_f32 v[72:73], v[66:67], v[78:79]
	v_pk_add_f32 v[74:75], v[64:65], v[76:77]
	v_cvt_pk_bf16_f32 v64, v68, v69
	v_cvt_pk_bf16_f32 v65, v70, v71
	v_cvt_pk_bf16_f32 v66, v74, v75
	v_cvt_pk_bf16_f32 v67, v72, v73
	global_store_dwordx4 v[88:89], v[64:67], off offset:256
	v_mul_f32_e32 v86, v93, v93
	v_mul_f32_e32 v83, v83, v83
	v_mul_f32_e32 v64, v69, v69
	v_mul_f32_e32 v65, v71, v71
	v_fmac_f32_e32 v64, v68, v68
	v_fmac_f32_e32 v65, v70, v70
	v_fmac_f32_e32 v86, v92, v92
	v_fmac_f32_e32 v83, v82, v82
	v_add_f32_e32 v64, v64, v65
	v_mul_f32_e32 v65, v75, v75
	v_add_f32_e32 v82, v86, v83
	v_mul_f32_e32 v83, v85, v85
	v_fmac_f32_e32 v65, v74, v74
	v_fmac_f32_e32 v83, v84, v84
	v_mul_f32_e32 v81, v81, v81
	v_add_f32_e32 v64, v65, v64
	v_mul_f32_e32 v65, v73, v73
	v_add_f32_e32 v82, v83, v82
	v_fmac_f32_e32 v81, v80, v80
	v_fmac_f32_e32 v65, v72, v72
	v_add_f32_e32 v80, v81, v82
	v_add_f32_e32 v64, v65, v64
	v_add_f32_e32 v64, v80, v64
	v_mov_b32_e32 v65, v64
	s_nop 1
	v_permlane16_swap_b32_e32 v64, v65
	v_add_f32_e32 v64, v64, v65
	v_mov_b32_e32 v65, v64
	s_nop 1
	v_permlane32_swap_b32_e32 v64, v65
	s_and_saveexec_b64 s[0:1], s[10:11]
	v_add_f32_e32 v64, v64, v65
	ds_write_b32 v126, v64 offset:768
	s_or_b64 exec, exec, s[0:1]
	v_add_u32_e32 v64, 0x80, v152
	v_ashrrev_i32_e32 v65, 31, v64
	v_lshlrev_b64 v[64:65], 10, v[64:65]
	v_lshl_add_u64 v[72:73], v[64:65], 0, v[154:155]
	s_and_b64 vcc, exec, s[12:13]
	v_lshl_add_u64 v[74:75], v[72:73], 2, s[6:7]
	s_cbranch_vccnz .LBB0_613
	global_load_dwordx4 v[68:71], v[74:75], off offset:16 nt
	global_load_dwordx4 v[64:67], v[74:75], off nt
	v_lshl_add_u64 v[72:73], v[72:73], 1, s[16:17]
	s_cbranch_execnz .LBB0_571
.LBB0_570:
	global_load_dwordx4 v[68:71], v[72:73], off nt
	s_waitcnt vmcnt(0)
	v_lshlrev_b32_e32 v64, 16, v68
	v_and_b32_e32 v65, 0xffff0000, v68
	v_lshlrev_b32_e32 v66, 16, v69
	v_and_b32_e32 v67, 0xffff0000, v69
	v_lshlrev_b32_e32 v68, 16, v70
	v_and_b32_e32 v69, 0xffff0000, v70
	v_lshlrev_b32_e32 v70, 16, v71
	v_and_b32_e32 v71, 0xffff0000, v71
.LBB0_571:
	s_waitcnt vmcnt(0)
	v_pk_add_f32 v[66:67], v[62:63], v[66:67]
	v_pk_add_f32 v[76:77], v[60:61], v[64:65]
	v_pk_add_f32 v[64:65], v[58:59], v[70:71]
	v_pk_add_f32 v[68:69], v[56:57], v[68:69]
	v_cvt_pk_bf16_f32 v56, v76, v77
	v_cvt_pk_bf16_f32 v57, v66, v67
	v_cvt_pk_bf16_f32 v58, v68, v69
	v_cvt_pk_bf16_f32 v59, v64, v65
	s_and_b64 vcc, exec, s[12:13]
	global_store_dwordx4 v[72:73], v[56:59], off
	s_cbranch_vccnz .LBB0_614
	global_load_dwordx4 v[60:63], v[74:75], off offset:528 nt
	global_load_dwordx4 v[56:59], v[74:75], off offset:512 nt
	s_cbranch_execnz .LBB0_574
.LBB0_573:
	global_load_dwordx4 v[60:63], v[72:73], off offset:256 nt
	s_waitcnt vmcnt(0)
	v_lshlrev_b32_e32 v56, 16, v60
	v_and_b32_e32 v57, 0xffff0000, v60
	v_lshlrev_b32_e32 v58, 16, v61
	v_and_b32_e32 v59, 0xffff0000, v61
	v_lshlrev_b32_e32 v60, 16, v62
	v_and_b32_e32 v61, 0xffff0000, v62
	v_lshlrev_b32_e32 v62, 16, v63
	v_and_b32_e32 v63, 0xffff0000, v63
.LBB0_574:
	s_waitcnt vmcnt(0)
	v_pk_add_f32 v[54:55], v[54:55], v[58:59]
	v_pk_add_f32 v[52:53], v[52:53], v[56:57]
	v_pk_add_f32 v[56:57], v[50:51], v[62:63]
	v_pk_add_f32 v[58:59], v[48:49], v[60:61]
	v_cvt_pk_bf16_f32 v48, v52, v53
	v_cvt_pk_bf16_f32 v49, v54, v55
	v_cvt_pk_bf16_f32 v50, v58, v59
	v_cvt_pk_bf16_f32 v51, v56, v57
	global_store_dwordx4 v[72:73], v[48:51], off offset:256
	v_mul_f32_e32 v70, v77, v77
	v_mul_f32_e32 v67, v67, v67
	v_mul_f32_e32 v48, v53, v53
	v_mul_f32_e32 v49, v55, v55
	v_fmac_f32_e32 v48, v52, v52
	v_fmac_f32_e32 v49, v54, v54
	v_fmac_f32_e32 v70, v76, v76
	v_fmac_f32_e32 v67, v66, v66
	v_add_f32_e32 v48, v48, v49
	v_mul_f32_e32 v49, v59, v59
	v_add_f32_e32 v66, v70, v67
	v_mul_f32_e32 v67, v69, v69
	v_fmac_f32_e32 v49, v58, v58
	v_fmac_f32_e32 v67, v68, v68
	v_mul_f32_e32 v65, v65, v65
	v_add_f32_e32 v48, v49, v48
	v_mul_f32_e32 v49, v57, v57
	v_add_f32_e32 v66, v67, v66
	v_fmac_f32_e32 v65, v64, v64
	v_fmac_f32_e32 v49, v56, v56
	v_add_f32_e32 v64, v65, v66
	v_add_f32_e32 v48, v49, v48
	v_add_f32_e32 v48, v64, v48
	v_mov_b32_e32 v49, v48
	s_nop 1
	v_permlane16_swap_b32_e32 v48, v49
	v_add_f32_e32 v48, v48, v49
	v_mov_b32_e32 v49, v48
	s_nop 1
	v_permlane32_swap_b32_e32 v48, v49
	s_and_saveexec_b64 s[0:1], s[10:11]
	v_add_f32_e32 v48, v48, v49
	ds_write_b32 v126, v48 offset:2048
	s_or_b64 exec, exec, s[0:1]
	v_add_u32_e32 v48, 0x90, v152
	v_ashrrev_i32_e32 v49, 31, v48
	v_lshlrev_b64 v[48:49], 10, v[48:49]
	v_lshl_add_u64 v[56:57], v[48:49], 0, v[154:155]
	s_and_b64 vcc, exec, s[12:13]
	v_lshl_add_u64 v[58:59], v[56:57], 2, s[6:7]
	s_cbranch_vccnz .LBB0_615
	global_load_dwordx4 v[52:55], v[58:59], off offset:16 nt
	global_load_dwordx4 v[48:51], v[58:59], off nt
	v_lshl_add_u64 v[56:57], v[56:57], 1, s[16:17]
	s_cbranch_execnz .LBB0_579
; __device__ __forceinline__ unsigned pk2(float lo, float hi) { f32x2_t v = {lo, hi}; bf16x2_t b = __builtin_convertvector(v, bf16x2_t); return __builtin_bit_cast(unsigned, b); }
; __device__ __forceinline__ float xor16_sum(float v) { const auto r = __builtin_amdgcn_permlane16_swap(__float_as_uint(v), __float_as_uint(v), false, false); return __uint_as_float(r[0]) + __uint_as_float(r[1]); }
; __device__ __forceinline__ float xor32_sum(float v) { const auto r = __builtin_amdgcn_permlane32_swap(__float_as_uint(v), __float_as_uint(v), false, false); return __uint_as_float(r[0]) + __uint_as_float(r[1]); }
; #define BF16_LO(w) __uint_as_float((w) << 16)
; #define BF16_HI(w) __uint_as_float((w) & 0xffff0000u)
;     __device__ __forceinline__ void operator()(const f32x4 (&acc)[2][2][4][2], const Unit& u, int wr, int wc, int fr_in, int fq_in) const {
;     ...
; #pragma unroll
;         for (int ai = 0; ai < 2; ++ai)
; #pragma unroll
;             for (int m = 0; m < 4; ++m) {
;                 const int row = u.pm * BM + ai * 128 + wr * 64 + m * 16 + fr;
;                 float s = 0.f;
; #pragma unroll
;                 for (int bj = 0; bj < 2; ++bj) {
;                     const size_t off = (size_t)row * DM + u.pn * BM + bj * HALF + wc * 32 + 8 * fq;
;                     f32x4 b0, b1;
;                     if (xbase) { b0 = *(const f32x4*)(xbase + off); b1 = *(const f32x4*)(xbase + off + 4); }
;                     else { const u32x4 q = *(const u32x4*)(hb + off);
;                         b0 = (f32x4){BF16_LO(q.x), BF16_HI(q.x), BF16_LO(q.y), BF16_HI(q.y)}; b1 = (f32x4){BF16_LO(q.z), BF16_HI(q.z), BF16_LO(q.w), BF16_HI(q.w)}; }
;                     const f32x4 h0 = b0 + acc[ai][bj][m][0], h1 = b1 + acc[ai][bj][m][1];
;                     u32x4 w; w.x = pk2(h0[0], h0[1]); w.y = pk2(h0[2], h0[3]); w.z = pk2(h1[0], h1[1]); w.w = pk2(h1[2], h1[3]);
;                     *(u32x4*)(hb + off) = w;
;                     s += (h0[0] * h0[0] + h0[1] * h0[1]) + (h0[2] * h0[2] + h0[3] * h0[3]) + (h1[0] * h1[0] + h1[1] * h1[1]) + (h1[2] * h1[2] + h1[3] * h1[3]);
;                 }
;                 s = xor32_sum(xor16_sum(s));
;                 if (fq == 0) xch[(ai * 128 + wr * 64 + m * 16 + fr) * 4 + wc] = s;
.LBB0_578:
	global_load_dwordx4 v[52:55], v[56:57], off nt
	s_waitcnt vmcnt(0)
	v_lshlrev_b32_e32 v48, 16, v52
	v_and_b32_e32 v49, 0xffff0000, v52
	v_lshlrev_b32_e32 v50, 16, v53
	v_and_b32_e32 v51, 0xffff0000, v53
	v_lshlrev_b32_e32 v52, 16, v54
	v_and_b32_e32 v53, 0xffff0000, v54
	v_lshlrev_b32_e32 v54, 16, v55
	v_and_b32_e32 v55, 0xffff0000, v55
.LBB0_579:
	s_waitcnt vmcnt(0)
	v_pk_add_f32 v[50:51], v[46:47], v[50:51]
	v_pk_add_f32 v[60:61], v[44:45], v[48:49]
	v_pk_add_f32 v[48:49], v[42:43], v[54:55]
	v_pk_add_f32 v[52:53], v[40:41], v[52:53]
	v_cvt_pk_bf16_f32 v40, v60, v61
	v_cvt_pk_bf16_f32 v41, v50, v51
	v_cvt_pk_bf16_f32 v42, v52, v53
	v_cvt_pk_bf16_f32 v43, v48, v49
	s_and_b64 vcc, exec, s[12:13]
	global_store_dwordx4 v[56:57], v[40:43], off
	s_cbranch_vccnz .LBB0_616
	global_load_dwordx4 v[44:47], v[58:59], off offset:528 nt
	global_load_dwordx4 v[40:43], v[58:59], off offset:512 nt
	s_cbranch_execnz .LBB0_582
.LBB0_581:
	global_load_dwordx4 v[44:47], v[56:57], off offset:256 nt
	s_waitcnt vmcnt(0)
	v_lshlrev_b32_e32 v40, 16, v44
	v_and_b32_e32 v41, 0xffff0000, v44
	v_lshlrev_b32_e32 v42, 16, v45
	v_and_b32_e32 v43, 0xffff0000, v45
	v_lshlrev_b32_e32 v44, 16, v46
	v_and_b32_e32 v45, 0xffff0000, v46
	v_lshlrev_b32_e32 v46, 16, v47
	v_and_b32_e32 v47, 0xffff0000, v47
.LBB0_582:
	s_waitcnt vmcnt(0)
	v_pk_add_f32 v[38:39], v[38:39], v[42:43]
	v_pk_add_f32 v[36:37], v[36:37], v[40:41]
	v_pk_add_f32 v[40:41], v[34:35], v[46:47]
	v_pk_add_f32 v[42:43], v[32:33], v[44:45]
	v_cvt_pk_bf16_f32 v32, v36, v37
	v_cvt_pk_bf16_f32 v33, v38, v39
	v_cvt_pk_bf16_f32 v34, v42, v43
	v_cvt_pk_bf16_f32 v35, v40, v41
	global_store_dwordx4 v[56:57], v[32:35], off offset:256
	v_mul_f32_e32 v54, v61, v61
	v_mul_f32_e32 v51, v51, v51
	v_mul_f32_e32 v32, v37, v37
	v_mul_f32_e32 v33, v39, v39
	v_fmac_f32_e32 v32, v36, v36
	v_fmac_f32_e32 v33, v38, v38
	v_fmac_f32_e32 v54, v60, v60
	v_fmac_f32_e32 v51, v50, v50
	v_add_f32_e32 v32, v32, v33
	v_mul_f32_e32 v33, v43, v43
	v_add_f32_e32 v50, v54, v51
	v_mul_f32_e32 v51, v53, v53
	v_fmac_f32_e32 v33, v42, v42
	v_fmac_f32_e32 v51, v52, v52
	v_mul_f32_e32 v49, v49, v49
	v_add_f32_e32 v32, v33, v32
	v_mul_f32_e32 v33, v41, v41
	v_add_f32_e32 v50, v51, v50
	v_fmac_f32_e32 v49, v48, v48
	v_fmac_f32_e32 v33, v40, v40
	v_add_f32_e32 v48, v49, v50
	v_add_f32_e32 v32, v33, v32
	v_add_f32_e32 v32, v48, v32
	v_mov_b32_e32 v33, v32
	s_nop 1
	v_permlane16_swap_b32_e32 v32, v33
	v_add_f32_e32 v32, v32, v33
	v_mov_b32_e32 v33, v32
	s_nop 1
	v_permlane32_swap_b32_e32 v32, v33
	s_and_saveexec_b64 s[0:1], s[10:11]
	v_add_f32_e32 v32, v32, v33
	ds_write_b32 v126, v32 offset:2304
	s_or_b64 exec, exec, s[0:1]
	v_add_u32_e32 v32, 0xa0, v152
	v_ashrrev_i32_e32 v33, 31, v32
	v_lshlrev_b64 v[32:33], 10, v[32:33]
	v_lshl_add_u64 v[40:41], v[32:33], 0, v[154:155]
	s_and_b64 vcc, exec, s[12:13]
	v_lshl_add_u64 v[42:43], v[40:41], 2, s[6:7]
	s_cbranch_vccnz .LBB0_617
	global_load_dwordx4 v[36:39], v[42:43], off offset:16 nt
	global_load_dwordx4 v[32:35], v[42:43], off nt
	v_lshl_add_u64 v[40:41], v[40:41], 1, s[16:17]
	s_cbranch_execnz .LBB0_587
.LBB0_586:
	global_load_dwordx4 v[36:39], v[40:41], off nt
	s_waitcnt vmcnt(0)
	v_lshlrev_b32_e32 v32, 16, v36
	v_and_b32_e32 v33, 0xffff0000, v36
	v_lshlrev_b32_e32 v34, 16, v37
	v_and_b32_e32 v35, 0xffff0000, v37
	v_lshlrev_b32_e32 v36, 16, v38
	v_and_b32_e32 v37, 0xffff0000, v38
	v_lshlrev_b32_e32 v38, 16, v39
	v_and_b32_e32 v39, 0xffff0000, v39
.LBB0_587:
	s_waitcnt vmcnt(0)
	v_pk_add_f32 v[34:35], v[30:31], v[34:35]
	v_pk_add_f32 v[44:45], v[28:29], v[32:33]
	v_pk_add_f32 v[32:33], v[26:27], v[38:39]
	v_pk_add_f32 v[36:37], v[24:25], v[36:37]
	v_cvt_pk_bf16_f32 v24, v44, v45
	v_cvt_pk_bf16_f32 v25, v34, v35
	v_cvt_pk_bf16_f32 v26, v36, v37
	v_cvt_pk_bf16_f32 v27, v32, v33
	s_and_b64 vcc, exec, s[12:13]
	global_store_dwordx4 v[40:41], v[24:27], off
	s_cbranch_vccnz .LBB0_618
	global_load_dwordx4 v[28:31], v[42:43], off offset:528 nt
	global_load_dwordx4 v[24:27], v[42:43], off offset:512 nt
	s_cbranch_execnz .LBB0_590
; __device__ __forceinline__ unsigned pk2(float lo, float hi) { f32x2_t v = {lo, hi}; bf16x2_t b = __builtin_convertvector(v, bf16x2_t); return __builtin_bit_cast(unsigned, b); }
; __device__ __forceinline__ float xor16_sum(float v) { const auto r = __builtin_amdgcn_permlane16_swap(__float_as_uint(v), __float_as_uint(v), false, false); return __uint_as_float(r[0]) + __uint_as_float(r[1]); }
; __device__ __forceinline__ float xor32_sum(float v) { const auto r = __builtin_amdgcn_permlane32_swap(__float_as_uint(v), __float_as_uint(v), false, false); return __uint_as_float(r[0]) + __uint_as_float(r[1]); }
; #define BF16_LO(w) __uint_as_float((w) << 16)
; #define BF16_HI(w) __uint_as_float((w) & 0xffff0000u)
;     __device__ __forceinline__ void operator()(const f32x4 (&acc)[2][2][4][2], const Unit& u, int wr, int wc, int fr_in, int fq_in) const {
;     ...
; #pragma unroll
;         for (int ai = 0; ai < 2; ++ai)
; #pragma unroll
;             for (int m = 0; m < 4; ++m) {
;                 const int row = u.pm * BM + ai * 128 + wr * 64 + m * 16 + fr;
;                 float s = 0.f;
; #pragma unroll
;                 for (int bj = 0; bj < 2; ++bj) {
;                     const size_t off = (size_t)row * DM + u.pn * BM + bj * HALF + wc * 32 + 8 * fq;
;                     f32x4 b0, b1;
;                     if (xbase) { b0 = *(const f32x4*)(xbase + off); b1 = *(const f32x4*)(xbase + off + 4); }
;                     else { const u32x4 q = *(const u32x4*)(hb + off);
;                         b0 = (f32x4){BF16_LO(q.x), BF16_HI(q.x), BF16_LO(q.y), BF16_HI(q.y)}; b1 = (f32x4){BF16_LO(q.z), BF16_HI(q.z), BF16_LO(q.w), BF16_HI(q.w)}; }
;                     const f32x4 h0 = b0 + acc[ai][bj][m][0], h1 = b1 + acc[ai][bj][m][1];
;                     u32x4 w; w.x = pk2(h0[0], h0[1]); w.y = pk2(h0[2], h0[3]); w.z = pk2(h1[0], h1[1]); w.w = pk2(h1[2], h1[3]);
;                     *(u32x4*)(hb + off) = w;
;                     s += (h0[0] * h0[0] + h0[1] * h0[1]) + (h0[2] * h0[2] + h0[3] * h0[3]) + (h1[0] * h1[0] + h1[1] * h1[1]) + (h1[2] * h1[2] + h1[3] * h1[3]);
;                 }
;                 s = xor32_sum(xor16_sum(s));
;                 if (fq == 0) xch[(ai * 128 + wr * 64 + m * 16 + fr) * 4 + wc] = s;
.LBB0_589:
	global_load_dwordx4 v[28:31], v[40:41], off offset:256 nt
	s_waitcnt vmcnt(0)
	v_lshlrev_b32_e32 v24, 16, v28
	v_and_b32_e32 v25, 0xffff0000, v28
	v_lshlrev_b32_e32 v26, 16, v29
	v_and_b32_e32 v27, 0xffff0000, v29
	v_lshlrev_b32_e32 v28, 16, v30
	v_and_b32_e32 v29, 0xffff0000, v30
	v_lshlrev_b32_e32 v30, 16, v31
	v_and_b32_e32 v31, 0xffff0000, v31
.LBB0_590:
	s_waitcnt vmcnt(0)
	v_pk_add_f32 v[22:23], v[22:23], v[26:27]
	v_pk_add_f32 v[20:21], v[20:21], v[24:25]
	v_pk_add_f32 v[24:25], v[18:19], v[30:31]
	v_pk_add_f32 v[26:27], v[16:17], v[28:29]
	v_cvt_pk_bf16_f32 v16, v20, v21
	v_cvt_pk_bf16_f32 v17, v22, v23
	v_cvt_pk_bf16_f32 v18, v26, v27
	v_cvt_pk_bf16_f32 v19, v24, v25
	global_store_dwordx4 v[40:41], v[16:19], off offset:256
	v_mul_f32_e32 v38, v45, v45
	v_mul_f32_e32 v35, v35, v35
	v_mul_f32_e32 v16, v21, v21
	v_mul_f32_e32 v17, v23, v23
	v_fmac_f32_e32 v16, v20, v20
	v_fmac_f32_e32 v17, v22, v22
	v_fmac_f32_e32 v38, v44, v44
	v_fmac_f32_e32 v35, v34, v34
	v_add_f32_e32 v16, v16, v17
	v_mul_f32_e32 v17, v27, v27
	v_add_f32_e32 v34, v38, v35
	v_mul_f32_e32 v35, v37, v37
	v_fmac_f32_e32 v17, v26, v26
	v_fmac_f32_e32 v35, v36, v36
	v_mul_f32_e32 v33, v33, v33
	v_add_f32_e32 v16, v17, v16
	v_mul_f32_e32 v17, v25, v25
	v_add_f32_e32 v34, v35, v34
	v_fmac_f32_e32 v33, v32, v32
	v_fmac_f32_e32 v17, v24, v24
	v_add_f32_e32 v32, v33, v34
	v_add_f32_e32 v16, v17, v16
	v_add_f32_e32 v16, v32, v16
	v_mov_b32_e32 v17, v16
	s_nop 1
	v_permlane16_swap_b32_e32 v16, v17
	v_add_f32_e32 v16, v16, v17
	v_mov_b32_e32 v17, v16
	s_nop 1
	v_permlane32_swap_b32_e32 v16, v17
	s_and_saveexec_b64 s[0:1], s[10:11]
	v_add_f32_e32 v16, v16, v17
	ds_write_b32 v126, v16 offset:2560
	s_or_b64 exec, exec, s[0:1]
	v_add_u32_e32 v16, 0xb0, v152
	v_ashrrev_i32_e32 v17, 31, v16
	v_lshlrev_b64 v[16:17], 10, v[16:17]
	v_lshl_add_u64 v[24:25], v[16:17], 0, v[154:155]
	s_and_b64 vcc, exec, s[12:13]
	v_lshl_add_u64 v[26:27], v[24:25], 2, s[6:7]
	s_cbranch_vccnz .LBB0_619
	global_load_dwordx4 v[20:23], v[26:27], off offset:16 nt
	global_load_dwordx4 v[16:19], v[26:27], off nt
	v_lshl_add_u64 v[24:25], v[24:25], 1, s[16:17]
	s_cbranch_execnz .LBB0_595
.LBB0_594:
	global_load_dwordx4 v[20:23], v[24:25], off nt
	s_waitcnt vmcnt(0)
	v_lshlrev_b32_e32 v16, 16, v20
	v_and_b32_e32 v17, 0xffff0000, v20
	v_lshlrev_b32_e32 v18, 16, v21
	v_and_b32_e32 v19, 0xffff0000, v21
	v_lshlrev_b32_e32 v20, 16, v22
	v_and_b32_e32 v21, 0xffff0000, v22
	v_lshlrev_b32_e32 v22, 16, v23
	v_and_b32_e32 v23, 0xffff0000, v23
.LBB0_595:
	s_waitcnt vmcnt(0)
	v_pk_add_f32 v[18:19], v[14:15], v[18:19]
	v_pk_add_f32 v[28:29], v[12:13], v[16:17]
	v_pk_add_f32 v[16:17], v[10:11], v[22:23]
	v_pk_add_f32 v[20:21], v[8:9], v[20:21]
	v_cvt_pk_bf16_f32 v8, v28, v29
	v_cvt_pk_bf16_f32 v9, v18, v19
	v_cvt_pk_bf16_f32 v10, v20, v21
	v_cvt_pk_bf16_f32 v11, v16, v17
	s_and_b64 vcc, exec, s[12:13]
	global_store_dwordx4 v[24:25], v[8:11], off
	s_cbranch_vccnz .LBB0_620
	global_load_dwordx4 v[12:15], v[26:27], off offset:528 nt
	global_load_dwordx4 v[8:11], v[26:27], off offset:512 nt
	s_cbranch_execnz .LBB0_598
.LBB0_597:
	global_load_dwordx4 v[12:15], v[24:25], off offset:256 nt
	s_waitcnt vmcnt(0)
	v_lshlrev_b32_e32 v8, 16, v12
	v_and_b32_e32 v9, 0xffff0000, v12
	v_lshlrev_b32_e32 v10, 16, v13
	v_and_b32_e32 v11, 0xffff0000, v13
	v_lshlrev_b32_e32 v12, 16, v14
	v_and_b32_e32 v13, 0xffff0000, v14
	v_lshlrev_b32_e32 v14, 16, v15
	v_and_b32_e32 v15, 0xffff0000, v15

; __device__ __forceinline__ unsigned pk2(float lo, float hi) { f32x2_t v = {lo, hi}; bf16x2_t b = __builtin_convertvector(v, bf16x2_t); return __builtin_bit_cast(unsigned, b); }
; __device__ __forceinline__ float xor16_sum(float v) { const auto r = __builtin_amdgcn_permlane16_swap(__float_as_uint(v), __float_as_uint(v), false, false); return __uint_as_float(r[0]) + __uint_as_float(r[1]); }
; __device__ __forceinline__ float xor32_sum(float v) { const auto r = __builtin_amdgcn_permlane32_swap(__float_as_uint(v), __float_as_uint(v), false, false); return __uint_as_float(r[0]) + __uint_as_float(r[1]); }
; #define BF16_LO(w) __uint_as_float((w) << 16)
; #define BF16_HI(w) __uint_as_float((w) & 0xffff0000u)
;     __device__ __forceinline__ void operator()(const f32x4 (&acc)[2][2][4][2], const Unit& u, int wr, int wc, int fr_in, int fq_in) const {
;     ...
; #pragma unroll
;         for (int ai = 0; ai < 2; ++ai)
; #pragma unroll
;             for (int m = 0; m < 4; ++m) {
;                 const int row = u.pm * BM + ai * 128 + wr * 64 + m * 16 + fr;
;                 float s = 0.f;
; #pragma unroll
;                 for (int bj = 0; bj < 2; ++bj) {
;                     const size_t off = (size_t)row * DM + u.pn * BM + bj * HALF + wc * 32 + 8 * fq;
;                     f32x4 b0, b1;
;                     if (xbase) { b0 = *(const f32x4*)(xbase + off); b1 = *(const f32x4*)(xbase + off + 4); }
;                     else { const u32x4 q = *(const u32x4*)(hb + off);
;                         b0 = (f32x4){BF16_LO(q.x), BF16_HI(q.x), BF16_LO(q.y), BF16_HI(q.y)}; b1 = (f32x4){BF16_LO(q.z), BF16_HI(q.z), BF16_LO(q.w), BF16_HI(q.w)}; }
;                     const f32x4 h0 = b0 + acc[ai][bj][m][0], h1 = b1 + acc[ai][bj][m][1];
;                     u32x4 w; w.x = pk2(h0[0], h0[1]); w.y = pk2(h0[2], h0[3]); w.z = pk2(h1[0], h1[1]); w.w = pk2(h1[2], h1[3]);
;                     *(u32x4*)(hb + off) = w;
;                     s += (h0[0] * h0[0] + h0[1] * h0[1]) + (h0[2] * h0[2] + h0[3] * h0[3]) + (h1[0] * h1[0] + h1[1] * h1[1]) + (h1[2] * h1[2] + h1[3] * h1[3]);
;                 }
;                 s = xor32_sum(xor16_sum(s));
;                 if (fq == 0) xch[(ai * 128 + wr * 64 + m * 16 + fr) * 4 + wc] = s;
.LBB0_874:
	v_mov_b32_e32 v168, v149
	v_mov_b32_e32 v169, v148
	s_lshl_b32 s4, s54, 8
	v_add_u32_e32 v188, s39, v168
	v_add_u32_e32 v144, s4, v188
	s_lshl_b32 s0, s53, 8
	s_ashr_i32 s1, s0, 31
	v_lshlrev_b32_e32 v146, 3, v169
	v_ashrrev_i32_e32 v145, 31, v144
	v_ashrrev_i32_e32 v147, 31, v146
	s_or_b64 s[0:1], s[0:1], s[14:15]
	v_lshlrev_b64 v[170:171], 11, v[144:145]
	v_lshl_add_u64 v[146:147], s[0:1], 0, v[146:147]
	v_lshl_add_u64 v[170:171], s[8:9], 0, v[170:171]
	v_lshl_add_u64 v[178:179], v[146:147], 1, v[170:171]
	global_load_dwordx4 v[170:173], v[178:179], off nt
	global_load_dwordx4 v[174:177], v[178:179], off offset:256 nt
	v_cmp_eq_u32_e32 vcc, 0, v169
	s_waitcnt vmcnt(0)
	v_lshlrev_b32_e32 v180, 16, v170
	v_and_b32_e32 v181, 0xffff0000, v170
	v_lshlrev_b32_e32 v170, 16, v171
	v_and_b32_e32 v171, 0xffff0000, v171
	v_lshlrev_b32_e32 v182, 16, v172
	v_and_b32_e32 v183, 0xffff0000, v172
	v_lshlrev_b32_e32 v172, 16, v173
	v_and_b32_e32 v173, 0xffff0000, v173
	v_lshlrev_b32_e32 v184, 16, v174
	v_and_b32_e32 v185, 0xffff0000, v174
	v_lshlrev_b32_e32 v174, 16, v175
	v_and_b32_e32 v175, 0xffff0000, v175
	v_lshlrev_b32_e32 v186, 16, v176
	v_and_b32_e32 v187, 0xffff0000, v176
	v_lshlrev_b32_e32 v176, 16, v177
	v_and_b32_e32 v177, 0xffff0000, v177
	v_pk_add_f32 v[126:127], v[126:127], v[170:171]
	v_pk_add_f32 v[124:125], v[124:125], v[180:181]
	v_pk_add_f32 v[122:123], v[122:123], v[172:173]
	v_pk_add_f32 v[170:171], v[118:119], v[174:175]
	v_pk_add_f32 v[172:173], v[116:117], v[184:185]
	v_pk_add_f32 v[120:121], v[120:121], v[182:183]
	v_pk_add_f32 v[174:175], v[114:115], v[176:177]
	v_pk_add_f32 v[176:177], v[112:113], v[186:187]
	v_cvt_pk_bf16_f32 v112, v124, v125
	v_cvt_pk_bf16_f32 v113, v126, v127
	v_mul_f32_e32 v125, v125, v125
	v_mul_f32_e32 v127, v127, v127
	v_mul_f32_e32 v145, v173, v173
	v_mul_f32_e32 v169, v171, v171
	v_cvt_pk_bf16_f32 v114, v120, v121
	v_cvt_pk_bf16_f32 v115, v122, v123
	v_mul_f32_e32 v121, v121, v121
	v_cvt_pk_bf16_f32 v117, v170, v171
	v_mul_f32_e32 v171, v177, v177
	v_fmac_f32_e32 v125, v124, v124
	v_fmac_f32_e32 v127, v126, v126
	v_fmac_f32_e32 v145, v172, v172
	v_fmac_f32_e32 v169, v170, v170
	v_mul_f32_e32 v123, v123, v123
	v_cvt_pk_bf16_f32 v116, v172, v173
	v_mul_f32_e32 v173, v175, v175
	global_store_dwordx4 v[178:179], v[112:115], off
	v_fmac_f32_e32 v121, v120, v120
	v_fmac_f32_e32 v171, v176, v176
	v_add_f32_e32 v112, v125, v127
	v_add_f32_e32 v113, v145, v169
	v_fmac_f32_e32 v123, v122, v122
	v_fmac_f32_e32 v173, v174, v174
	v_add_f32_e32 v112, v121, v112
	v_add_f32_e32 v113, v171, v113
	v_add_f32_e32 v112, v123, v112
	v_add_f32_e32 v113, v173, v113
	v_add_f32_e32 v112, v112, v113
	v_mov_b32_e32 v113, v112
	s_nop 1
	v_permlane16_swap_b32_e32 v112, v113
	v_add_f32_e32 v113, v112, v113
	v_mov_b32_e32 v114, v113
	v_cvt_pk_bf16_f32 v118, v176, v177
	v_cvt_pk_bf16_f32 v119, v174, v175
	v_permlane32_swap_b32_e32 v113, v114
	v_lshl_add_u32 v112, v188, 4, s47
	global_store_dwordx4 v[178:179], v[116:119], off offset:256
	s_and_saveexec_b64 s[0:1], vcc
	v_add_f32_e32 v113, v113, v114
	ds_write_b32 v112, v113
	s_or_b64 exec, exec, s[0:1]
	v_add_u32_e32 v114, 16, v144
	v_ashrrev_i32_e32 v115, 31, v114
	v_lshlrev_b64 v[114:115], 11, v[114:115]
	v_lshl_add_u64 v[114:115], s[8:9], 0, v[114:115]
	v_lshl_add_u64 v[122:123], v[146:147], 1, v[114:115]
	global_load_dwordx4 v[114:117], v[122:123], off nt
	global_load_dwordx4 v[118:121], v[122:123], off offset:256 nt
	s_waitcnt vmcnt(1)
	v_lshlrev_b32_e32 v124, 16, v114
	v_and_b32_e32 v125, 0xffff0000, v114
	v_lshlrev_b32_e32 v114, 16, v115
	v_and_b32_e32 v115, 0xffff0000, v115
	v_lshlrev_b32_e32 v126, 16, v116
	v_and_b32_e32 v127, 0xffff0000, v116
	v_lshlrev_b32_e32 v116, 16, v117
	v_and_b32_e32 v117, 0xffff0000, v117
	s_waitcnt vmcnt(0)
	v_lshlrev_b32_e32 v170, 16, v118
	v_and_b32_e32 v171, 0xffff0000, v118
	v_lshlrev_b32_e32 v118, 16, v119
	v_and_b32_e32 v119, 0xffff0000, v119
	v_lshlrev_b32_e32 v172, 16, v120
	v_and_b32_e32 v173, 0xffff0000, v120
	v_lshlrev_b32_e32 v120, 16, v121
	v_and_b32_e32 v121, 0xffff0000, v121
	v_pk_add_f32 v[110:111], v[110:111], v[114:115]
	v_pk_add_f32 v[108:109], v[108:109], v[124:125]
	v_pk_add_f32 v[106:107], v[106:107], v[116:117]
	v_pk_add_f32 v[114:115], v[102:103], v[118:119]
	v_pk_add_f32 v[116:117], v[100:101], v[170:171]
	v_pk_add_f32 v[104:105], v[104:105], v[126:127]
	v_pk_add_f32 v[118:119], v[98:99], v[120:121]
	v_pk_add_f32 v[120:121], v[96:97], v[172:173]
	v_cvt_pk_bf16_f32 v96, v108, v109
	v_cvt_pk_bf16_f32 v97, v110, v111
	v_mul_f32_e32 v109, v109, v109
	v_mul_f32_e32 v111, v111, v111
	v_cvt_pk_bf16_f32 v101, v114, v115
	v_mul_f32_e32 v113, v117, v117
	v_mul_f32_e32 v115, v115, v115
	v_cvt_pk_bf16_f32 v98, v104, v105
	v_cvt_pk_bf16_f32 v99, v106, v107
	v_mul_f32_e32 v105, v105, v105
	v_cvt_pk_bf16_f32 v100, v116, v117
	v_mul_f32_e32 v117, v121, v121
	v_fmac_f32_e32 v109, v108, v108
	v_fmac_f32_e32 v111, v110, v110
	v_fmac_f32_e32 v113, v116, v116
	v_fmac_f32_e32 v115, v114, v114
	v_mul_f32_e32 v107, v107, v107
	v_cvt_pk_bf16_f32 v103, v118, v119
	v_mul_f32_e32 v119, v119, v119
	global_store_dwordx4 v[122:123], v[96:99], off
	v_fmac_f32_e32 v105, v104, v104
	v_fmac_f32_e32 v117, v120, v120
	v_add_f32_e32 v96, v109, v111
	v_add_f32_e32 v97, v113, v115
	v_fmac_f32_e32 v107, v106, v106
	v_fmac_f32_e32 v119, v118, v118
	v_add_f32_e32 v96, v105, v96
	v_add_f32_e32 v97, v117, v97
	v_add_f32_e32 v96, v107, v96
	v_add_f32_e32 v97, v119, v97
	v_add_f32_e32 v96, v96, v97
	v_mov_b32_e32 v97, v96
	s_nop 1
	v_permlane16_swap_b32_e32 v96, v97
	v_add_f32_e32 v96, v96, v97
	v_mov_b32_e32 v97, v96
	v_cvt_pk_bf16_f32 v102, v120, v121
	s_nop 0
	v_permlane32_swap_b32_e32 v96, v97
	global_store_dwordx4 v[122:123], v[100:103], off offset:256
	s_and_saveexec_b64 s[0:1], vcc
	v_add_f32_e32 v96, v96, v97
	ds_write_b32 v112, v96 offset:256
	s_or_b64 exec, exec, s[0:1]
	v_add_u32_e32 v96, 32, v144
	v_ashrrev_i32_e32 v97, 31, v96
	v_lshlrev_b64 v[96:97], 11, v[96:97]
	v_lshl_add_u64 v[96:97], s[8:9], 0, v[96:97]
	v_lshl_add_u64 v[104:105], v[146:147], 1, v[96:97]
	global_load_dwordx4 v[96:99], v[104:105], off nt
	global_load_dwordx4 v[100:103], v[104:105], off offset:256 nt
	s_waitcnt vmcnt(1)
; __device__ __forceinline__ unsigned pk2(float lo, float hi) { f32x2_t v = {lo, hi}; bf16x2_t b = __builtin_convertvector(v, bf16x2_t); return __builtin_bit_cast(unsigned, b); }
; __device__ __forceinline__ float xor16_sum(float v) { const auto r = __builtin_amdgcn_permlane16_swap(__float_as_uint(v), __float_as_uint(v), false, false); return __uint_as_float(r[0]) + __uint_as_float(r[1]); }
; __device__ __forceinline__ float xor32_sum(float v) { const auto r = __builtin_amdgcn_permlane32_swap(__float_as_uint(v), __float_as_uint(v), false, false); return __uint_as_float(r[0]) + __uint_as_float(r[1]); }
; #define BF16_LO(w) __uint_as_float((w) << 16)
; #define BF16_HI(w) __uint_as_float((w) & 0xffff0000u)
;     __device__ __forceinline__ void operator()(const f32x4 (&acc)[2][2][4][2], const Unit& u, int wr, int wc, int fr_in, int fq_in) const {
;     ...
; #pragma unroll
;         for (int ai = 0; ai < 2; ++ai)
; #pragma unroll
;             for (int m = 0; m < 4; ++m) {
;                 const int row = u.pm * BM + ai * 128 + wr * 64 + m * 16 + fr;
;                 float s = 0.f;
; #pragma unroll
;                 for (int bj = 0; bj < 2; ++bj) {
;                     const size_t off = (size_t)row * DM + u.pn * BM + bj * HALF + wc * 32 + 8 * fq;
;                     f32x4 b0, b1;
;                     if (xbase) { b0 = *(const f32x4*)(xbase + off); b1 = *(const f32x4*)(xbase + off + 4); }
;                     else { const u32x4 q = *(const u32x4*)(hb + off);
;                         b0 = (f32x4){BF16_LO(q.x), BF16_HI(q.x), BF16_LO(q.y), BF16_HI(q.y)}; b1 = (f32x4){BF16_LO(q.z), BF16_HI(q.z), BF16_LO(q.w), BF16_HI(q.w)}; }
;                     const f32x4 h0 = b0 + acc[ai][bj][m][0], h1 = b1 + acc[ai][bj][m][1];
;                     u32x4 w; w.x = pk2(h0[0], h0[1]); w.y = pk2(h0[2], h0[3]); w.z = pk2(h1[0], h1[1]); w.w = pk2(h1[2], h1[3]);
;                     *(u32x4*)(hb + off) = w;
;                     s += (h0[0] * h0[0] + h0[1] * h0[1]) + (h0[2] * h0[2] + h0[3] * h0[3]) + (h1[0] * h1[0] + h1[1] * h1[1]) + (h1[2] * h1[2] + h1[3] * h1[3]);
;                 }
;                 s = xor32_sum(xor16_sum(s));
;                 if (fq == 0) xch[(ai * 128 + wr * 64 + m * 16 + fr) * 4 + wc] = s;
	v_lshlrev_b32_e32 v106, 16, v96
	v_and_b32_e32 v107, 0xffff0000, v96
	v_lshlrev_b32_e32 v96, 16, v97
	v_and_b32_e32 v97, 0xffff0000, v97
	v_lshlrev_b32_e32 v108, 16, v98
	v_and_b32_e32 v109, 0xffff0000, v98
	v_lshlrev_b32_e32 v98, 16, v99
	v_and_b32_e32 v99, 0xffff0000, v99
	s_waitcnt vmcnt(0)
	v_lshlrev_b32_e32 v110, 16, v100
	v_and_b32_e32 v111, 0xffff0000, v100
	v_lshlrev_b32_e32 v100, 16, v101
	v_and_b32_e32 v101, 0xffff0000, v101
	v_lshlrev_b32_e32 v114, 16, v102
	v_and_b32_e32 v115, 0xffff0000, v102
	v_lshlrev_b32_e32 v102, 16, v103
	v_and_b32_e32 v103, 0xffff0000, v103
	v_pk_add_f32 v[94:95], v[94:95], v[96:97]
	v_pk_add_f32 v[92:93], v[92:93], v[106:107]
	v_pk_add_f32 v[90:91], v[90:91], v[98:99]
	v_pk_add_f32 v[96:97], v[86:87], v[100:101]
	v_pk_add_f32 v[98:99], v[84:85], v[110:111]
	v_pk_add_f32 v[88:89], v[88:89], v[108:109]
	v_pk_add_f32 v[100:101], v[82:83], v[102:103]
	v_pk_add_f32 v[102:103], v[80:81], v[114:115]
	v_cvt_pk_bf16_f32 v80, v92, v93
	v_cvt_pk_bf16_f32 v81, v94, v95
	v_mul_f32_e32 v93, v93, v93
	v_mul_f32_e32 v95, v95, v95
	v_cvt_pk_bf16_f32 v84, v98, v99
	v_cvt_pk_bf16_f32 v85, v96, v97
	v_mul_f32_e32 v99, v99, v99
	v_mul_f32_e32 v97, v97, v97
	v_cvt_pk_bf16_f32 v82, v88, v89
	v_cvt_pk_bf16_f32 v83, v90, v91
	v_mul_f32_e32 v89, v89, v89
	v_cvt_pk_bf16_f32 v86, v102, v103
	v_mul_f32_e32 v103, v103, v103
	v_fmac_f32_e32 v93, v92, v92
	v_fmac_f32_e32 v95, v94, v94
	v_fmac_f32_e32 v99, v98, v98
	v_fmac_f32_e32 v97, v96, v96
	v_mul_f32_e32 v91, v91, v91
	v_cvt_pk_bf16_f32 v87, v100, v101
	v_mul_f32_e32 v101, v101, v101
	global_store_dwordx4 v[104:105], v[80:83], off
	v_fmac_f32_e32 v89, v88, v88
	v_fmac_f32_e32 v103, v102, v102
	v_add_f32_e32 v80, v93, v95
	v_add_f32_e32 v81, v99, v97
	v_fmac_f32_e32 v91, v90, v90
	v_fmac_f32_e32 v101, v100, v100
	v_add_f32_e32 v80, v89, v80
	v_add_f32_e32 v81, v103, v81
	v_add_f32_e32 v80, v91, v80
	v_add_f32_e32 v81, v101, v81
	v_add_f32_e32 v80, v80, v81
	v_mov_b32_e32 v81, v80
	s_nop 1
	v_permlane16_swap_b32_e32 v80, v81
	v_add_f32_e32 v80, v80, v81
	v_mov_b32_e32 v81, v80
	s_nop 1
	v_permlane32_swap_b32_e32 v80, v81
	global_store_dwordx4 v[104:105], v[84:87], off offset:256
	s_and_saveexec_b64 s[0:1], vcc
	v_add_f32_e32 v80, v80, v81
	ds_write_b32 v112, v80 offset:512
	s_or_b64 exec, exec, s[0:1]
	v_add_u32_e32 v80, 48, v144
	v_ashrrev_i32_e32 v81, 31, v80
	v_lshlrev_b64 v[80:81], 11, v[80:81]
	v_lshl_add_u64 v[80:81], s[8:9], 0, v[80:81]
	v_lshl_add_u64 v[88:89], v[146:147], 1, v[80:81]
	global_load_dwordx4 v[80:83], v[88:89], off nt
	global_load_dwordx4 v[84:87], v[88:89], off offset:256 nt
	s_waitcnt vmcnt(1)
	v_lshlrev_b32_e32 v90, 16, v80
	v_and_b32_e32 v91, 0xffff0000, v80
	v_lshlrev_b32_e32 v80, 16, v81
	v_and_b32_e32 v81, 0xffff0000, v81
	v_lshlrev_b32_e32 v92, 16, v82
	v_and_b32_e32 v93, 0xffff0000, v82
	v_lshlrev_b32_e32 v82, 16, v83
	v_and_b32_e32 v83, 0xffff0000, v83
	s_waitcnt vmcnt(0)
	v_lshlrev_b32_e32 v94, 16, v84
	v_and_b32_e32 v95, 0xffff0000, v84
	v_lshlrev_b32_e32 v84, 16, v85
	v_and_b32_e32 v85, 0xffff0000, v85
	v_lshlrev_b32_e32 v96, 16, v86
	v_and_b32_e32 v97, 0xffff0000, v86
	v_lshlrev_b32_e32 v86, 16, v87
	v_and_b32_e32 v87, 0xffff0000, v87
	v_pk_add_f32 v[78:79], v[78:79], v[80:81]
	v_pk_add_f32 v[76:77], v[76:77], v[90:91]
	v_pk_add_f32 v[74:75], v[74:75], v[82:83]
	v_pk_add_f32 v[80:81], v[70:71], v[84:85]
	v_pk_add_f32 v[82:83], v[68:69], v[94:95]
	v_pk_add_f32 v[72:73], v[72:73], v[92:93]
	v_pk_add_f32 v[84:85], v[66:67], v[86:87]
	v_pk_add_f32 v[86:87], v[64:65], v[96:97]
	v_cvt_pk_bf16_f32 v64, v76, v77
	v_cvt_pk_bf16_f32 v65, v78, v79
	v_mul_f32_e32 v77, v77, v77
	v_mul_f32_e32 v79, v79, v79
	v_cvt_pk_bf16_f32 v68, v82, v83
	v_cvt_pk_bf16_f32 v69, v80, v81
	v_mul_f32_e32 v83, v83, v83
	v_mul_f32_e32 v81, v81, v81
	v_cvt_pk_bf16_f32 v66, v72, v73
	v_cvt_pk_bf16_f32 v67, v74, v75
	v_mul_f32_e32 v73, v73, v73
	v_cvt_pk_bf16_f32 v70, v86, v87
	v_mul_f32_e32 v87, v87, v87
	v_fmac_f32_e32 v77, v76, v76
	v_fmac_f32_e32 v79, v78, v78
	v_fmac_f32_e32 v83, v82, v82
	v_fmac_f32_e32 v81, v80, v80
	v_mul_f32_e32 v75, v75, v75
	v_cvt_pk_bf16_f32 v71, v84, v85
	v_mul_f32_e32 v85, v85, v85
	global_store_dwordx4 v[88:89], v[64:67], off
	v_fmac_f32_e32 v73, v72, v72
	v_fmac_f32_e32 v87, v86, v86
	v_add_f32_e32 v64, v77, v79
	v_add_f32_e32 v65, v83, v81
	v_fmac_f32_e32 v75, v74, v74
	v_fmac_f32_e32 v85, v84, v84
	v_add_f32_e32 v64, v73, v64
	v_add_f32_e32 v65, v87, v65
	v_add_f32_e32 v64, v75, v64
	v_add_f32_e32 v65, v85, v65
	v_add_f32_e32 v64, v64, v65
	v_mov_b32_e32 v65, v64
	s_nop 1
	v_permlane16_swap_b32_e32 v64, v65
	v_add_f32_e32 v64, v64, v65
	v_mov_b32_e32 v65, v64
	s_nop 1
	v_permlane32_swap_b32_e32 v64, v65
	global_store_dwordx4 v[88:89], v[68:71], off offset:256
	s_and_saveexec_b64 s[0:1], vcc
	v_add_f32_e32 v64, v64, v65
	ds_write_b32 v112, v64 offset:768
	s_or_b64 exec, exec, s[0:1]
	v_add_u32_e32 v64, 0x80, v144
	v_ashrrev_i32_e32 v65, 31, v64
	v_lshlrev_b64 v[64:65], 11, v[64:65]
	v_lshl_add_u64 v[64:65], s[8:9], 0, v[64:65]
	v_lshl_add_u64 v[72:73], v[146:147], 1, v[64:65]
	global_load_dwordx4 v[64:67], v[72:73], off nt
	global_load_dwordx4 v[68:71], v[72:73], off offset:256 nt
	s_waitcnt vmcnt(1)
	v_lshlrev_b32_e32 v74, 16, v64
	v_and_b32_e32 v75, 0xffff0000, v64
	v_lshlrev_b32_e32 v64, 16, v65
	v_and_b32_e32 v65, 0xffff0000, v65
	v_lshlrev_b32_e32 v76, 16, v66
	v_and_b32_e32 v77, 0xffff0000, v66
	v_lshlrev_b32_e32 v66, 16, v67
	v_and_b32_e32 v67, 0xffff0000, v67
	s_waitcnt vmcnt(0)
; __device__ __forceinline__ unsigned pk2(float lo, float hi) { f32x2_t v = {lo, hi}; bf16x2_t b = __builtin_convertvector(v, bf16x2_t); return __builtin_bit_cast(unsigned, b); }
; __device__ __forceinline__ float xor16_sum(float v) { const auto r = __builtin_amdgcn_permlane16_swap(__float_as_uint(v), __float_as_uint(v), false, false); return __uint_as_float(r[0]) + __uint_as_float(r[1]); }
; __device__ __forceinline__ float xor32_sum(float v) { const auto r = __builtin_amdgcn_permlane32_swap(__float_as_uint(v), __float_as_uint(v), false, false); return __uint_as_float(r[0]) + __uint_as_float(r[1]); }
; #define BF16_LO(w) __uint_as_float((w) << 16)
; #define BF16_HI(w) __uint_as_float((w) & 0xffff0000u)
;     __device__ __forceinline__ void operator()(const f32x4 (&acc)[2][2][4][2], const Unit& u, int wr, int wc, int fr_in, int fq_in) const {
;     ...
; #pragma unroll
;         for (int ai = 0; ai < 2; ++ai)
; #pragma unroll
;             for (int m = 0; m < 4; ++m) {
;                 const int row = u.pm * BM + ai * 128 + wr * 64 + m * 16 + fr;
;                 float s = 0.f;
; #pragma unroll
;                 for (int bj = 0; bj < 2; ++bj) {
;                     const size_t off = (size_t)row * DM + u.pn * BM + bj * HALF + wc * 32 + 8 * fq;
;                     f32x4 b0, b1;
;                     if (xbase) { b0 = *(const f32x4*)(xbase + off); b1 = *(const f32x4*)(xbase + off + 4); }
;                     else { const u32x4 q = *(const u32x4*)(hb + off);
;                         b0 = (f32x4){BF16_LO(q.x), BF16_HI(q.x), BF16_LO(q.y), BF16_HI(q.y)}; b1 = (f32x4){BF16_LO(q.z), BF16_HI(q.z), BF16_LO(q.w), BF16_HI(q.w)}; }
;                     const f32x4 h0 = b0 + acc[ai][bj][m][0], h1 = b1 + acc[ai][bj][m][1];
;                     u32x4 w; w.x = pk2(h0[0], h0[1]); w.y = pk2(h0[2], h0[3]); w.z = pk2(h1[0], h1[1]); w.w = pk2(h1[2], h1[3]);
;                     *(u32x4*)(hb + off) = w;
;                     s += (h0[0] * h0[0] + h0[1] * h0[1]) + (h0[2] * h0[2] + h0[3] * h0[3]) + (h1[0] * h1[0] + h1[1] * h1[1]) + (h1[2] * h1[2] + h1[3] * h1[3]);
;                 }
;                 s = xor32_sum(xor16_sum(s));
;                 if (fq == 0) xch[(ai * 128 + wr * 64 + m * 16 + fr) * 4 + wc] = s;
	v_lshlrev_b32_e32 v78, 16, v68
	v_and_b32_e32 v79, 0xffff0000, v68
	v_lshlrev_b32_e32 v68, 16, v69
	v_and_b32_e32 v69, 0xffff0000, v69
	v_lshlrev_b32_e32 v80, 16, v70
	v_and_b32_e32 v81, 0xffff0000, v70
	v_lshlrev_b32_e32 v70, 16, v71
	v_and_b32_e32 v71, 0xffff0000, v71
	v_pk_add_f32 v[62:63], v[62:63], v[64:65]
	v_pk_add_f32 v[60:61], v[60:61], v[74:75]
	v_pk_add_f32 v[58:59], v[58:59], v[66:67]
	v_pk_add_f32 v[64:65], v[54:55], v[68:69]
	v_pk_add_f32 v[66:67], v[52:53], v[78:79]
	v_pk_add_f32 v[56:57], v[56:57], v[76:77]
	v_pk_add_f32 v[68:69], v[50:51], v[70:71]
	v_pk_add_f32 v[70:71], v[48:49], v[80:81]
	v_cvt_pk_bf16_f32 v48, v60, v61
	v_cvt_pk_bf16_f32 v49, v62, v63
	v_mul_f32_e32 v61, v61, v61
	v_mul_f32_e32 v63, v63, v63
	v_cvt_pk_bf16_f32 v52, v66, v67
	v_cvt_pk_bf16_f32 v53, v64, v65
	v_mul_f32_e32 v67, v67, v67
	v_mul_f32_e32 v65, v65, v65
	v_cvt_pk_bf16_f32 v50, v56, v57
	v_cvt_pk_bf16_f32 v51, v58, v59
	v_mul_f32_e32 v57, v57, v57
	v_cvt_pk_bf16_f32 v54, v70, v71
	v_mul_f32_e32 v71, v71, v71
	v_fmac_f32_e32 v61, v60, v60
	v_fmac_f32_e32 v63, v62, v62
	v_fmac_f32_e32 v67, v66, v66
	v_fmac_f32_e32 v65, v64, v64
	v_mul_f32_e32 v59, v59, v59
	v_cvt_pk_bf16_f32 v55, v68, v69
	v_mul_f32_e32 v69, v69, v69
	global_store_dwordx4 v[72:73], v[48:51], off
	v_fmac_f32_e32 v57, v56, v56
	v_fmac_f32_e32 v71, v70, v70
	v_add_f32_e32 v48, v61, v63
	v_add_f32_e32 v49, v67, v65
	v_fmac_f32_e32 v59, v58, v58
	v_fmac_f32_e32 v69, v68, v68
	v_add_f32_e32 v48, v57, v48
	v_add_f32_e32 v49, v71, v49
	v_add_f32_e32 v48, v59, v48
	v_add_f32_e32 v49, v69, v49
	v_add_f32_e32 v48, v48, v49
	v_mov_b32_e32 v49, v48
	s_nop 1
	v_permlane16_swap_b32_e32 v48, v49
	v_add_f32_e32 v48, v48, v49
	v_mov_b32_e32 v49, v48
	s_nop 1
	v_permlane32_swap_b32_e32 v48, v49
	global_store_dwordx4 v[72:73], v[52:55], off offset:256
	s_and_saveexec_b64 s[0:1], vcc
	v_add_f32_e32 v48, v48, v49
	ds_write_b32 v112, v48 offset:2048
	s_or_b64 exec, exec, s[0:1]
	v_add_u32_e32 v48, 0x90, v144
	v_ashrrev_i32_e32 v49, 31, v48
	v_lshlrev_b64 v[48:49], 11, v[48:49]
	v_lshl_add_u64 v[48:49], s[8:9], 0, v[48:49]
	v_lshl_add_u64 v[56:57], v[146:147], 1, v[48:49]
	global_load_dwordx4 v[48:51], v[56:57], off nt
	global_load_dwordx4 v[52:55], v[56:57], off offset:256 nt
	s_waitcnt vmcnt(1)
	v_lshlrev_b32_e32 v58, 16, v48
	v_and_b32_e32 v59, 0xffff0000, v48
	v_lshlrev_b32_e32 v48, 16, v49
	v_and_b32_e32 v49, 0xffff0000, v49
	v_lshlrev_b32_e32 v60, 16, v50
	v_and_b32_e32 v61, 0xffff0000, v50
	v_lshlrev_b32_e32 v50, 16, v51
	v_and_b32_e32 v51, 0xffff0000, v51
	s_waitcnt vmcnt(0)
	v_lshlrev_b32_e32 v62, 16, v52
	v_and_b32_e32 v63, 0xffff0000, v52
	v_lshlrev_b32_e32 v52, 16, v53
	v_and_b32_e32 v53, 0xffff0000, v53
	v_lshlrev_b32_e32 v64, 16, v54
	v_and_b32_e32 v65, 0xffff0000, v54
	v_lshlrev_b32_e32 v54, 16, v55
	v_and_b32_e32 v55, 0xffff0000, v55
	v_pk_add_f32 v[46:47], v[46:47], v[48:49]
	v_pk_add_f32 v[44:45], v[44:45], v[58:59]
	v_pk_add_f32 v[42:43], v[42:43], v[50:51]
	v_pk_add_f32 v[48:49], v[38:39], v[52:53]
	v_pk_add_f32 v[50:51], v[36:37], v[62:63]
	v_pk_add_f32 v[40:41], v[40:41], v[60:61]
	v_pk_add_f32 v[52:53], v[34:35], v[54:55]
	v_pk_add_f32 v[54:55], v[32:33], v[64:65]
	v_cvt_pk_bf16_f32 v32, v44, v45
	v_cvt_pk_bf16_f32 v33, v46, v47
	v_mul_f32_e32 v45, v45, v45
	v_mul_f32_e32 v47, v47, v47
	v_cvt_pk_bf16_f32 v36, v50, v51
	v_cvt_pk_bf16_f32 v37, v48, v49
	v_mul_f32_e32 v51, v51, v51
	v_mul_f32_e32 v49, v49, v49
	v_cvt_pk_bf16_f32 v34, v40, v41
	v_cvt_pk_bf16_f32 v35, v42, v43
	v_mul_f32_e32 v41, v41, v41
	v_cvt_pk_bf16_f32 v38, v54, v55
	v_mul_f32_e32 v55, v55, v55
	v_fmac_f32_e32 v45, v44, v44
	v_fmac_f32_e32 v47, v46, v46
	v_fmac_f32_e32 v51, v50, v50
	v_fmac_f32_e32 v49, v48, v48
	v_mul_f32_e32 v43, v43, v43
	v_cvt_pk_bf16_f32 v39, v52, v53
	v_mul_f32_e32 v53, v53, v53
	global_store_dwordx4 v[56:57], v[32:35], off
	v_fmac_f32_e32 v41, v40, v40
	v_fmac_f32_e32 v55, v54, v54
	v_add_f32_e32 v32, v45, v47
	v_add_f32_e32 v33, v51, v49
	v_fmac_f32_e32 v43, v42, v42
	v_fmac_f32_e32 v53, v52, v52
	v_add_f32_e32 v32, v41, v32
	v_add_f32_e32 v33, v55, v33
	v_add_f32_e32 v32, v43, v32
	v_add_f32_e32 v33, v53, v33
	v_add_f32_e32 v32, v32, v33
	v_mov_b32_e32 v33, v32
	s_nop 1
	v_permlane16_swap_b32_e32 v32, v33
	v_add_f32_e32 v32, v32, v33
	v_mov_b32_e32 v33, v32
	s_nop 1
	v_permlane32_swap_b32_e32 v32, v33
	global_store_dwordx4 v[56:57], v[36:39], off offset:256
	s_and_saveexec_b64 s[0:1], vcc
	v_add_f32_e32 v32, v32, v33
	ds_write_b32 v112, v32 offset:2304
	s_or_b64 exec, exec, s[0:1]
	v_add_u32_e32 v32, 0xa0, v144
	v_ashrrev_i32_e32 v33, 31, v32
	v_lshlrev_b64 v[32:33], 11, v[32:33]
	v_lshl_add_u64 v[32:33], s[8:9], 0, v[32:33]
	v_lshl_add_u64 v[40:41], v[146:147], 1, v[32:33]
	global_load_dwordx4 v[32:35], v[40:41], off nt
	global_load_dwordx4 v[36:39], v[40:41], off offset:256 nt
	s_waitcnt vmcnt(1)
	v_lshlrev_b32_e32 v42, 16, v32
	v_and_b32_e32 v43, 0xffff0000, v32
	v_lshlrev_b32_e32 v32, 16, v33
	v_and_b32_e32 v33, 0xffff0000, v33
	v_lshlrev_b32_e32 v44, 16, v34
	v_and_b32_e32 v45, 0xffff0000, v34
	v_lshlrev_b32_e32 v34, 16, v35
	v_and_b32_e32 v35, 0xffff0000, v35
	s_waitcnt vmcnt(0)
; __device__ __forceinline__ unsigned pk2(float lo, float hi) { f32x2_t v = {lo, hi}; bf16x2_t b = __builtin_convertvector(v, bf16x2_t); return __builtin_bit_cast(unsigned, b); }
; __device__ __forceinline__ float xor16_sum(float v) { const auto r = __builtin_amdgcn_permlane16_swap(__float_as_uint(v), __float_as_uint(v), false, false); return __uint_as_float(r[0]) + __uint_as_float(r[1]); }
;     __device__ __forceinline__ void operator()(const f32x4 (&acc)[2][2][4][2], const Unit& u, int wr, int wc, int fr_in, int fq_in) const {
;     ...
; #pragma unroll
;         for (int ai = 0; ai < 2; ++ai)
; #pragma unroll
;             for (int m = 0; m < 4; ++m) {
;                 const int row = u.pm * BM + ai * 128 + wr * 64 + m * 16 + fr;
;                 float s = 0.f;
; #pragma unroll
;                 for (int bj = 0; bj < 2; ++bj) {
;                     const size_t off = (size_t)row * DM + u.pn * BM + bj * HALF + wc * 32 + 8 * fq;
;                     f32x4 b0, b1;
;                     if (xbase) { b0 = *(const f32x4*)(xbase + off); b1 = *(const f32x4*)(xbase + off + 4); }
;                     else { const u32x4 q = *(const u32x4*)(hb + off);
;                         b0 = (f32x4){BF16_LO(q.x), BF16_HI(q.x), BF16_LO(q.y), BF16_HI(q.y)}; b1 = (f32x4){BF16_LO(q.z), BF16_HI(q.z), BF16_LO(q.w), BF16_HI(q.w)}; }
;                     const f32x4 h0 = b0 + acc[ai][bj][m][0], h1 = b1 + acc[ai][bj][m][1];
;                     u32x4 w; w.x = pk2(h0[0], h0[1]); w.y = pk2(h0[2], h0[3]); w.z = pk2(h1[0], h1[1]); w.w = pk2(h1[2], h1[3]);
;                     *(u32x4*)(hb + off) = w;
;                     s += (h0[0] * h0[0] + h0[1] * h0[1]) + (h0[2] * h0[2] + h0[3] * h0[3]) + (h1[0] * h1[0] + h1[1] * h1[1]) + (h1[2] * h1[2] + h1[3] * h1[3]);
;                 }
;                 s = xor32_sum(xor16_sum(s));
;                 if (fq == 0) xch[(ai * 128 + wr * 64 + m * 16 + fr) * 4 + wc] = s;
;                 if (m == 3) asm volatile("" ::: "memory");
;             }
;         PG8_EPI_BAR();
;         if (fq == 0) {
; #pragma unroll
;             for (int ai = 0; ai < 2; ++ai) {
;                 const int rl = ai * 128 + wr * 64 + wc * 16 + fr;
;                 const f32x4 p = *(const PG8_LAS f32x4*)(xch + rl * 4);
;                 const float t = (p[0] + p[1]) + (p[2] + p[3]);
;                 atomicAdd(rsq + u.pm * BM + rl, (u64_t)(t * 16777216.0f));
	v_lshlrev_b32_e32 v46, 16, v36
	v_and_b32_e32 v47, 0xffff0000, v36
	v_lshlrev_b32_e32 v36, 16, v37
	v_and_b32_e32 v37, 0xffff0000, v37
	v_lshlrev_b32_e32 v48, 16, v38
	v_and_b32_e32 v49, 0xffff0000, v38
	v_lshlrev_b32_e32 v38, 16, v39
	v_and_b32_e32 v39, 0xffff0000, v39
	v_pk_add_f32 v[30:31], v[30:31], v[32:33]
	v_pk_add_f32 v[28:29], v[28:29], v[42:43]
	v_pk_add_f32 v[26:27], v[26:27], v[34:35]
	v_pk_add_f32 v[32:33], v[22:23], v[36:37]
	v_pk_add_f32 v[34:35], v[20:21], v[46:47]
	v_pk_add_f32 v[24:25], v[24:25], v[44:45]
	v_pk_add_f32 v[36:37], v[18:19], v[38:39]
	v_pk_add_f32 v[38:39], v[16:17], v[48:49]
	v_cvt_pk_bf16_f32 v16, v28, v29
	v_cvt_pk_bf16_f32 v17, v30, v31
	v_mul_f32_e32 v29, v29, v29
	v_mul_f32_e32 v31, v31, v31
	v_cvt_pk_bf16_f32 v20, v34, v35
	v_cvt_pk_bf16_f32 v21, v32, v33
	v_mul_f32_e32 v35, v35, v35
	v_mul_f32_e32 v33, v33, v33
	v_cvt_pk_bf16_f32 v18, v24, v25
	v_cvt_pk_bf16_f32 v19, v26, v27
	v_mul_f32_e32 v25, v25, v25
	v_cvt_pk_bf16_f32 v22, v38, v39
	v_mul_f32_e32 v39, v39, v39
	v_fmac_f32_e32 v29, v28, v28
	v_fmac_f32_e32 v31, v30, v30
	v_fmac_f32_e32 v35, v34, v34
	v_fmac_f32_e32 v33, v32, v32
	v_mul_f32_e32 v27, v27, v27
	v_cvt_pk_bf16_f32 v23, v36, v37
	v_mul_f32_e32 v37, v37, v37
	global_store_dwordx4 v[40:41], v[16:19], off
	v_fmac_f32_e32 v25, v24, v24
	v_fmac_f32_e32 v39, v38, v38
	v_add_f32_e32 v16, v29, v31
	v_add_f32_e32 v17, v35, v33
	v_fmac_f32_e32 v27, v26, v26
	v_fmac_f32_e32 v37, v36, v36
	v_add_f32_e32 v16, v25, v16
	v_add_f32_e32 v17, v39, v17
	v_add_f32_e32 v16, v27, v16
	v_add_f32_e32 v17, v37, v17
	v_add_f32_e32 v16, v16, v17
	v_mov_b32_e32 v17, v16
	s_nop 1
	v_permlane16_swap_b32_e32 v16, v17
	v_add_f32_e32 v16, v16, v17
	v_mov_b32_e32 v17, v16
	s_nop 1
	v_permlane32_swap_b32_e32 v16, v17
	global_store_dwordx4 v[40:41], v[20:23], off offset:256
	s_and_saveexec_b64 s[0:1], vcc
	v_add_f32_e32 v16, v16, v17
	ds_write_b32 v112, v16 offset:2560
	s_or_b64 exec, exec, s[0:1]
	v_add_u32_e32 v16, 0xb0, v144
	v_ashrrev_i32_e32 v17, 31, v16
	v_lshlrev_b64 v[16:17], 11, v[16:17]
	v_lshl_add_u64 v[16:17], s[8:9], 0, v[16:17]
	v_lshl_add_u64 v[24:25], v[146:147], 1, v[16:17]
	global_load_dwordx4 v[16:19], v[24:25], off nt
	global_load_dwordx4 v[20:23], v[24:25], off offset:256 nt
	s_waitcnt vmcnt(1)
	v_lshlrev_b32_e32 v26, 16, v16
	v_and_b32_e32 v27, 0xffff0000, v16
	v_lshlrev_b32_e32 v16, 16, v17
	v_and_b32_e32 v17, 0xffff0000, v17
	v_lshlrev_b32_e32 v28, 16, v18
	v_and_b32_e32 v29, 0xffff0000, v18
	v_lshlrev_b32_e32 v18, 16, v19
	v_and_b32_e32 v19, 0xffff0000, v19
	s_waitcnt vmcnt(0)
	v_lshlrev_b32_e32 v30, 16, v20
	v_and_b32_e32 v31, 0xffff0000, v20
	v_lshlrev_b32_e32 v20, 16, v21
	v_and_b32_e32 v21, 0xffff0000, v21
	v_lshlrev_b32_e32 v32, 16, v22
	v_and_b32_e32 v33, 0xffff0000, v22
	v_lshlrev_b32_e32 v22, 16, v23
	v_and_b32_e32 v23, 0xffff0000, v23
	v_pk_add_f32 v[14:15], v[14:15], v[16:17]
	v_pk_add_f32 v[12:13], v[12:13], v[26:27]
	v_pk_add_f32 v[10:11], v[10:11], v[18:19]
	v_pk_add_f32 v[16:17], v[6:7], v[20:21]
	v_pk_add_f32 v[18:19], v[4:5], v[30:31]
	v_pk_add_f32 v[8:9], v[8:9], v[28:29]
	v_pk_add_f32 v[20:21], v[2:3], v[22:23]
	v_pk_add_f32 v[22:23], v[0:1], v[32:33]
	v_cvt_pk_bf16_f32 v0, v12, v13
	v_cvt_pk_bf16_f32 v1, v14, v15
	v_mul_f32_e32 v13, v13, v13
	v_mul_f32_e32 v15, v15, v15
	v_cvt_pk_bf16_f32 v4, v18, v19
	v_cvt_pk_bf16_f32 v5, v16, v17
	v_mul_f32_e32 v19, v19, v19
	v_mul_f32_e32 v17, v17, v17
	v_cvt_pk_bf16_f32 v2, v8, v9
	v_cvt_pk_bf16_f32 v3, v10, v11
	v_mul_f32_e32 v9, v9, v9
	v_cvt_pk_bf16_f32 v6, v22, v23
	v_mul_f32_e32 v23, v23, v23
	v_fmac_f32_e32 v13, v12, v12
	v_fmac_f32_e32 v15, v14, v14
	v_fmac_f32_e32 v19, v18, v18
	v_fmac_f32_e32 v17, v16, v16
	v_mul_f32_e32 v11, v11, v11
	v_cvt_pk_bf16_f32 v7, v20, v21
	v_mul_f32_e32 v21, v21, v21
	global_store_dwordx4 v[24:25], v[0:3], off
	v_fmac_f32_e32 v9, v8, v8
	v_fmac_f32_e32 v23, v22, v22
	v_add_f32_e32 v0, v13, v15
	v_add_f32_e32 v1, v19, v17
	v_fmac_f32_e32 v11, v10, v10
	v_fmac_f32_e32 v21, v20, v20
	v_add_f32_e32 v0, v9, v0
	v_add_f32_e32 v1, v23, v1
	v_add_f32_e32 v0, v11, v0
	v_add_f32_e32 v1, v21, v1
	v_add_f32_e32 v0, v0, v1
	v_mov_b32_e32 v1, v0
	s_nop 1
	v_permlane16_swap_b32_e32 v0, v1
	v_add_f32_e32 v0, v0, v1
	v_mov_b32_e32 v1, v0
	s_nop 1
	v_permlane32_swap_b32_e32 v0, v1
	global_store_dwordx4 v[24:25], v[4:7], off offset:256
	s_and_saveexec_b64 s[0:1], vcc
	v_add_f32_e32 v0, v0, v1
	ds_write_b32 v112, v0 offset:2816
	s_or_b64 exec, exec, s[0:1]
	s_waitcnt lgkmcnt(0)
	s_barrier
	s_and_saveexec_b64 s[0:1], vcc
	s_cbranch_execz .LBB0_892
	v_add_u32_e32 v4, s46, v168
	v_lshl_add_u32 v6, v4, 4, v167
	ds_read_b128 v[0:3], v6
	s_ashr_i32 s5, s4, 31
	s_lshl_b64 s[4:5], s[4:5], 3
	s_add_u32 s4, s37, s4
	s_addc_u32 s5, s38, s5
	s_waitcnt lgkmcnt(0)
	v_add_f32_e32 v0, v0, v1
	v_add_f32_e32 v1, v2, v3
	v_add_f32_e32 v0, v0, v1
	v_mul_f32_e32 v0, 0x4b800000, v0
	v_trunc_f32_e32 v0, v0
	v_mul_f32_e32 v1, 0x2f800000, v0
	v_floor_f32_e32 v1, v1
	v_fmac_f32_e32 v0, 0xcf800000, v1
	v_cvt_u32_f32_e32 v0, v0
	v_cvt_u32_f32_e32 v1, v1
	v_ashrrev_i32_e32 v5, 31, v4
	v_lshl_add_u64 v[4:5], v[4:5], 3, s[4:5]
	global_atomic_add_x2 v[4:5], v[0:1], off
	ds_read_b128 v[0:3], v6 offset:2048
	s_waitcnt lgkmcnt(0)
	v_add_f32_e32 v0, v0, v1
	v_add_f32_e32 v1, v2, v3
	v_add_f32_e32 v0, v0, v1
	v_mul_f32_e32 v0, 0x4b800000, v0
	v_trunc_f32_e32 v0, v0
	v_mul_f32_e32 v1, 0x2f800000, v0
	v_floor_f32_e32 v1, v1
	v_fmac_f32_e32 v0, 0xcf800000, v1
	v_cvt_u32_f32_e32 v0, v0
	v_cvt_u32_f32_e32 v1, v1
	global_atomic_add_x2 v[4:5], v[0:1], off offset:1024

; __device__ __forceinline__ unsigned pk2(float lo, float hi) { f32x2_t v = {lo, hi}; bf16x2_t b = __builtin_convertvector(v, bf16x2_t); return __builtin_bit_cast(unsigned, b); }
; #define BF16_LO(w) __uint_as_float((w) << 16)
; #define BF16_HI(w) __uint_as_float((w) & 0xffff0000u)
;     __device__ __forceinline__ void operator()(const f32x4 (&acc)[2][2][4][2], const Unit& u, int wr, int wc, int fr_in, int fq_in) const {
;     ...
; #pragma unroll
;                 for (int bj = 0; bj < 2; ++bj) {
;                     const size_t off = (size_t)(u.pm * BM + ai * 128 + wr * 64 + m * 16 + fr) * DM + u.pn * BM + bj * HALF + wc * 32 + 8 * fq;
;                     const u32x4 s = *(const u32x4*)(SG + off), q = *(const u32x4*)(hb + off);
;                     const f32x4 s0 = {BF16_LO(s.x), BF16_HI(s.x), BF16_LO(s.y), BF16_HI(s.y)}, s1 = {BF16_LO(s.z), BF16_HI(s.z), BF16_LO(s.w), BF16_HI(s.w)};
;                     const f32x4 b0 = {BF16_LO(q.x), BF16_HI(q.x), BF16_LO(q.y), BF16_HI(q.y)}, b1 = {BF16_LO(q.z), BF16_HI(q.z), BF16_LO(q.w), BF16_HI(q.w)};
;                     const f32x4 h0 = b0 + acc[ai][bj][m][0] * s0, h1 = b1 + acc[ai][bj][m][1] * s1;
;                     if (outf) { *(f32x4*)(outf + off) = h0; *(f32x4*)(outf + off + 4) = h1; }
;                     else { u32x4 w; w.x = pk2(h0[0], h0[1]); w.y = pk2(h0[2], h0[3]); w.z = pk2(h1[0], h1[1]); w.w = pk2(h1[2], h1[3]); *(u32x4*)(hb + off) = w; }
;                     if (bj == 1 && (m & 1)) asm volatile("" ::: "memory");
.LBB0_1049:
	v_mov_b32_e32 v144, v149
	v_mov_b32_e32 v145, v148
	s_lshl_b32 s0, s58, 8
	s_add_i32 s0, s0, s51
	v_add_u32_e32 v144, s0, v144
	s_lshl_b32 s0, s59, 8
	s_ashr_i32 s1, s0, 31
	v_lshlrev_b32_e32 v146, 3, v145
	v_ashrrev_i32_e32 v147, 31, v146
	s_or_b64 s[0:1], s[0:1], s[24:25]
	v_ashrrev_i32_e32 v145, 31, v144
	v_lshl_add_u64 v[146:147], s[0:1], 0, v[146:147]
	v_lshlrev_b64 v[168:169], 10, v[144:145]
	v_lshl_add_u64 v[168:169], v[146:147], 0, v[168:169]
	v_lshlrev_b64 v[172:173], 1, v[168:169]
	v_lshl_add_u64 v[180:181], s[16:17], 0, v[172:173]
	global_load_dwordx4 v[168:171], v[180:181], off nt
	v_lshl_add_u64 v[182:183], s[20:21], 0, v[172:173]
	global_load_dwordx4 v[172:175], v[182:183], off nt
	global_load_dwordx4 v[176:179], v[182:183], off offset:256 nt
	s_and_b64 vcc, exec, s[12:13]
	s_mov_b64 s[0:1], -1
	s_waitcnt vmcnt(0)
	v_lshlrev_b32_e32 v184, 16, v168
	v_and_b32_e32 v185, 0xffff0000, v168
	v_lshlrev_b32_e32 v168, 16, v169
	v_and_b32_e32 v169, 0xffff0000, v169
	v_lshlrev_b32_e32 v186, 16, v170
	v_and_b32_e32 v187, 0xffff0000, v170
	v_lshlrev_b32_e32 v170, 16, v171
	v_and_b32_e32 v171, 0xffff0000, v171
	v_lshlrev_b32_e32 v188, 16, v172
	v_and_b32_e32 v189, 0xffff0000, v172
	v_lshlrev_b32_e32 v172, 16, v173
	v_and_b32_e32 v173, 0xffff0000, v173
	v_lshlrev_b32_e32 v190, 16, v174
	v_and_b32_e32 v191, 0xffff0000, v174
	v_lshlrev_b32_e32 v174, 16, v175
	v_and_b32_e32 v175, 0xffff0000, v175
	v_pk_fma_f32 v[126:127], v[126:127], v[168:169], v[172:173]
	v_pk_fma_f32 v[124:125], v[124:125], v[184:185], v[188:189]
	v_pk_fma_f32 v[168:169], v[122:123], v[170:171], v[174:175]
	v_pk_fma_f32 v[122:123], v[120:121], v[186:187], v[190:191]
	v_cvt_pk_bf16_f32 v120, v124, v125
	v_cvt_pk_bf16_f32 v121, v126, v127
	v_cvt_pk_bf16_f32 v122, v122, v123
	v_cvt_pk_bf16_f32 v123, v168, v169
	global_store_dwordx4 v[182:183], v[120:123], off
	global_load_dwordx4 v[120:123], v[180:181], off offset:256 nt
	v_add_u32_e32 v124, 16, v144
	v_ashrrev_i32_e32 v125, 31, v124
	v_lshlrev_b64 v[124:125], 10, v[124:125]
	v_lshlrev_b32_e32 v168, 16, v176
	v_and_b32_e32 v169, 0xffff0000, v176
	v_lshlrev_b32_e32 v170, 16, v177
	v_and_b32_e32 v171, 0xffff0000, v177
	v_lshlrev_b32_e32 v172, 16, v178
	v_and_b32_e32 v173, 0xffff0000, v178
	v_lshlrev_b32_e32 v174, 16, v179
	v_and_b32_e32 v175, 0xffff0000, v179
	v_lshl_add_u64 v[124:125], v[124:125], 0, v[146:147]
	v_lshlrev_b64 v[124:125], 1, v[124:125]
	v_lshl_add_u64 v[126:127], s[16:17], 0, v[124:125]
	v_lshl_add_u64 v[124:125], s[20:21], 0, v[124:125]
	s_waitcnt vmcnt(0)
	v_lshlrev_b32_e32 v176, 16, v120
	v_and_b32_e32 v177, 0xffff0000, v120
	v_lshlrev_b32_e32 v120, 16, v121
	v_and_b32_e32 v121, 0xffff0000, v121
	v_lshlrev_b32_e32 v178, 16, v122
	v_and_b32_e32 v179, 0xffff0000, v122
	v_lshlrev_b32_e32 v122, 16, v123
	v_and_b32_e32 v123, 0xffff0000, v123
	v_pk_fma_f32 v[118:119], v[118:119], v[120:121], v[170:171]
	v_pk_fma_f32 v[116:117], v[116:117], v[176:177], v[168:169]
	v_pk_fma_f32 v[120:121], v[114:115], v[122:123], v[174:175]
	v_pk_fma_f32 v[114:115], v[112:113], v[178:179], v[172:173]
	v_cvt_pk_bf16_f32 v112, v116, v117
	v_cvt_pk_bf16_f32 v113, v118, v119
	v_cvt_pk_bf16_f32 v114, v114, v115
	v_cvt_pk_bf16_f32 v115, v120, v121
	global_store_dwordx4 v[182:183], v[112:115], off offset:256
	global_load_dwordx4 v[112:115], v[126:127], off nt
	s_nop 0
	global_load_dwordx4 v[116:119], v[124:125], off nt
	global_load_dwordx4 v[120:123], v[124:125], off offset:256 nt
	s_waitcnt vmcnt(0)
	v_lshlrev_b32_e32 v172, 16, v116
	v_lshlrev_b32_e32 v168, 16, v112
	v_and_b32_e32 v169, 0xffff0000, v112
	v_lshlrev_b32_e32 v112, 16, v113
	v_and_b32_e32 v113, 0xffff0000, v113
	v_lshlrev_b32_e32 v170, 16, v114
	v_and_b32_e32 v171, 0xffff0000, v114
	v_lshlrev_b32_e32 v114, 16, v115
	v_and_b32_e32 v115, 0xffff0000, v115
	v_and_b32_e32 v173, 0xffff0000, v116
	v_lshlrev_b32_e32 v116, 16, v117
	v_and_b32_e32 v117, 0xffff0000, v117
	v_lshlrev_b32_e32 v174, 16, v118
	v_and_b32_e32 v175, 0xffff0000, v118
	v_lshlrev_b32_e32 v118, 16, v119
	v_and_b32_e32 v119, 0xffff0000, v119
	v_pk_fma_f32 v[110:111], v[110:111], v[112:113], v[116:117]
	v_pk_fma_f32 v[108:109], v[108:109], v[168:169], v[172:173]
	v_pk_fma_f32 v[112:113], v[106:107], v[114:115], v[118:119]
	v_pk_fma_f32 v[106:107], v[104:105], v[170:171], v[174:175]
	v_cvt_pk_bf16_f32 v104, v108, v109
	v_cvt_pk_bf16_f32 v105, v110, v111
	v_cvt_pk_bf16_f32 v106, v106, v107
	v_cvt_pk_bf16_f32 v107, v112, v113
	global_store_dwordx4 v[124:125], v[104:107], off
	global_load_dwordx4 v[104:107], v[126:127], off offset:256 nt
	v_add_u32_e32 v108, 32, v144
	v_ashrrev_i32_e32 v109, 31, v108
	v_lshlrev_b32_e32 v112, 16, v120
	v_and_b32_e32 v113, 0xffff0000, v120
	v_lshlrev_b32_e32 v114, 16, v121
	v_and_b32_e32 v115, 0xffff0000, v121
	v_lshlrev_b32_e32 v116, 16, v122
	v_and_b32_e32 v117, 0xffff0000, v122
	v_lshlrev_b32_e32 v118, 16, v123
	v_and_b32_e32 v119, 0xffff0000, v123
	v_lshlrev_b64 v[108:109], 10, v[108:109]
	v_lshl_add_u64 v[108:109], v[108:109], 0, v[146:147]
	v_lshlrev_b64 v[108:109], 1, v[108:109]
	v_lshl_add_u64 v[110:111], s[16:17], 0, v[108:109]
	v_lshl_add_u64 v[108:109], s[20:21], 0, v[108:109]
	s_waitcnt vmcnt(0)
	v_lshlrev_b32_e32 v120, 16, v104
	v_and_b32_e32 v121, 0xffff0000, v104
	v_lshlrev_b32_e32 v104, 16, v105
	v_and_b32_e32 v105, 0xffff0000, v105
	v_lshlrev_b32_e32 v122, 16, v106
	v_and_b32_e32 v123, 0xffff0000, v106
	v_lshlrev_b32_e32 v106, 16, v107
	v_and_b32_e32 v107, 0xffff0000, v107
	v_pk_fma_f32 v[102:103], v[102:103], v[104:105], v[114:115]
	v_pk_fma_f32 v[100:101], v[100:101], v[120:121], v[112:113]
	v_pk_fma_f32 v[104:105], v[98:99], v[106:107], v[118:119]
	v_pk_fma_f32 v[98:99], v[96:97], v[122:123], v[116:117]
	v_cvt_pk_bf16_f32 v96, v100, v101
	v_cvt_pk_bf16_f32 v97, v102, v103
	v_cvt_pk_bf16_f32 v98, v98, v99
	v_cvt_pk_bf16_f32 v99, v104, v105
	global_store_dwordx4 v[124:125], v[96:99], off offset:256
	global_load_dwordx4 v[96:99], v[110:111], off nt
	global_load_dwordx4 v[100:103], v[108:109], off nt
	global_load_dwordx4 v[104:107], v[108:109], off offset:256 nt
	s_waitcnt vmcnt(0)
; __device__ __forceinline__ unsigned pk2(float lo, float hi) { f32x2_t v = {lo, hi}; bf16x2_t b = __builtin_convertvector(v, bf16x2_t); return __builtin_bit_cast(unsigned, b); }
; #define BF16_LO(w) __uint_as_float((w) << 16)
; #define BF16_HI(w) __uint_as_float((w) & 0xffff0000u)
;     __device__ __forceinline__ void operator()(const f32x4 (&acc)[2][2][4][2], const Unit& u, int wr, int wc, int fr_in, int fq_in) const {
;     ...
; #pragma unroll
;                 for (int bj = 0; bj < 2; ++bj) {
;                     const size_t off = (size_t)(u.pm * BM + ai * 128 + wr * 64 + m * 16 + fr) * DM + u.pn * BM + bj * HALF + wc * 32 + 8 * fq;
;                     const u32x4 s = *(const u32x4*)(SG + off), q = *(const u32x4*)(hb + off);
;                     const f32x4 s0 = {BF16_LO(s.x), BF16_HI(s.x), BF16_LO(s.y), BF16_HI(s.y)}, s1 = {BF16_LO(s.z), BF16_HI(s.z), BF16_LO(s.w), BF16_HI(s.w)};
;                     const f32x4 b0 = {BF16_LO(q.x), BF16_HI(q.x), BF16_LO(q.y), BF16_HI(q.y)}, b1 = {BF16_LO(q.z), BF16_HI(q.z), BF16_LO(q.w), BF16_HI(q.w)};
;                     const f32x4 h0 = b0 + acc[ai][bj][m][0] * s0, h1 = b1 + acc[ai][bj][m][1] * s1;
;                     if (outf) { *(f32x4*)(outf + off) = h0; *(f32x4*)(outf + off + 4) = h1; }
;                     else { u32x4 w; w.x = pk2(h0[0], h0[1]); w.y = pk2(h0[2], h0[3]); w.z = pk2(h1[0], h1[1]); w.w = pk2(h1[2], h1[3]); *(u32x4*)(hb + off) = w; }
;                     if (bj == 1 && (m & 1)) asm volatile("" ::: "memory");
	v_lshlrev_b32_e32 v116, 16, v100
	v_lshlrev_b32_e32 v112, 16, v96
	v_and_b32_e32 v113, 0xffff0000, v96
	v_lshlrev_b32_e32 v96, 16, v97
	v_and_b32_e32 v97, 0xffff0000, v97
	v_lshlrev_b32_e32 v114, 16, v98
	v_and_b32_e32 v115, 0xffff0000, v98
	v_lshlrev_b32_e32 v98, 16, v99
	v_and_b32_e32 v99, 0xffff0000, v99
	v_and_b32_e32 v117, 0xffff0000, v100
	v_lshlrev_b32_e32 v100, 16, v101
	v_and_b32_e32 v101, 0xffff0000, v101
	v_lshlrev_b32_e32 v118, 16, v102
	v_and_b32_e32 v119, 0xffff0000, v102
	v_lshlrev_b32_e32 v102, 16, v103
	v_and_b32_e32 v103, 0xffff0000, v103
	v_pk_fma_f32 v[94:95], v[94:95], v[96:97], v[100:101]
	v_pk_fma_f32 v[92:93], v[92:93], v[112:113], v[116:117]
	v_pk_fma_f32 v[96:97], v[90:91], v[98:99], v[102:103]
	v_pk_fma_f32 v[90:91], v[88:89], v[114:115], v[118:119]
	v_cvt_pk_bf16_f32 v88, v92, v93
	v_cvt_pk_bf16_f32 v89, v94, v95
	v_cvt_pk_bf16_f32 v90, v90, v91
	v_cvt_pk_bf16_f32 v91, v96, v97
	global_store_dwordx4 v[108:109], v[88:91], off
	global_load_dwordx4 v[88:91], v[110:111], off offset:256 nt
	v_add_u32_e32 v92, 48, v144
	v_ashrrev_i32_e32 v93, 31, v92
	v_lshlrev_b64 v[92:93], 10, v[92:93]
	v_lshlrev_b32_e32 v96, 16, v104
	v_and_b32_e32 v97, 0xffff0000, v104
	v_lshlrev_b32_e32 v98, 16, v105
	v_and_b32_e32 v99, 0xffff0000, v105
	v_lshlrev_b32_e32 v100, 16, v106
	v_and_b32_e32 v101, 0xffff0000, v106
	v_lshlrev_b32_e32 v102, 16, v107
	v_and_b32_e32 v103, 0xffff0000, v107
	v_lshl_add_u64 v[92:93], v[92:93], 0, v[146:147]
	v_lshlrev_b64 v[92:93], 1, v[92:93]
	v_lshl_add_u64 v[94:95], s[16:17], 0, v[92:93]
	v_lshl_add_u64 v[92:93], s[20:21], 0, v[92:93]
	s_waitcnt vmcnt(0)
	v_lshlrev_b32_e32 v104, 16, v88
	v_and_b32_e32 v105, 0xffff0000, v88
	v_lshlrev_b32_e32 v88, 16, v89
	v_and_b32_e32 v89, 0xffff0000, v89
	v_lshlrev_b32_e32 v106, 16, v90
	v_and_b32_e32 v107, 0xffff0000, v90
	v_lshlrev_b32_e32 v90, 16, v91
	v_and_b32_e32 v91, 0xffff0000, v91
	v_pk_fma_f32 v[86:87], v[86:87], v[88:89], v[98:99]
	v_pk_fma_f32 v[84:85], v[84:85], v[104:105], v[96:97]
	v_pk_fma_f32 v[88:89], v[82:83], v[90:91], v[102:103]
	v_pk_fma_f32 v[82:83], v[80:81], v[106:107], v[100:101]
	v_cvt_pk_bf16_f32 v80, v84, v85
	v_cvt_pk_bf16_f32 v81, v86, v87
	v_cvt_pk_bf16_f32 v82, v82, v83
	v_cvt_pk_bf16_f32 v83, v88, v89
	global_store_dwordx4 v[108:109], v[80:83], off offset:256
	global_load_dwordx4 v[80:83], v[94:95], off nt
	s_nop 0
	global_load_dwordx4 v[84:87], v[92:93], off nt
	global_load_dwordx4 v[88:91], v[92:93], off offset:256 nt
	s_waitcnt vmcnt(0)
	v_lshlrev_b32_e32 v96, 16, v80
	v_and_b32_e32 v97, 0xffff0000, v80
	v_lshlrev_b32_e32 v80, 16, v81
	v_and_b32_e32 v81, 0xffff0000, v81
	v_lshlrev_b32_e32 v98, 16, v82
	v_and_b32_e32 v99, 0xffff0000, v82
	v_lshlrev_b32_e32 v82, 16, v83
	v_and_b32_e32 v83, 0xffff0000, v83
	v_lshlrev_b32_e32 v100, 16, v84
	v_and_b32_e32 v101, 0xffff0000, v84
	v_lshlrev_b32_e32 v84, 16, v85
	v_and_b32_e32 v85, 0xffff0000, v85
	v_lshlrev_b32_e32 v102, 16, v86
	v_and_b32_e32 v103, 0xffff0000, v86
	v_lshlrev_b32_e32 v86, 16, v87
	v_and_b32_e32 v87, 0xffff0000, v87
	v_pk_fma_f32 v[78:79], v[78:79], v[80:81], v[84:85]
	v_pk_fma_f32 v[76:77], v[76:77], v[96:97], v[100:101]
	v_pk_fma_f32 v[80:81], v[74:75], v[82:83], v[86:87]
	v_pk_fma_f32 v[74:75], v[72:73], v[98:99], v[102:103]
	v_cvt_pk_bf16_f32 v72, v76, v77
	v_cvt_pk_bf16_f32 v73, v78, v79
	v_cvt_pk_bf16_f32 v74, v74, v75
	v_cvt_pk_bf16_f32 v75, v80, v81
	global_store_dwordx4 v[92:93], v[72:75], off
	global_load_dwordx4 v[72:75], v[94:95], off offset:256 nt
	v_add_u32_e32 v76, 0x80, v144
	v_ashrrev_i32_e32 v77, 31, v76
	v_lshlrev_b32_e32 v80, 16, v88
	v_and_b32_e32 v81, 0xffff0000, v88
	v_lshlrev_b32_e32 v82, 16, v89
	v_and_b32_e32 v83, 0xffff0000, v89
	v_lshlrev_b32_e32 v84, 16, v90
	v_and_b32_e32 v85, 0xffff0000, v90
	v_lshlrev_b32_e32 v86, 16, v91
	v_and_b32_e32 v87, 0xffff0000, v91
	v_lshlrev_b64 v[76:77], 10, v[76:77]
	v_lshl_add_u64 v[76:77], v[76:77], 0, v[146:147]
	v_lshlrev_b64 v[76:77], 1, v[76:77]
	v_lshl_add_u64 v[78:79], s[16:17], 0, v[76:77]
	v_lshl_add_u64 v[76:77], s[20:21], 0, v[76:77]
	s_waitcnt vmcnt(0)
	v_lshlrev_b32_e32 v88, 16, v72
	v_and_b32_e32 v89, 0xffff0000, v72
	v_lshlrev_b32_e32 v72, 16, v73
	v_and_b32_e32 v73, 0xffff0000, v73
	v_lshlrev_b32_e32 v90, 16, v74
	v_and_b32_e32 v91, 0xffff0000, v74
	v_lshlrev_b32_e32 v74, 16, v75
	v_and_b32_e32 v75, 0xffff0000, v75
	v_pk_fma_f32 v[70:71], v[70:71], v[72:73], v[82:83]
	v_pk_fma_f32 v[68:69], v[68:69], v[88:89], v[80:81]
	v_pk_fma_f32 v[72:73], v[66:67], v[74:75], v[86:87]
	v_pk_fma_f32 v[66:67], v[64:65], v[90:91], v[84:85]
	v_cvt_pk_bf16_f32 v64, v68, v69
	v_cvt_pk_bf16_f32 v65, v70, v71
	v_cvt_pk_bf16_f32 v66, v66, v67
	v_cvt_pk_bf16_f32 v67, v72, v73
	global_store_dwordx4 v[92:93], v[64:67], off offset:256
	global_load_dwordx4 v[64:67], v[78:79], off nt
	global_load_dwordx4 v[68:71], v[76:77], off nt
	global_load_dwordx4 v[72:75], v[76:77], off offset:256 nt
	s_waitcnt vmcnt(0)
; __device__ __forceinline__ unsigned pk2(float lo, float hi) { f32x2_t v = {lo, hi}; bf16x2_t b = __builtin_convertvector(v, bf16x2_t); return __builtin_bit_cast(unsigned, b); }
; #define BF16_LO(w) __uint_as_float((w) << 16)
; #define BF16_HI(w) __uint_as_float((w) & 0xffff0000u)
;     __device__ __forceinline__ void operator()(const f32x4 (&acc)[2][2][4][2], const Unit& u, int wr, int wc, int fr_in, int fq_in) const {
;     ...
; #pragma unroll
;                 for (int bj = 0; bj < 2; ++bj) {
;                     const size_t off = (size_t)(u.pm * BM + ai * 128 + wr * 64 + m * 16 + fr) * DM + u.pn * BM + bj * HALF + wc * 32 + 8 * fq;
;                     const u32x4 s = *(const u32x4*)(SG + off), q = *(const u32x4*)(hb + off);
;                     const f32x4 s0 = {BF16_LO(s.x), BF16_HI(s.x), BF16_LO(s.y), BF16_HI(s.y)}, s1 = {BF16_LO(s.z), BF16_HI(s.z), BF16_LO(s.w), BF16_HI(s.w)};
;                     const f32x4 b0 = {BF16_LO(q.x), BF16_HI(q.x), BF16_LO(q.y), BF16_HI(q.y)}, b1 = {BF16_LO(q.z), BF16_HI(q.z), BF16_LO(q.w), BF16_HI(q.w)};
;                     const f32x4 h0 = b0 + acc[ai][bj][m][0] * s0, h1 = b1 + acc[ai][bj][m][1] * s1;
;                     if (outf) { *(f32x4*)(outf + off) = h0; *(f32x4*)(outf + off + 4) = h1; }
;                     else { u32x4 w; w.x = pk2(h0[0], h0[1]); w.y = pk2(h0[2], h0[3]); w.z = pk2(h1[0], h1[1]); w.w = pk2(h1[2], h1[3]); *(u32x4*)(hb + off) = w; }
;                     if (bj == 1 && (m & 1)) asm volatile("" ::: "memory");
	v_lshlrev_b32_e32 v80, 16, v64
	v_and_b32_e32 v81, 0xffff0000, v64
	v_lshlrev_b32_e32 v64, 16, v65
	v_and_b32_e32 v65, 0xffff0000, v65
	v_lshlrev_b32_e32 v82, 16, v66
	v_and_b32_e32 v83, 0xffff0000, v66
	v_lshlrev_b32_e32 v66, 16, v67
	v_and_b32_e32 v67, 0xffff0000, v67
	v_lshlrev_b32_e32 v84, 16, v68
	v_and_b32_e32 v85, 0xffff0000, v68
	v_lshlrev_b32_e32 v68, 16, v69
	v_and_b32_e32 v69, 0xffff0000, v69
	v_lshlrev_b32_e32 v86, 16, v70
	v_and_b32_e32 v87, 0xffff0000, v70
	v_lshlrev_b32_e32 v70, 16, v71
	v_and_b32_e32 v71, 0xffff0000, v71
	v_pk_fma_f32 v[62:63], v[62:63], v[64:65], v[68:69]
	v_pk_fma_f32 v[60:61], v[60:61], v[80:81], v[84:85]
	v_pk_fma_f32 v[64:65], v[58:59], v[66:67], v[70:71]
	v_pk_fma_f32 v[58:59], v[56:57], v[82:83], v[86:87]
	v_cvt_pk_bf16_f32 v56, v60, v61
	v_cvt_pk_bf16_f32 v57, v62, v63
	v_cvt_pk_bf16_f32 v58, v58, v59
	v_cvt_pk_bf16_f32 v59, v64, v65
	global_store_dwordx4 v[76:77], v[56:59], off
	global_load_dwordx4 v[56:59], v[78:79], off offset:256 nt
	v_add_u32_e32 v60, 0x90, v144
	v_ashrrev_i32_e32 v61, 31, v60
	v_lshlrev_b64 v[60:61], 10, v[60:61]
	v_lshlrev_b32_e32 v64, 16, v72
	v_and_b32_e32 v65, 0xffff0000, v72
	v_lshlrev_b32_e32 v66, 16, v73
	v_and_b32_e32 v67, 0xffff0000, v73
	v_lshlrev_b32_e32 v68, 16, v74
	v_and_b32_e32 v69, 0xffff0000, v74
	v_lshlrev_b32_e32 v70, 16, v75
	v_and_b32_e32 v71, 0xffff0000, v75
	v_lshl_add_u64 v[60:61], v[60:61], 0, v[146:147]
	v_lshlrev_b64 v[60:61], 1, v[60:61]
	v_lshl_add_u64 v[62:63], s[16:17], 0, v[60:61]
	v_lshl_add_u64 v[60:61], s[20:21], 0, v[60:61]
	s_waitcnt vmcnt(0)
	v_lshlrev_b32_e32 v72, 16, v56
	v_and_b32_e32 v73, 0xffff0000, v56
	v_lshlrev_b32_e32 v56, 16, v57
	v_and_b32_e32 v57, 0xffff0000, v57
	v_lshlrev_b32_e32 v74, 16, v58
	v_and_b32_e32 v75, 0xffff0000, v58
	v_lshlrev_b32_e32 v58, 16, v59
	v_and_b32_e32 v59, 0xffff0000, v59
	v_pk_fma_f32 v[54:55], v[54:55], v[56:57], v[66:67]
	v_pk_fma_f32 v[52:53], v[52:53], v[72:73], v[64:65]
	v_pk_fma_f32 v[56:57], v[50:51], v[58:59], v[70:71]
	v_pk_fma_f32 v[50:51], v[48:49], v[74:75], v[68:69]
	v_cvt_pk_bf16_f32 v48, v52, v53
	v_cvt_pk_bf16_f32 v49, v54, v55
	v_cvt_pk_bf16_f32 v50, v50, v51
	v_cvt_pk_bf16_f32 v51, v56, v57
	global_store_dwordx4 v[76:77], v[48:51], off offset:256
	global_load_dwordx4 v[48:51], v[62:63], off nt
	s_nop 0
	global_load_dwordx4 v[52:55], v[60:61], off nt
	global_load_dwordx4 v[56:59], v[60:61], off offset:256 nt
	s_waitcnt vmcnt(0)
	v_lshlrev_b32_e32 v64, 16, v48
	v_and_b32_e32 v65, 0xffff0000, v48
	v_lshlrev_b32_e32 v48, 16, v49
	v_and_b32_e32 v49, 0xffff0000, v49
	v_lshlrev_b32_e32 v66, 16, v50
	v_and_b32_e32 v67, 0xffff0000, v50
	v_lshlrev_b32_e32 v50, 16, v51
	v_and_b32_e32 v51, 0xffff0000, v51
	v_lshlrev_b32_e32 v68, 16, v52
	v_and_b32_e32 v69, 0xffff0000, v52
	v_lshlrev_b32_e32 v52, 16, v53
	v_and_b32_e32 v53, 0xffff0000, v53
	v_lshlrev_b32_e32 v70, 16, v54
	v_and_b32_e32 v71, 0xffff0000, v54
	v_lshlrev_b32_e32 v54, 16, v55
	v_and_b32_e32 v55, 0xffff0000, v55
	v_pk_fma_f32 v[46:47], v[46:47], v[48:49], v[52:53]
	v_pk_fma_f32 v[44:45], v[44:45], v[64:65], v[68:69]
	v_pk_fma_f32 v[48:49], v[42:43], v[50:51], v[54:55]
	v_pk_fma_f32 v[42:43], v[40:41], v[66:67], v[70:71]
	v_cvt_pk_bf16_f32 v40, v44, v45
	v_cvt_pk_bf16_f32 v41, v46, v47
	v_cvt_pk_bf16_f32 v42, v42, v43
	v_cvt_pk_bf16_f32 v43, v48, v49
	global_store_dwordx4 v[60:61], v[40:43], off
	global_load_dwordx4 v[40:43], v[62:63], off offset:256 nt
	v_add_u32_e32 v44, 0xa0, v144
	v_ashrrev_i32_e32 v45, 31, v44
	v_lshlrev_b32_e32 v48, 16, v56
	v_and_b32_e32 v49, 0xffff0000, v56
	v_lshlrev_b32_e32 v50, 16, v57
	v_and_b32_e32 v51, 0xffff0000, v57
	v_lshlrev_b32_e32 v52, 16, v58
	v_and_b32_e32 v53, 0xffff0000, v58
	v_lshlrev_b32_e32 v54, 16, v59
	v_and_b32_e32 v55, 0xffff0000, v59
	v_lshlrev_b64 v[44:45], 10, v[44:45]
	v_lshl_add_u64 v[44:45], v[44:45], 0, v[146:147]
	v_lshlrev_b64 v[44:45], 1, v[44:45]
	v_lshl_add_u64 v[46:47], s[16:17], 0, v[44:45]
	v_lshl_add_u64 v[44:45], s[20:21], 0, v[44:45]
	s_waitcnt vmcnt(0)
	v_lshlrev_b32_e32 v56, 16, v40
	v_and_b32_e32 v57, 0xffff0000, v40
	v_lshlrev_b32_e32 v40, 16, v41
	v_and_b32_e32 v41, 0xffff0000, v41
	v_lshlrev_b32_e32 v58, 16, v42
	v_and_b32_e32 v59, 0xffff0000, v42
	v_lshlrev_b32_e32 v42, 16, v43
	v_and_b32_e32 v43, 0xffff0000, v43
	v_pk_fma_f32 v[38:39], v[38:39], v[40:41], v[50:51]
	v_pk_fma_f32 v[36:37], v[36:37], v[56:57], v[48:49]
	v_pk_fma_f32 v[40:41], v[34:35], v[42:43], v[54:55]
	v_pk_fma_f32 v[34:35], v[32:33], v[58:59], v[52:53]
	v_cvt_pk_bf16_f32 v32, v36, v37
	v_cvt_pk_bf16_f32 v33, v38, v39
	v_cvt_pk_bf16_f32 v34, v34, v35
	v_cvt_pk_bf16_f32 v35, v40, v41
	global_store_dwordx4 v[60:61], v[32:35], off offset:256
	global_load_dwordx4 v[32:35], v[46:47], off nt
	global_load_dwordx4 v[36:39], v[44:45], off nt
	global_load_dwordx4 v[40:43], v[44:45], off offset:256 nt
	s_waitcnt vmcnt(0)
; __device__ __forceinline__ unsigned pk2(float lo, float hi) { f32x2_t v = {lo, hi}; bf16x2_t b = __builtin_convertvector(v, bf16x2_t); return __builtin_bit_cast(unsigned, b); }
; #define BF16_LO(w) __uint_as_float((w) << 16)
; #define BF16_HI(w) __uint_as_float((w) & 0xffff0000u)
; #define PG8_BAR __builtin_amdgcn_s_barrier()
;     __device__ __forceinline__ void operator()(const f32x4 (&acc)[2][2][4][2], const Unit& u, int wr, int wc, int fr_in, int fq_in) const {
;     ...
; #pragma unroll
;                 for (int bj = 0; bj < 2; ++bj) {
;                     const size_t off = (size_t)(u.pm * BM + ai * 128 + wr * 64 + m * 16 + fr) * DM + u.pn * BM + bj * HALF + wc * 32 + 8 * fq;
;                     const u32x4 s = *(const u32x4*)(SG + off), q = *(const u32x4*)(hb + off);
;                     const f32x4 s0 = {BF16_LO(s.x), BF16_HI(s.x), BF16_LO(s.y), BF16_HI(s.y)}, s1 = {BF16_LO(s.z), BF16_HI(s.z), BF16_LO(s.w), BF16_HI(s.w)};
;                     const f32x4 b0 = {BF16_LO(q.x), BF16_HI(q.x), BF16_LO(q.y), BF16_HI(q.y)}, b1 = {BF16_LO(q.z), BF16_HI(q.z), BF16_LO(q.w), BF16_HI(q.w)};
;                     const f32x4 h0 = b0 + acc[ai][bj][m][0] * s0, h1 = b1 + acc[ai][bj][m][1] * s1;
;                     if (outf) { *(f32x4*)(outf + off) = h0; *(f32x4*)(outf + off + 4) = h1; }
;                     else { u32x4 w; w.x = pk2(h0[0], h0[1]); w.y = pk2(h0[2], h0[3]); w.z = pk2(h1[0], h1[1]); w.w = pk2(h1[2], h1[3]); *(u32x4*)(hb + off) = w; }
;                     if (bj == 1 && (m & 1)) asm volatile("" ::: "memory");
; template <class Epi, class Sched, bool ALIGN_EPI = false, bool SP2 = false>
; __device__ __forceinline__ void gemm_phase(PG8_LAS unsigned char* lds, const Gemm g, const Sched& S, const Epi& E, const int tid_arg) {
;     ...
;         cur = nxt; cA = nA; cB = nB; ++ui;
;         if constexpr (ALIGN_EPI) { if (wr == 1) PG8_BAR; }
	v_lshlrev_b32_e32 v48, 16, v32
	v_and_b32_e32 v49, 0xffff0000, v32
	v_lshlrev_b32_e32 v32, 16, v33
	v_and_b32_e32 v33, 0xffff0000, v33
	v_lshlrev_b32_e32 v50, 16, v34
	v_and_b32_e32 v51, 0xffff0000, v34
	v_lshlrev_b32_e32 v34, 16, v35
	v_and_b32_e32 v35, 0xffff0000, v35
	v_lshlrev_b32_e32 v52, 16, v36
	v_and_b32_e32 v53, 0xffff0000, v36
	v_lshlrev_b32_e32 v36, 16, v37
	v_and_b32_e32 v37, 0xffff0000, v37
	v_lshlrev_b32_e32 v54, 16, v38
	v_and_b32_e32 v55, 0xffff0000, v38
	v_lshlrev_b32_e32 v38, 16, v39
	v_and_b32_e32 v39, 0xffff0000, v39
	v_pk_fma_f32 v[30:31], v[30:31], v[32:33], v[36:37]
	v_pk_fma_f32 v[28:29], v[28:29], v[48:49], v[52:53]
	v_pk_fma_f32 v[32:33], v[26:27], v[34:35], v[38:39]
	v_pk_fma_f32 v[26:27], v[24:25], v[50:51], v[54:55]
	v_cvt_pk_bf16_f32 v24, v28, v29
	v_cvt_pk_bf16_f32 v25, v30, v31
	v_cvt_pk_bf16_f32 v26, v26, v27
	v_cvt_pk_bf16_f32 v27, v32, v33
	global_store_dwordx4 v[44:45], v[24:27], off
	global_load_dwordx4 v[24:27], v[46:47], off offset:256 nt
	v_add_u32_e32 v28, 0xb0, v144
	v_ashrrev_i32_e32 v29, 31, v28
	v_lshlrev_b64 v[28:29], 10, v[28:29]
	v_lshlrev_b32_e32 v32, 16, v40
	v_and_b32_e32 v33, 0xffff0000, v40
	v_lshlrev_b32_e32 v34, 16, v41
	v_and_b32_e32 v35, 0xffff0000, v41
	v_lshlrev_b32_e32 v36, 16, v42
	v_and_b32_e32 v37, 0xffff0000, v42
	v_lshlrev_b32_e32 v38, 16, v43
	v_and_b32_e32 v39, 0xffff0000, v43
	v_lshl_add_u64 v[28:29], v[28:29], 0, v[146:147]
	v_lshlrev_b64 v[28:29], 1, v[28:29]
	v_lshl_add_u64 v[30:31], s[16:17], 0, v[28:29]
	v_lshl_add_u64 v[28:29], s[20:21], 0, v[28:29]
	s_waitcnt vmcnt(0)
	v_lshlrev_b32_e32 v40, 16, v24
	v_and_b32_e32 v41, 0xffff0000, v24
	v_lshlrev_b32_e32 v24, 16, v25
	v_and_b32_e32 v25, 0xffff0000, v25
	v_lshlrev_b32_e32 v42, 16, v26
	v_and_b32_e32 v43, 0xffff0000, v26
	v_lshlrev_b32_e32 v26, 16, v27
	v_and_b32_e32 v27, 0xffff0000, v27
	v_pk_fma_f32 v[22:23], v[22:23], v[24:25], v[34:35]
	v_pk_fma_f32 v[20:21], v[20:21], v[40:41], v[32:33]
	v_pk_fma_f32 v[24:25], v[18:19], v[26:27], v[38:39]
	v_pk_fma_f32 v[18:19], v[16:17], v[42:43], v[36:37]
	v_cvt_pk_bf16_f32 v16, v20, v21
	v_cvt_pk_bf16_f32 v17, v22, v23
	v_cvt_pk_bf16_f32 v18, v18, v19
	v_cvt_pk_bf16_f32 v19, v24, v25
	global_store_dwordx4 v[44:45], v[16:19], off offset:256
	global_load_dwordx4 v[16:19], v[30:31], off nt
	s_nop 0
	global_load_dwordx4 v[20:23], v[28:29], off nt
	global_load_dwordx4 v[24:27], v[28:29], off offset:256 nt
	s_waitcnt vmcnt(0)
	v_lshlrev_b32_e32 v32, 16, v16
	v_and_b32_e32 v33, 0xffff0000, v16
	v_lshlrev_b32_e32 v16, 16, v17
	v_and_b32_e32 v17, 0xffff0000, v17
	v_lshlrev_b32_e32 v34, 16, v18
	v_and_b32_e32 v35, 0xffff0000, v18
	v_lshlrev_b32_e32 v18, 16, v19
	v_and_b32_e32 v19, 0xffff0000, v19
	v_lshlrev_b32_e32 v36, 16, v20
	v_and_b32_e32 v37, 0xffff0000, v20
	v_lshlrev_b32_e32 v20, 16, v21
	v_and_b32_e32 v21, 0xffff0000, v21
	v_lshlrev_b32_e32 v38, 16, v22
	v_and_b32_e32 v39, 0xffff0000, v22
	v_lshlrev_b32_e32 v22, 16, v23
	v_and_b32_e32 v23, 0xffff0000, v23
	v_pk_fma_f32 v[14:15], v[14:15], v[16:17], v[20:21]
	v_pk_fma_f32 v[12:13], v[12:13], v[32:33], v[36:37]
	v_pk_fma_f32 v[16:17], v[10:11], v[18:19], v[22:23]
	v_pk_fma_f32 v[10:11], v[8:9], v[34:35], v[38:39]
	v_cvt_pk_bf16_f32 v8, v12, v13
	v_cvt_pk_bf16_f32 v9, v14, v15
	v_cvt_pk_bf16_f32 v10, v10, v11
	v_cvt_pk_bf16_f32 v11, v16, v17
	global_store_dwordx4 v[28:29], v[8:11], off
	global_load_dwordx4 v[8:11], v[30:31], off offset:256 nt
	v_lshlrev_b32_e32 v12, 16, v24
	v_and_b32_e32 v13, 0xffff0000, v24
	v_lshlrev_b32_e32 v14, 16, v25
	v_and_b32_e32 v15, 0xffff0000, v25
	v_lshlrev_b32_e32 v16, 16, v26
	v_and_b32_e32 v17, 0xffff0000, v26
	v_lshlrev_b32_e32 v18, 16, v27
	v_and_b32_e32 v19, 0xffff0000, v27
	s_waitcnt vmcnt(0)
	v_lshlrev_b32_e32 v20, 16, v8
	v_and_b32_e32 v21, 0xffff0000, v8
	v_lshlrev_b32_e32 v8, 16, v9
	v_and_b32_e32 v9, 0xffff0000, v9
	v_lshlrev_b32_e32 v22, 16, v10
	v_and_b32_e32 v23, 0xffff0000, v10
	v_lshlrev_b32_e32 v10, 16, v11
	v_and_b32_e32 v11, 0xffff0000, v11
	v_pk_fma_f32 v[6:7], v[6:7], v[8:9], v[14:15]
	v_pk_fma_f32 v[4:5], v[4:5], v[20:21], v[12:13]
	v_pk_fma_f32 v[8:9], v[2:3], v[10:11], v[18:19]
	v_pk_fma_f32 v[2:3], v[0:1], v[22:23], v[16:17]
	v_cvt_pk_bf16_f32 v0, v4, v5
	v_cvt_pk_bf16_f32 v1, v6, v7
	v_cvt_pk_bf16_f32 v2, v2, v3
	v_cvt_pk_bf16_f32 v3, v8, v9
	global_store_dwordx4 v[28:29], v[0:3], off offset:256
	s_cbranch_vccnz .LBB0_1033
	s_andn2_b64 vcc, exec, s[18:19]
	s_cbranch_vccnz .LBB0_1032
	s_barrier
	s_branch .LBB0_1032

; __device__ __forceinline__ unsigned pk2(float lo, float hi) { f32x2_t v = {lo, hi}; bf16x2_t b = __builtin_convertvector(v, bf16x2_t); return __builtin_bit_cast(unsigned, b); }
; __device__ __forceinline__ float xor16_sum(float v) { const auto r = __builtin_amdgcn_permlane16_swap(__float_as_uint(v), __float_as_uint(v), false, false); return __uint_as_float(r[0]) + __uint_as_float(r[1]); }
; __device__ __forceinline__ float xor32_sum(float v) { const auto r = __builtin_amdgcn_permlane32_swap(__float_as_uint(v), __float_as_uint(v), false, false); return __uint_as_float(r[0]) + __uint_as_float(r[1]); }
; #define BF16_LO(w) __uint_as_float((w) << 16)
; #define BF16_HI(w) __uint_as_float((w) & 0xffff0000u)
;     __device__ __forceinline__ void operator()(const f32x4 (&acc)[2][2][4][2], const Unit& u, int wr, int wc, int fr_in, int fq_in) const {
;     ...
; #pragma unroll
;         for (int ai = 0; ai < 2; ++ai)
; #pragma unroll
;             for (int m = 0; m < 4; ++m) {
;                 const int row = u.pm * BM + ai * 128 + wr * 64 + m * 16 + fr;
;                 float s = 0.f;
; #pragma unroll
;                 for (int bj = 0; bj < 2; ++bj) {
;                     const size_t off = (size_t)row * DM + u.pn * BM + bj * HALF + wc * 32 + 8 * fq;
;                     f32x4 b0, b1;
;                     if (xbase) { b0 = *(const f32x4*)(xbase + off); b1 = *(const f32x4*)(xbase + off + 4); }
;                     else { const u32x4 q = *(const u32x4*)(hb + off);
;                         b0 = (f32x4){BF16_LO(q.x), BF16_HI(q.x), BF16_LO(q.y), BF16_HI(q.y)}; b1 = (f32x4){BF16_LO(q.z), BF16_HI(q.z), BF16_LO(q.w), BF16_HI(q.w)}; }
;                     const f32x4 h0 = b0 + acc[ai][bj][m][0], h1 = b1 + acc[ai][bj][m][1];
;                     u32x4 w; w.x = pk2(h0[0], h0[1]); w.y = pk2(h0[2], h0[3]); w.z = pk2(h1[0], h1[1]); w.w = pk2(h1[2], h1[3]);
;                     *(u32x4*)(hb + off) = w;
;                     s += (h0[0] * h0[0] + h0[1] * h0[1]) + (h0[2] * h0[2] + h0[3] * h0[3]) + (h1[0] * h1[0] + h1[1] * h1[1]) + (h1[2] * h1[2] + h1[3] * h1[3]);
;                 }
;                 s = xor32_sum(xor16_sum(s));
;                 if (fq == 0) xch[(ai * 128 + wr * 64 + m * 16 + fr) * 4 + wc] = s;
.LBB0_1462:
	v_mov_b32_e32 v169, v148
	v_mov_b32_e32 v168, v149
	s_lshl_b32 s26, s26, 8
	v_add_u32_e32 v188, s44, v168
	v_add_u32_e32 v144, s26, v188
	s_lshl_b32 s0, s4, 8
	s_ashr_i32 s1, s0, 31
	v_lshlrev_b32_e32 v146, 3, v169
	v_ashrrev_i32_e32 v145, 31, v144
	v_ashrrev_i32_e32 v147, 31, v146
	s_or_b64 s[0:1], s[0:1], s[12:13]
	v_lshlrev_b64 v[170:171], 11, v[144:145]
	v_lshl_add_u64 v[146:147], s[0:1], 0, v[146:147]
	v_lshl_add_u64 v[170:171], s[10:11], 0, v[170:171]
	v_lshl_add_u64 v[178:179], v[146:147], 1, v[170:171]
	global_load_dwordx4 v[170:173], v[178:179], off nt
	global_load_dwordx4 v[174:177], v[178:179], off offset:256 nt
	v_cmp_eq_u32_e32 vcc, 0, v169
	s_waitcnt vmcnt(0)
	v_lshlrev_b32_e32 v180, 16, v170
	v_and_b32_e32 v181, 0xffff0000, v170
	v_lshlrev_b32_e32 v170, 16, v171
	v_and_b32_e32 v171, 0xffff0000, v171
	v_lshlrev_b32_e32 v182, 16, v172
	v_and_b32_e32 v183, 0xffff0000, v172
	v_lshlrev_b32_e32 v172, 16, v173
	v_and_b32_e32 v173, 0xffff0000, v173
	v_lshlrev_b32_e32 v184, 16, v174
	v_and_b32_e32 v185, 0xffff0000, v174
	v_lshlrev_b32_e32 v174, 16, v175
	v_and_b32_e32 v175, 0xffff0000, v175
	v_lshlrev_b32_e32 v186, 16, v176
	v_and_b32_e32 v187, 0xffff0000, v176
	v_lshlrev_b32_e32 v176, 16, v177
	v_and_b32_e32 v177, 0xffff0000, v177
	v_pk_add_f32 v[126:127], v[126:127], v[170:171]
	v_pk_add_f32 v[124:125], v[124:125], v[180:181]
	v_pk_add_f32 v[122:123], v[122:123], v[172:173]
	v_pk_add_f32 v[170:171], v[118:119], v[174:175]
	v_pk_add_f32 v[172:173], v[116:117], v[184:185]
	v_pk_add_f32 v[120:121], v[120:121], v[182:183]
	v_pk_add_f32 v[174:175], v[114:115], v[176:177]
	v_pk_add_f32 v[176:177], v[112:113], v[186:187]
	v_cvt_pk_bf16_f32 v112, v124, v125
	v_cvt_pk_bf16_f32 v113, v126, v127
	v_mul_f32_e32 v125, v125, v125
	v_mul_f32_e32 v127, v127, v127
	v_mul_f32_e32 v145, v173, v173
	v_mul_f32_e32 v169, v171, v171
	v_cvt_pk_bf16_f32 v114, v120, v121
	v_cvt_pk_bf16_f32 v115, v122, v123
	v_mul_f32_e32 v121, v121, v121
	v_cvt_pk_bf16_f32 v117, v170, v171
	v_mul_f32_e32 v171, v177, v177
	v_fmac_f32_e32 v125, v124, v124
	v_fmac_f32_e32 v127, v126, v126
	v_fmac_f32_e32 v145, v172, v172
	v_fmac_f32_e32 v169, v170, v170
	v_mul_f32_e32 v123, v123, v123
	v_cvt_pk_bf16_f32 v116, v172, v173
	v_mul_f32_e32 v173, v175, v175
	global_store_dwordx4 v[178:179], v[112:115], off
	v_fmac_f32_e32 v121, v120, v120
	v_fmac_f32_e32 v171, v176, v176
	v_add_f32_e32 v112, v125, v127
	v_add_f32_e32 v113, v145, v169
	v_fmac_f32_e32 v123, v122, v122
	v_fmac_f32_e32 v173, v174, v174
	v_add_f32_e32 v112, v121, v112
	v_add_f32_e32 v113, v171, v113
	v_add_f32_e32 v112, v123, v112
	v_add_f32_e32 v113, v173, v113
	v_add_f32_e32 v112, v112, v113
	v_mov_b32_e32 v113, v112
	s_nop 1
	v_permlane16_swap_b32_e32 v112, v113
	v_add_f32_e32 v113, v112, v113
	v_mov_b32_e32 v114, v113
	v_cvt_pk_bf16_f32 v118, v176, v177
	v_cvt_pk_bf16_f32 v119, v174, v175
	v_permlane32_swap_b32_e32 v113, v114
	v_lshl_add_u32 v112, v188, 4, s52
	global_store_dwordx4 v[178:179], v[116:119], off offset:256
	s_and_saveexec_b64 s[0:1], vcc
	v_add_f32_e32 v113, v113, v114
	ds_write_b32 v112, v113
	s_or_b64 exec, exec, s[0:1]
	v_add_u32_e32 v114, 16, v144
	v_ashrrev_i32_e32 v115, 31, v114
	v_lshlrev_b64 v[114:115], 11, v[114:115]
	v_lshl_add_u64 v[114:115], s[10:11], 0, v[114:115]
	v_lshl_add_u64 v[122:123], v[146:147], 1, v[114:115]
	global_load_dwordx4 v[114:117], v[122:123], off nt
	global_load_dwordx4 v[118:121], v[122:123], off offset:256 nt
	s_waitcnt vmcnt(1)
	v_lshlrev_b32_e32 v124, 16, v114
	v_and_b32_e32 v125, 0xffff0000, v114
	v_lshlrev_b32_e32 v114, 16, v115
	v_and_b32_e32 v115, 0xffff0000, v115
	v_lshlrev_b32_e32 v126, 16, v116
	v_and_b32_e32 v127, 0xffff0000, v116
	v_lshlrev_b32_e32 v116, 16, v117
	v_and_b32_e32 v117, 0xffff0000, v117
	s_waitcnt vmcnt(0)
	v_lshlrev_b32_e32 v170, 16, v118
	v_and_b32_e32 v171, 0xffff0000, v118
	v_lshlrev_b32_e32 v118, 16, v119
	v_and_b32_e32 v119, 0xffff0000, v119
	v_lshlrev_b32_e32 v172, 16, v120
	v_and_b32_e32 v173, 0xffff0000, v120
	v_lshlrev_b32_e32 v120, 16, v121
	v_and_b32_e32 v121, 0xffff0000, v121
	v_pk_add_f32 v[110:111], v[110:111], v[114:115]
	v_pk_add_f32 v[108:109], v[108:109], v[124:125]
	v_pk_add_f32 v[106:107], v[106:107], v[116:117]
	v_pk_add_f32 v[114:115], v[102:103], v[118:119]
	v_pk_add_f32 v[116:117], v[100:101], v[170:171]
	v_pk_add_f32 v[104:105], v[104:105], v[126:127]
	v_pk_add_f32 v[118:119], v[98:99], v[120:121]
	v_pk_add_f32 v[120:121], v[96:97], v[172:173]
	v_cvt_pk_bf16_f32 v96, v108, v109
	v_cvt_pk_bf16_f32 v97, v110, v111
	v_mul_f32_e32 v109, v109, v109
	v_mul_f32_e32 v111, v111, v111
	v_cvt_pk_bf16_f32 v101, v114, v115
	v_mul_f32_e32 v113, v117, v117
	v_mul_f32_e32 v115, v115, v115
	v_cvt_pk_bf16_f32 v98, v104, v105
	v_cvt_pk_bf16_f32 v99, v106, v107
	v_mul_f32_e32 v105, v105, v105
	v_cvt_pk_bf16_f32 v100, v116, v117
	v_mul_f32_e32 v117, v121, v121
	v_fmac_f32_e32 v109, v108, v108
	v_fmac_f32_e32 v111, v110, v110
	v_fmac_f32_e32 v113, v116, v116
	v_fmac_f32_e32 v115, v114, v114
	v_mul_f32_e32 v107, v107, v107
	v_cvt_pk_bf16_f32 v103, v118, v119
	v_mul_f32_e32 v119, v119, v119
	global_store_dwordx4 v[122:123], v[96:99], off
	v_fmac_f32_e32 v105, v104, v104
	v_fmac_f32_e32 v117, v120, v120
	v_add_f32_e32 v96, v109, v111
	v_add_f32_e32 v97, v113, v115
	v_fmac_f32_e32 v107, v106, v106
	v_fmac_f32_e32 v119, v118, v118
	v_add_f32_e32 v96, v105, v96
	v_add_f32_e32 v97, v117, v97
	v_add_f32_e32 v96, v107, v96
	v_add_f32_e32 v97, v119, v97
	v_add_f32_e32 v96, v96, v97
	v_mov_b32_e32 v97, v96
	s_nop 1
	v_permlane16_swap_b32_e32 v96, v97
	v_add_f32_e32 v96, v96, v97
	v_mov_b32_e32 v97, v96
	v_cvt_pk_bf16_f32 v102, v120, v121
	s_nop 0
	v_permlane32_swap_b32_e32 v96, v97
	global_store_dwordx4 v[122:123], v[100:103], off offset:256
	s_and_saveexec_b64 s[0:1], vcc
	v_add_f32_e32 v96, v96, v97
	ds_write_b32 v112, v96 offset:256
	s_or_b64 exec, exec, s[0:1]
	v_add_u32_e32 v96, 32, v144
	v_ashrrev_i32_e32 v97, 31, v96
	v_lshlrev_b64 v[96:97], 11, v[96:97]
	v_lshl_add_u64 v[96:97], s[10:11], 0, v[96:97]
	v_lshl_add_u64 v[104:105], v[146:147], 1, v[96:97]
	global_load_dwordx4 v[96:99], v[104:105], off nt
	global_load_dwordx4 v[100:103], v[104:105], off offset:256 nt
	s_waitcnt vmcnt(1)
; __device__ __forceinline__ unsigned pk2(float lo, float hi) { f32x2_t v = {lo, hi}; bf16x2_t b = __builtin_convertvector(v, bf16x2_t); return __builtin_bit_cast(unsigned, b); }
; __device__ __forceinline__ float xor16_sum(float v) { const auto r = __builtin_amdgcn_permlane16_swap(__float_as_uint(v), __float_as_uint(v), false, false); return __uint_as_float(r[0]) + __uint_as_float(r[1]); }
; __device__ __forceinline__ float xor32_sum(float v) { const auto r = __builtin_amdgcn_permlane32_swap(__float_as_uint(v), __float_as_uint(v), false, false); return __uint_as_float(r[0]) + __uint_as_float(r[1]); }
; #define BF16_LO(w) __uint_as_float((w) << 16)
; #define BF16_HI(w) __uint_as_float((w) & 0xffff0000u)
;     __device__ __forceinline__ void operator()(const f32x4 (&acc)[2][2][4][2], const Unit& u, int wr, int wc, int fr_in, int fq_in) const {
;     ...
; #pragma unroll
;         for (int ai = 0; ai < 2; ++ai)
; #pragma unroll
;             for (int m = 0; m < 4; ++m) {
;                 const int row = u.pm * BM + ai * 128 + wr * 64 + m * 16 + fr;
;                 float s = 0.f;
; #pragma unroll
;                 for (int bj = 0; bj < 2; ++bj) {
;                     const size_t off = (size_t)row * DM + u.pn * BM + bj * HALF + wc * 32 + 8 * fq;
;                     f32x4 b0, b1;
;                     if (xbase) { b0 = *(const f32x4*)(xbase + off); b1 = *(const f32x4*)(xbase + off + 4); }
;                     else { const u32x4 q = *(const u32x4*)(hb + off);
;                         b0 = (f32x4){BF16_LO(q.x), BF16_HI(q.x), BF16_LO(q.y), BF16_HI(q.y)}; b1 = (f32x4){BF16_LO(q.z), BF16_HI(q.z), BF16_LO(q.w), BF16_HI(q.w)}; }
;                     const f32x4 h0 = b0 + acc[ai][bj][m][0], h1 = b1 + acc[ai][bj][m][1];
;                     u32x4 w; w.x = pk2(h0[0], h0[1]); w.y = pk2(h0[2], h0[3]); w.z = pk2(h1[0], h1[1]); w.w = pk2(h1[2], h1[3]);
;                     *(u32x4*)(hb + off) = w;
;                     s += (h0[0] * h0[0] + h0[1] * h0[1]) + (h0[2] * h0[2] + h0[3] * h0[3]) + (h1[0] * h1[0] + h1[1] * h1[1]) + (h1[2] * h1[2] + h1[3] * h1[3]);
;                 }
;                 s = xor32_sum(xor16_sum(s));
;                 if (fq == 0) xch[(ai * 128 + wr * 64 + m * 16 + fr) * 4 + wc] = s;
	v_lshlrev_b32_e32 v106, 16, v96
	v_and_b32_e32 v107, 0xffff0000, v96
	v_lshlrev_b32_e32 v96, 16, v97
	v_and_b32_e32 v97, 0xffff0000, v97
	v_lshlrev_b32_e32 v108, 16, v98
	v_and_b32_e32 v109, 0xffff0000, v98
	v_lshlrev_b32_e32 v98, 16, v99
	v_and_b32_e32 v99, 0xffff0000, v99
	s_waitcnt vmcnt(0)
	v_lshlrev_b32_e32 v110, 16, v100
	v_and_b32_e32 v111, 0xffff0000, v100
	v_lshlrev_b32_e32 v100, 16, v101
	v_and_b32_e32 v101, 0xffff0000, v101
	v_lshlrev_b32_e32 v114, 16, v102
	v_and_b32_e32 v115, 0xffff0000, v102
	v_lshlrev_b32_e32 v102, 16, v103
	v_and_b32_e32 v103, 0xffff0000, v103
	v_pk_add_f32 v[94:95], v[94:95], v[96:97]
	v_pk_add_f32 v[92:93], v[92:93], v[106:107]
	v_pk_add_f32 v[90:91], v[90:91], v[98:99]
	v_pk_add_f32 v[96:97], v[86:87], v[100:101]
	v_pk_add_f32 v[98:99], v[84:85], v[110:111]
	v_pk_add_f32 v[88:89], v[88:89], v[108:109]
	v_pk_add_f32 v[100:101], v[82:83], v[102:103]
	v_pk_add_f32 v[102:103], v[80:81], v[114:115]
	v_cvt_pk_bf16_f32 v80, v92, v93
	v_cvt_pk_bf16_f32 v81, v94, v95
	v_mul_f32_e32 v93, v93, v93
	v_mul_f32_e32 v95, v95, v95
	v_cvt_pk_bf16_f32 v84, v98, v99
	v_cvt_pk_bf16_f32 v85, v96, v97
	v_mul_f32_e32 v99, v99, v99
	v_mul_f32_e32 v97, v97, v97
	v_cvt_pk_bf16_f32 v82, v88, v89
	v_cvt_pk_bf16_f32 v83, v90, v91
	v_mul_f32_e32 v89, v89, v89
	v_cvt_pk_bf16_f32 v86, v102, v103
	v_mul_f32_e32 v103, v103, v103
	v_fmac_f32_e32 v93, v92, v92
	v_fmac_f32_e32 v95, v94, v94
	v_fmac_f32_e32 v99, v98, v98
	v_fmac_f32_e32 v97, v96, v96
	v_mul_f32_e32 v91, v91, v91
	v_cvt_pk_bf16_f32 v87, v100, v101
	v_mul_f32_e32 v101, v101, v101
	global_store_dwordx4 v[104:105], v[80:83], off
	v_fmac_f32_e32 v89, v88, v88
	v_fmac_f32_e32 v103, v102, v102
	v_add_f32_e32 v80, v93, v95
	v_add_f32_e32 v81, v99, v97
	v_fmac_f32_e32 v91, v90, v90
	v_fmac_f32_e32 v101, v100, v100
	v_add_f32_e32 v80, v89, v80
	v_add_f32_e32 v81, v103, v81
	v_add_f32_e32 v80, v91, v80
	v_add_f32_e32 v81, v101, v81
	v_add_f32_e32 v80, v80, v81
	v_mov_b32_e32 v81, v80
	s_nop 1
	v_permlane16_swap_b32_e32 v80, v81
	v_add_f32_e32 v80, v80, v81
	v_mov_b32_e32 v81, v80
	s_nop 1
	v_permlane32_swap_b32_e32 v80, v81
	global_store_dwordx4 v[104:105], v[84:87], off offset:256
	s_and_saveexec_b64 s[0:1], vcc
	v_add_f32_e32 v80, v80, v81
	ds_write_b32 v112, v80 offset:512
	s_or_b64 exec, exec, s[0:1]
	v_add_u32_e32 v80, 48, v144
	v_ashrrev_i32_e32 v81, 31, v80
	v_lshlrev_b64 v[80:81], 11, v[80:81]
	v_lshl_add_u64 v[80:81], s[10:11], 0, v[80:81]
	v_lshl_add_u64 v[88:89], v[146:147], 1, v[80:81]
	global_load_dwordx4 v[80:83], v[88:89], off nt
	global_load_dwordx4 v[84:87], v[88:89], off offset:256 nt
	s_waitcnt vmcnt(1)
	v_lshlrev_b32_e32 v90, 16, v80
	v_and_b32_e32 v91, 0xffff0000, v80
	v_lshlrev_b32_e32 v80, 16, v81
	v_and_b32_e32 v81, 0xffff0000, v81
	v_lshlrev_b32_e32 v92, 16, v82
	v_and_b32_e32 v93, 0xffff0000, v82
	v_lshlrev_b32_e32 v82, 16, v83
	v_and_b32_e32 v83, 0xffff0000, v83
	s_waitcnt vmcnt(0)
	v_lshlrev_b32_e32 v94, 16, v84
	v_and_b32_e32 v95, 0xffff0000, v84
	v_lshlrev_b32_e32 v84, 16, v85
	v_and_b32_e32 v85, 0xffff0000, v85
	v_lshlrev_b32_e32 v96, 16, v86
	v_and_b32_e32 v97, 0xffff0000, v86
	v_lshlrev_b32_e32 v86, 16, v87
	v_and_b32_e32 v87, 0xffff0000, v87
	v_pk_add_f32 v[78:79], v[78:79], v[80:81]
	v_pk_add_f32 v[76:77], v[76:77], v[90:91]
	v_pk_add_f32 v[74:75], v[74:75], v[82:83]
	v_pk_add_f32 v[80:81], v[70:71], v[84:85]
	v_pk_add_f32 v[82:83], v[68:69], v[94:95]
	v_pk_add_f32 v[72:73], v[72:73], v[92:93]
	v_pk_add_f32 v[84:85], v[66:67], v[86:87]
	v_pk_add_f32 v[86:87], v[64:65], v[96:97]
	v_cvt_pk_bf16_f32 v64, v76, v77
	v_cvt_pk_bf16_f32 v65, v78, v79
	v_mul_f32_e32 v77, v77, v77
	v_mul_f32_e32 v79, v79, v79
	v_cvt_pk_bf16_f32 v68, v82, v83
	v_cvt_pk_bf16_f32 v69, v80, v81
	v_mul_f32_e32 v83, v83, v83
	v_mul_f32_e32 v81, v81, v81
	v_cvt_pk_bf16_f32 v66, v72, v73
	v_cvt_pk_bf16_f32 v67, v74, v75
	v_mul_f32_e32 v73, v73, v73
	v_cvt_pk_bf16_f32 v70, v86, v87
	v_mul_f32_e32 v87, v87, v87
	v_fmac_f32_e32 v77, v76, v76
	v_fmac_f32_e32 v79, v78, v78
	v_fmac_f32_e32 v83, v82, v82
	v_fmac_f32_e32 v81, v80, v80
	v_mul_f32_e32 v75, v75, v75
	v_cvt_pk_bf16_f32 v71, v84, v85
	v_mul_f32_e32 v85, v85, v85
	global_store_dwordx4 v[88:89], v[64:67], off
	v_fmac_f32_e32 v73, v72, v72
	v_fmac_f32_e32 v87, v86, v86
	v_add_f32_e32 v64, v77, v79
	v_add_f32_e32 v65, v83, v81
	v_fmac_f32_e32 v75, v74, v74
	v_fmac_f32_e32 v85, v84, v84
	v_add_f32_e32 v64, v73, v64
	v_add_f32_e32 v65, v87, v65
	v_add_f32_e32 v64, v75, v64
	v_add_f32_e32 v65, v85, v65
	v_add_f32_e32 v64, v64, v65
	v_mov_b32_e32 v65, v64
	s_nop 1
	v_permlane16_swap_b32_e32 v64, v65
	v_add_f32_e32 v64, v64, v65
	v_mov_b32_e32 v65, v64
	s_nop 1
	v_permlane32_swap_b32_e32 v64, v65
	global_store_dwordx4 v[88:89], v[68:71], off offset:256
	s_and_saveexec_b64 s[0:1], vcc
	v_add_f32_e32 v64, v64, v65
	ds_write_b32 v112, v64 offset:768
	s_or_b64 exec, exec, s[0:1]
	v_add_u32_e32 v64, 0x80, v144
	v_ashrrev_i32_e32 v65, 31, v64
	v_lshlrev_b64 v[64:65], 11, v[64:65]
	v_lshl_add_u64 v[64:65], s[10:11], 0, v[64:65]
	v_lshl_add_u64 v[72:73], v[146:147], 1, v[64:65]
	global_load_dwordx4 v[64:67], v[72:73], off nt
	global_load_dwordx4 v[68:71], v[72:73], off offset:256 nt
	s_waitcnt vmcnt(1)
	v_lshlrev_b32_e32 v74, 16, v64
	v_and_b32_e32 v75, 0xffff0000, v64
	v_lshlrev_b32_e32 v64, 16, v65
	v_and_b32_e32 v65, 0xffff0000, v65
	v_lshlrev_b32_e32 v76, 16, v66
	v_and_b32_e32 v77, 0xffff0000, v66
	v_lshlrev_b32_e32 v66, 16, v67
	v_and_b32_e32 v67, 0xffff0000, v67
	s_waitcnt vmcnt(0)
; __device__ __forceinline__ unsigned pk2(float lo, float hi) { f32x2_t v = {lo, hi}; bf16x2_t b = __builtin_convertvector(v, bf16x2_t); return __builtin_bit_cast(unsigned, b); }
; __device__ __forceinline__ float xor16_sum(float v) { const auto r = __builtin_amdgcn_permlane16_swap(__float_as_uint(v), __float_as_uint(v), false, false); return __uint_as_float(r[0]) + __uint_as_float(r[1]); }
; __device__ __forceinline__ float xor32_sum(float v) { const auto r = __builtin_amdgcn_permlane32_swap(__float_as_uint(v), __float_as_uint(v), false, false); return __uint_as_float(r[0]) + __uint_as_float(r[1]); }
; #define BF16_LO(w) __uint_as_float((w) << 16)
; #define BF16_HI(w) __uint_as_float((w) & 0xffff0000u)
;     __device__ __forceinline__ void operator()(const f32x4 (&acc)[2][2][4][2], const Unit& u, int wr, int wc, int fr_in, int fq_in) const {
;     ...
; #pragma unroll
;         for (int ai = 0; ai < 2; ++ai)
; #pragma unroll
;             for (int m = 0; m < 4; ++m) {
;                 const int row = u.pm * BM + ai * 128 + wr * 64 + m * 16 + fr;
;                 float s = 0.f;
; #pragma unroll
;                 for (int bj = 0; bj < 2; ++bj) {
;                     const size_t off = (size_t)row * DM + u.pn * BM + bj * HALF + wc * 32 + 8 * fq;
;                     f32x4 b0, b1;
;                     if (xbase) { b0 = *(const f32x4*)(xbase + off); b1 = *(const f32x4*)(xbase + off + 4); }
;                     else { const u32x4 q = *(const u32x4*)(hb + off);
;                         b0 = (f32x4){BF16_LO(q.x), BF16_HI(q.x), BF16_LO(q.y), BF16_HI(q.y)}; b1 = (f32x4){BF16_LO(q.z), BF16_HI(q.z), BF16_LO(q.w), BF16_HI(q.w)}; }
;                     const f32x4 h0 = b0 + acc[ai][bj][m][0], h1 = b1 + acc[ai][bj][m][1];
;                     u32x4 w; w.x = pk2(h0[0], h0[1]); w.y = pk2(h0[2], h0[3]); w.z = pk2(h1[0], h1[1]); w.w = pk2(h1[2], h1[3]);
;                     *(u32x4*)(hb + off) = w;
;                     s += (h0[0] * h0[0] + h0[1] * h0[1]) + (h0[2] * h0[2] + h0[3] * h0[3]) + (h1[0] * h1[0] + h1[1] * h1[1]) + (h1[2] * h1[2] + h1[3] * h1[3]);
;                 }
;                 s = xor32_sum(xor16_sum(s));
;                 if (fq == 0) xch[(ai * 128 + wr * 64 + m * 16 + fr) * 4 + wc] = s;
	v_lshlrev_b32_e32 v78, 16, v68
	v_and_b32_e32 v79, 0xffff0000, v68
	v_lshlrev_b32_e32 v68, 16, v69
	v_and_b32_e32 v69, 0xffff0000, v69
	v_lshlrev_b32_e32 v80, 16, v70
	v_and_b32_e32 v81, 0xffff0000, v70
	v_lshlrev_b32_e32 v70, 16, v71
	v_and_b32_e32 v71, 0xffff0000, v71
	v_pk_add_f32 v[62:63], v[62:63], v[64:65]
	v_pk_add_f32 v[60:61], v[60:61], v[74:75]
	v_pk_add_f32 v[58:59], v[58:59], v[66:67]
	v_pk_add_f32 v[64:65], v[54:55], v[68:69]
	v_pk_add_f32 v[66:67], v[52:53], v[78:79]
	v_pk_add_f32 v[56:57], v[56:57], v[76:77]
	v_pk_add_f32 v[68:69], v[50:51], v[70:71]
	v_pk_add_f32 v[70:71], v[48:49], v[80:81]
	v_cvt_pk_bf16_f32 v48, v60, v61
	v_cvt_pk_bf16_f32 v49, v62, v63
	v_mul_f32_e32 v61, v61, v61
	v_mul_f32_e32 v63, v63, v63
	v_cvt_pk_bf16_f32 v52, v66, v67
	v_cvt_pk_bf16_f32 v53, v64, v65
	v_mul_f32_e32 v67, v67, v67
	v_mul_f32_e32 v65, v65, v65
	v_cvt_pk_bf16_f32 v50, v56, v57
	v_cvt_pk_bf16_f32 v51, v58, v59
	v_mul_f32_e32 v57, v57, v57
	v_cvt_pk_bf16_f32 v54, v70, v71
	v_mul_f32_e32 v71, v71, v71
	v_fmac_f32_e32 v61, v60, v60
	v_fmac_f32_e32 v63, v62, v62
	v_fmac_f32_e32 v67, v66, v66
	v_fmac_f32_e32 v65, v64, v64
	v_mul_f32_e32 v59, v59, v59
	v_cvt_pk_bf16_f32 v55, v68, v69
	v_mul_f32_e32 v69, v69, v69
	global_store_dwordx4 v[72:73], v[48:51], off
	v_fmac_f32_e32 v57, v56, v56
	v_fmac_f32_e32 v71, v70, v70
	v_add_f32_e32 v48, v61, v63
	v_add_f32_e32 v49, v67, v65
	v_fmac_f32_e32 v59, v58, v58
	v_fmac_f32_e32 v69, v68, v68
	v_add_f32_e32 v48, v57, v48
	v_add_f32_e32 v49, v71, v49
	v_add_f32_e32 v48, v59, v48
	v_add_f32_e32 v49, v69, v49
	v_add_f32_e32 v48, v48, v49
	v_mov_b32_e32 v49, v48
	s_nop 1
	v_permlane16_swap_b32_e32 v48, v49
	v_add_f32_e32 v48, v48, v49
	v_mov_b32_e32 v49, v48
	s_nop 1
	v_permlane32_swap_b32_e32 v48, v49
	global_store_dwordx4 v[72:73], v[52:55], off offset:256
	s_and_saveexec_b64 s[0:1], vcc
	v_add_f32_e32 v48, v48, v49
	ds_write_b32 v112, v48 offset:2048
	s_or_b64 exec, exec, s[0:1]
	v_add_u32_e32 v48, 0x90, v144
	v_ashrrev_i32_e32 v49, 31, v48
	v_lshlrev_b64 v[48:49], 11, v[48:49]
	v_lshl_add_u64 v[48:49], s[10:11], 0, v[48:49]
	v_lshl_add_u64 v[56:57], v[146:147], 1, v[48:49]
	global_load_dwordx4 v[48:51], v[56:57], off nt
	global_load_dwordx4 v[52:55], v[56:57], off offset:256 nt
	s_waitcnt vmcnt(1)
	v_lshlrev_b32_e32 v58, 16, v48
	v_and_b32_e32 v59, 0xffff0000, v48
	v_lshlrev_b32_e32 v48, 16, v49
	v_and_b32_e32 v49, 0xffff0000, v49
	v_lshlrev_b32_e32 v60, 16, v50
	v_and_b32_e32 v61, 0xffff0000, v50
	v_lshlrev_b32_e32 v50, 16, v51
	v_and_b32_e32 v51, 0xffff0000, v51
	s_waitcnt vmcnt(0)
	v_lshlrev_b32_e32 v62, 16, v52
	v_and_b32_e32 v63, 0xffff0000, v52
	v_lshlrev_b32_e32 v52, 16, v53
	v_and_b32_e32 v53, 0xffff0000, v53
	v_lshlrev_b32_e32 v64, 16, v54
	v_and_b32_e32 v65, 0xffff0000, v54
	v_lshlrev_b32_e32 v54, 16, v55
	v_and_b32_e32 v55, 0xffff0000, v55
	v_pk_add_f32 v[46:47], v[46:47], v[48:49]
	v_pk_add_f32 v[44:45], v[44:45], v[58:59]
	v_pk_add_f32 v[42:43], v[42:43], v[50:51]
	v_pk_add_f32 v[48:49], v[38:39], v[52:53]
	v_pk_add_f32 v[50:51], v[36:37], v[62:63]
	v_pk_add_f32 v[40:41], v[40:41], v[60:61]
	v_pk_add_f32 v[52:53], v[34:35], v[54:55]
	v_pk_add_f32 v[54:55], v[32:33], v[64:65]
	v_cvt_pk_bf16_f32 v32, v44, v45
	v_cvt_pk_bf16_f32 v33, v46, v47
	v_mul_f32_e32 v45, v45, v45
	v_mul_f32_e32 v47, v47, v47
	v_cvt_pk_bf16_f32 v36, v50, v51
	v_cvt_pk_bf16_f32 v37, v48, v49
	v_mul_f32_e32 v51, v51, v51
	v_mul_f32_e32 v49, v49, v49
	v_cvt_pk_bf16_f32 v34, v40, v41
	v_cvt_pk_bf16_f32 v35, v42, v43
	v_mul_f32_e32 v41, v41, v41
	v_cvt_pk_bf16_f32 v38, v54, v55
	v_mul_f32_e32 v55, v55, v55
	v_fmac_f32_e32 v45, v44, v44
	v_fmac_f32_e32 v47, v46, v46
	v_fmac_f32_e32 v51, v50, v50
	v_fmac_f32_e32 v49, v48, v48
	v_mul_f32_e32 v43, v43, v43
	v_cvt_pk_bf16_f32 v39, v52, v53
	v_mul_f32_e32 v53, v53, v53
	global_store_dwordx4 v[56:57], v[32:35], off
	v_fmac_f32_e32 v41, v40, v40
	v_fmac_f32_e32 v55, v54, v54
	v_add_f32_e32 v32, v45, v47
	v_add_f32_e32 v33, v51, v49
	v_fmac_f32_e32 v43, v42, v42
	v_fmac_f32_e32 v53, v52, v52
	v_add_f32_e32 v32, v41, v32
	v_add_f32_e32 v33, v55, v33
	v_add_f32_e32 v32, v43, v32
	v_add_f32_e32 v33, v53, v33
	v_add_f32_e32 v32, v32, v33
	v_mov_b32_e32 v33, v32
	s_nop 1
	v_permlane16_swap_b32_e32 v32, v33
	v_add_f32_e32 v32, v32, v33
	v_mov_b32_e32 v33, v32
	s_nop 1
	v_permlane32_swap_b32_e32 v32, v33
	global_store_dwordx4 v[56:57], v[36:39], off offset:256
	s_and_saveexec_b64 s[0:1], vcc
	v_add_f32_e32 v32, v32, v33
	ds_write_b32 v112, v32 offset:2304
	s_or_b64 exec, exec, s[0:1]
	v_add_u32_e32 v32, 0xa0, v144
	v_ashrrev_i32_e32 v33, 31, v32
	v_lshlrev_b64 v[32:33], 11, v[32:33]
	v_lshl_add_u64 v[32:33], s[10:11], 0, v[32:33]
	v_lshl_add_u64 v[40:41], v[146:147], 1, v[32:33]
	global_load_dwordx4 v[32:35], v[40:41], off nt
	global_load_dwordx4 v[36:39], v[40:41], off offset:256 nt
	s_waitcnt vmcnt(1)
	v_lshlrev_b32_e32 v42, 16, v32
	v_and_b32_e32 v43, 0xffff0000, v32
	v_lshlrev_b32_e32 v32, 16, v33
	v_and_b32_e32 v33, 0xffff0000, v33
	v_lshlrev_b32_e32 v44, 16, v34
	v_and_b32_e32 v45, 0xffff0000, v34
	v_lshlrev_b32_e32 v34, 16, v35
	v_and_b32_e32 v35, 0xffff0000, v35
	s_waitcnt vmcnt(0)
; __device__ __forceinline__ unsigned pk2(float lo, float hi) { f32x2_t v = {lo, hi}; bf16x2_t b = __builtin_convertvector(v, bf16x2_t); return __builtin_bit_cast(unsigned, b); }
; __device__ __forceinline__ float xor16_sum(float v) { const auto r = __builtin_amdgcn_permlane16_swap(__float_as_uint(v), __float_as_uint(v), false, false); return __uint_as_float(r[0]) + __uint_as_float(r[1]); }
;     __device__ __forceinline__ void operator()(const f32x4 (&acc)[2][2][4][2], const Unit& u, int wr, int wc, int fr_in, int fq_in) const {
;     ...
; #pragma unroll
;         for (int ai = 0; ai < 2; ++ai)
; #pragma unroll
;             for (int m = 0; m < 4; ++m) {
;                 const int row = u.pm * BM + ai * 128 + wr * 64 + m * 16 + fr;
;                 float s = 0.f;
; #pragma unroll
;                 for (int bj = 0; bj < 2; ++bj) {
;                     const size_t off = (size_t)row * DM + u.pn * BM + bj * HALF + wc * 32 + 8 * fq;
;                     f32x4 b0, b1;
;                     if (xbase) { b0 = *(const f32x4*)(xbase + off); b1 = *(const f32x4*)(xbase + off + 4); }
;                     else { const u32x4 q = *(const u32x4*)(hb + off);
;                         b0 = (f32x4){BF16_LO(q.x), BF16_HI(q.x), BF16_LO(q.y), BF16_HI(q.y)}; b1 = (f32x4){BF16_LO(q.z), BF16_HI(q.z), BF16_LO(q.w), BF16_HI(q.w)}; }
;                     const f32x4 h0 = b0 + acc[ai][bj][m][0], h1 = b1 + acc[ai][bj][m][1];
;                     u32x4 w; w.x = pk2(h0[0], h0[1]); w.y = pk2(h0[2], h0[3]); w.z = pk2(h1[0], h1[1]); w.w = pk2(h1[2], h1[3]);
;                     *(u32x4*)(hb + off) = w;
;                     s += (h0[0] * h0[0] + h0[1] * h0[1]) + (h0[2] * h0[2] + h0[3] * h0[3]) + (h1[0] * h1[0] + h1[1] * h1[1]) + (h1[2] * h1[2] + h1[3] * h1[3]);
;                 }
;                 s = xor32_sum(xor16_sum(s));
;                 if (fq == 0) xch[(ai * 128 + wr * 64 + m * 16 + fr) * 4 + wc] = s;
;                 if (m == 3) asm volatile("" ::: "memory");
;             }
;         PG8_EPI_BAR();
;         if (fq == 0) {
; #pragma unroll
;             for (int ai = 0; ai < 2; ++ai) {
;                 const int rl = ai * 128 + wr * 64 + wc * 16 + fr;
;                 const f32x4 p = *(const PG8_LAS f32x4*)(xch + rl * 4);
;                 const float t = (p[0] + p[1]) + (p[2] + p[3]);
;                 atomicAdd(rsq + u.pm * BM + rl, (u64_t)(t * 16777216.0f));
	v_lshlrev_b32_e32 v46, 16, v36
	v_and_b32_e32 v47, 0xffff0000, v36
	v_lshlrev_b32_e32 v36, 16, v37
	v_and_b32_e32 v37, 0xffff0000, v37
	v_lshlrev_b32_e32 v48, 16, v38
	v_and_b32_e32 v49, 0xffff0000, v38
	v_lshlrev_b32_e32 v38, 16, v39
	v_and_b32_e32 v39, 0xffff0000, v39
	v_pk_add_f32 v[30:31], v[30:31], v[32:33]
	v_pk_add_f32 v[28:29], v[28:29], v[42:43]
	v_pk_add_f32 v[26:27], v[26:27], v[34:35]
	v_pk_add_f32 v[32:33], v[22:23], v[36:37]
	v_pk_add_f32 v[34:35], v[20:21], v[46:47]
	v_pk_add_f32 v[24:25], v[24:25], v[44:45]
	v_pk_add_f32 v[36:37], v[18:19], v[38:39]
	v_pk_add_f32 v[38:39], v[16:17], v[48:49]
	v_cvt_pk_bf16_f32 v16, v28, v29
	v_cvt_pk_bf16_f32 v17, v30, v31
	v_mul_f32_e32 v29, v29, v29
	v_mul_f32_e32 v31, v31, v31
	v_cvt_pk_bf16_f32 v20, v34, v35
	v_cvt_pk_bf16_f32 v21, v32, v33
	v_mul_f32_e32 v35, v35, v35
	v_mul_f32_e32 v33, v33, v33
	v_cvt_pk_bf16_f32 v18, v24, v25
	v_cvt_pk_bf16_f32 v19, v26, v27
	v_mul_f32_e32 v25, v25, v25
	v_cvt_pk_bf16_f32 v22, v38, v39
	v_mul_f32_e32 v39, v39, v39
	v_fmac_f32_e32 v29, v28, v28
	v_fmac_f32_e32 v31, v30, v30
	v_fmac_f32_e32 v35, v34, v34
	v_fmac_f32_e32 v33, v32, v32
	v_mul_f32_e32 v27, v27, v27
	v_cvt_pk_bf16_f32 v23, v36, v37
	v_mul_f32_e32 v37, v37, v37
	global_store_dwordx4 v[40:41], v[16:19], off
	v_fmac_f32_e32 v25, v24, v24
	v_fmac_f32_e32 v39, v38, v38
	v_add_f32_e32 v16, v29, v31
	v_add_f32_e32 v17, v35, v33
	v_fmac_f32_e32 v27, v26, v26
	v_fmac_f32_e32 v37, v36, v36
	v_add_f32_e32 v16, v25, v16
	v_add_f32_e32 v17, v39, v17
	v_add_f32_e32 v16, v27, v16
	v_add_f32_e32 v17, v37, v17
	v_add_f32_e32 v16, v16, v17
	v_mov_b32_e32 v17, v16
	s_nop 1
	v_permlane16_swap_b32_e32 v16, v17
	v_add_f32_e32 v16, v16, v17
	v_mov_b32_e32 v17, v16
	s_nop 1
	v_permlane32_swap_b32_e32 v16, v17
	global_store_dwordx4 v[40:41], v[20:23], off offset:256
	s_and_saveexec_b64 s[0:1], vcc
	v_add_f32_e32 v16, v16, v17
	ds_write_b32 v112, v16 offset:2560
	s_or_b64 exec, exec, s[0:1]
	v_add_u32_e32 v16, 0xb0, v144
	v_ashrrev_i32_e32 v17, 31, v16
	v_lshlrev_b64 v[16:17], 11, v[16:17]
	v_lshl_add_u64 v[16:17], s[10:11], 0, v[16:17]
	v_lshl_add_u64 v[24:25], v[146:147], 1, v[16:17]
	global_load_dwordx4 v[16:19], v[24:25], off nt
	global_load_dwordx4 v[20:23], v[24:25], off offset:256 nt
	s_waitcnt vmcnt(1)
	v_lshlrev_b32_e32 v26, 16, v16
	v_and_b32_e32 v27, 0xffff0000, v16
	v_lshlrev_b32_e32 v16, 16, v17
	v_and_b32_e32 v17, 0xffff0000, v17
	v_lshlrev_b32_e32 v28, 16, v18
	v_and_b32_e32 v29, 0xffff0000, v18
	v_lshlrev_b32_e32 v18, 16, v19
	v_and_b32_e32 v19, 0xffff0000, v19
	s_waitcnt vmcnt(0)
	v_lshlrev_b32_e32 v30, 16, v20
	v_and_b32_e32 v31, 0xffff0000, v20
	v_lshlrev_b32_e32 v20, 16, v21
	v_and_b32_e32 v21, 0xffff0000, v21
	v_lshlrev_b32_e32 v32, 16, v22
	v_and_b32_e32 v33, 0xffff0000, v22
	v_lshlrev_b32_e32 v22, 16, v23
	v_and_b32_e32 v23, 0xffff0000, v23
	v_pk_add_f32 v[14:15], v[14:15], v[16:17]
	v_pk_add_f32 v[12:13], v[12:13], v[26:27]
	v_pk_add_f32 v[10:11], v[10:11], v[18:19]
	v_pk_add_f32 v[16:17], v[6:7], v[20:21]
	v_pk_add_f32 v[18:19], v[4:5], v[30:31]
	v_pk_add_f32 v[8:9], v[8:9], v[28:29]
	v_pk_add_f32 v[20:21], v[2:3], v[22:23]
	v_pk_add_f32 v[22:23], v[0:1], v[32:33]
	v_cvt_pk_bf16_f32 v0, v12, v13
	v_cvt_pk_bf16_f32 v1, v14, v15
	v_mul_f32_e32 v13, v13, v13
	v_mul_f32_e32 v15, v15, v15
	v_cvt_pk_bf16_f32 v4, v18, v19
	v_cvt_pk_bf16_f32 v5, v16, v17
	v_mul_f32_e32 v19, v19, v19
	v_mul_f32_e32 v17, v17, v17
	v_cvt_pk_bf16_f32 v2, v8, v9
	v_cvt_pk_bf16_f32 v3, v10, v11
	v_mul_f32_e32 v9, v9, v9
	v_cvt_pk_bf16_f32 v6, v22, v23
	v_mul_f32_e32 v23, v23, v23
	v_fmac_f32_e32 v13, v12, v12
	v_fmac_f32_e32 v15, v14, v14
	v_fmac_f32_e32 v19, v18, v18
	v_fmac_f32_e32 v17, v16, v16
	v_mul_f32_e32 v11, v11, v11
	v_cvt_pk_bf16_f32 v7, v20, v21
	v_mul_f32_e32 v21, v21, v21
	global_store_dwordx4 v[24:25], v[0:3], off
	v_fmac_f32_e32 v9, v8, v8
	v_fmac_f32_e32 v23, v22, v22
	v_add_f32_e32 v0, v13, v15
	v_add_f32_e32 v1, v19, v17
	v_fmac_f32_e32 v11, v10, v10
	v_fmac_f32_e32 v21, v20, v20
	v_add_f32_e32 v0, v9, v0
	v_add_f32_e32 v1, v23, v1
	v_add_f32_e32 v0, v11, v0
	v_add_f32_e32 v1, v21, v1
	v_add_f32_e32 v0, v0, v1
	v_mov_b32_e32 v1, v0
	s_nop 1
	v_permlane16_swap_b32_e32 v0, v1
	v_add_f32_e32 v0, v0, v1
	v_mov_b32_e32 v1, v0
	s_nop 1
	v_permlane32_swap_b32_e32 v0, v1
	global_store_dwordx4 v[24:25], v[4:7], off offset:256
	s_and_saveexec_b64 s[0:1], vcc
	v_add_f32_e32 v0, v0, v1
	ds_write_b32 v112, v0 offset:2816
	s_or_b64 exec, exec, s[0:1]
	s_waitcnt lgkmcnt(0)
	s_barrier
	s_and_saveexec_b64 s[0:1], vcc
	s_cbranch_execz .LBB0_1480
	v_add_u32_e32 v4, s51, v168
	v_lshl_add_u32 v6, v4, 4, v167
	ds_read_b128 v[0:3], v6
	s_ashr_i32 s27, s26, 31
	s_lshl_b64 s[26:27], s[26:27], 3
	s_add_u32 s26, s42, s26
	s_addc_u32 s27, s43, s27
	s_waitcnt lgkmcnt(0)
	v_add_f32_e32 v0, v0, v1
	v_add_f32_e32 v1, v2, v3
	v_add_f32_e32 v0, v0, v1
	v_mul_f32_e32 v0, 0x4b800000, v0
	v_trunc_f32_e32 v0, v0
	v_mul_f32_e32 v1, 0x2f800000, v0
	v_floor_f32_e32 v1, v1
	v_fmac_f32_e32 v0, 0xcf800000, v1
	v_cvt_u32_f32_e32 v0, v0
	v_cvt_u32_f32_e32 v1, v1
	v_ashrrev_i32_e32 v5, 31, v4
	v_lshl_add_u64 v[4:5], v[4:5], 3, s[26:27]
	global_atomic_add_x2 v[4:5], v[0:1], off
	ds_read_b128 v[0:3], v6 offset:2048
	s_waitcnt lgkmcnt(0)
	v_add_f32_e32 v0, v0, v1
	v_add_f32_e32 v1, v2, v3
	v_add_f32_e32 v0, v0, v1
	v_mul_f32_e32 v0, 0x4b800000, v0
	v_trunc_f32_e32 v0, v0
	v_mul_f32_e32 v1, 0x2f800000, v0
	v_floor_f32_e32 v1, v1
	v_fmac_f32_e32 v0, 0xcf800000, v1
	v_cvt_u32_f32_e32 v0, v0
	v_cvt_u32_f32_e32 v1, v1
	global_atomic_add_x2 v[4:5], v[0:1], off offset:1024

; __device__ __forceinline__ unsigned pk2(float lo, float hi) { f32x2_t v = {lo, hi}; bf16x2_t b = __builtin_convertvector(v, bf16x2_t); return __builtin_bit_cast(unsigned, b); }
; __device__ __forceinline__ float xor16_sum(float v) { const auto r = __builtin_amdgcn_permlane16_swap(__float_as_uint(v), __float_as_uint(v), false, false); return __uint_as_float(r[0]) + __uint_as_float(r[1]); }
; __device__ __forceinline__ float xor32_sum(float v) { const auto r = __builtin_amdgcn_permlane32_swap(__float_as_uint(v), __float_as_uint(v), false, false); return __uint_as_float(r[0]) + __uint_as_float(r[1]); }
; #define BF16_LO(w) __uint_as_float((w) << 16)
; #define BF16_HI(w) __uint_as_float((w) & 0xffff0000u)
;     __device__ __forceinline__ void operator()(const f32x4 (&acc)[2][2][4][2], const Unit& u, int wr, int wc, int fr_in, int fq_in) const {
;     ...
; #pragma unroll
;         for (int ai = 0; ai < 2; ++ai)
; #pragma unroll
;             for (int m = 0; m < 4; ++m) {
;                 const int row = u.pm * BM + ai * 128 + wr * 64 + m * 16 + fr;
;                 float s = 0.f;
; #pragma unroll
;                 for (int bj = 0; bj < 2; ++bj) {
;                     const size_t off = (size_t)row * DM + u.pn * BM + bj * HALF + wc * 32 + 8 * fq;
;                     f32x4 b0, b1;
;                     if (xbase) { b0 = *(const f32x4*)(xbase + off); b1 = *(const f32x4*)(xbase + off + 4); }
;                     else { const u32x4 q = *(const u32x4*)(hb + off);
;                         b0 = (f32x4){BF16_LO(q.x), BF16_HI(q.x), BF16_LO(q.y), BF16_HI(q.y)}; b1 = (f32x4){BF16_LO(q.z), BF16_HI(q.z), BF16_LO(q.w), BF16_HI(q.w)}; }
;                     const f32x4 h0 = b0 + acc[ai][bj][m][0], h1 = b1 + acc[ai][bj][m][1];
;                     u32x4 w; w.x = pk2(h0[0], h0[1]); w.y = pk2(h0[2], h0[3]); w.z = pk2(h1[0], h1[1]); w.w = pk2(h1[2], h1[3]);
;                     *(u32x4*)(hb + off) = w;
;                     s += (h0[0] * h0[0] + h0[1] * h0[1]) + (h0[2] * h0[2] + h0[3] * h0[3]) + (h1[0] * h1[0] + h1[1] * h1[1]) + (h1[2] * h1[2] + h1[3] * h1[3]);
;                 }
;                 s = xor32_sum(xor16_sum(s));
;                 if (fq == 0) xch[(ai * 128 + wr * 64 + m * 16 + fr) * 4 + wc] = s;
.LBB0_1736:
	v_mov_b32_e32 v169, v148
	v_mov_b32_e32 v168, v149
	s_lshl_b32 s4, s54, 8
	v_add_u32_e32 v188, s39, v168
	v_add_u32_e32 v144, s4, v188
	s_lshl_b32 s0, s53, 8
	s_ashr_i32 s1, s0, 31
	v_lshlrev_b32_e32 v146, 3, v169
	v_ashrrev_i32_e32 v145, 31, v144
	v_ashrrev_i32_e32 v147, 31, v146
	s_or_b64 s[0:1], s[0:1], s[14:15]
	v_lshlrev_b64 v[170:171], 11, v[144:145]
	v_lshl_add_u64 v[146:147], s[0:1], 0, v[146:147]
	v_lshl_add_u64 v[170:171], s[12:13], 0, v[170:171]
	v_lshl_add_u64 v[178:179], v[146:147], 1, v[170:171]
	global_load_dwordx4 v[170:173], v[178:179], off nt
	global_load_dwordx4 v[174:177], v[178:179], off offset:256 nt
	v_cmp_eq_u32_e32 vcc, 0, v169
	s_waitcnt vmcnt(0)
	v_lshlrev_b32_e32 v180, 16, v170
	v_and_b32_e32 v181, 0xffff0000, v170
	v_lshlrev_b32_e32 v170, 16, v171
	v_and_b32_e32 v171, 0xffff0000, v171
	v_lshlrev_b32_e32 v182, 16, v172
	v_and_b32_e32 v183, 0xffff0000, v172
	v_lshlrev_b32_e32 v172, 16, v173
	v_and_b32_e32 v173, 0xffff0000, v173
	v_lshlrev_b32_e32 v184, 16, v174
	v_and_b32_e32 v185, 0xffff0000, v174
	v_lshlrev_b32_e32 v174, 16, v175
	v_and_b32_e32 v175, 0xffff0000, v175
	v_lshlrev_b32_e32 v186, 16, v176
	v_and_b32_e32 v187, 0xffff0000, v176
	v_lshlrev_b32_e32 v176, 16, v177
	v_and_b32_e32 v177, 0xffff0000, v177
	v_pk_add_f32 v[126:127], v[126:127], v[170:171]
	v_pk_add_f32 v[124:125], v[124:125], v[180:181]
	v_pk_add_f32 v[122:123], v[122:123], v[172:173]
	v_pk_add_f32 v[170:171], v[118:119], v[174:175]
	v_pk_add_f32 v[172:173], v[116:117], v[184:185]
	v_pk_add_f32 v[120:121], v[120:121], v[182:183]
	v_pk_add_f32 v[174:175], v[114:115], v[176:177]
	v_pk_add_f32 v[176:177], v[112:113], v[186:187]
	v_cvt_pk_bf16_f32 v112, v124, v125
	v_cvt_pk_bf16_f32 v113, v126, v127
	v_mul_f32_e32 v125, v125, v125
	v_mul_f32_e32 v127, v127, v127
	v_mul_f32_e32 v145, v173, v173
	v_mul_f32_e32 v169, v171, v171
	v_cvt_pk_bf16_f32 v114, v120, v121
	v_cvt_pk_bf16_f32 v115, v122, v123
	v_mul_f32_e32 v121, v121, v121
	v_cvt_pk_bf16_f32 v117, v170, v171
	v_mul_f32_e32 v171, v177, v177
	v_fmac_f32_e32 v125, v124, v124
	v_fmac_f32_e32 v127, v126, v126
	v_fmac_f32_e32 v145, v172, v172
	v_fmac_f32_e32 v169, v170, v170
	v_mul_f32_e32 v123, v123, v123
	v_cvt_pk_bf16_f32 v116, v172, v173
	v_mul_f32_e32 v173, v175, v175
	global_store_dwordx4 v[178:179], v[112:115], off
	v_fmac_f32_e32 v121, v120, v120
	v_fmac_f32_e32 v171, v176, v176
	v_add_f32_e32 v112, v125, v127
	v_add_f32_e32 v113, v145, v169
	v_fmac_f32_e32 v123, v122, v122
	v_fmac_f32_e32 v173, v174, v174
	v_add_f32_e32 v112, v121, v112
	v_add_f32_e32 v113, v171, v113
	v_add_f32_e32 v112, v123, v112
	v_add_f32_e32 v113, v173, v113
	v_add_f32_e32 v112, v112, v113
	v_mov_b32_e32 v113, v112
	s_nop 1
	v_permlane16_swap_b32_e32 v112, v113
	v_add_f32_e32 v113, v112, v113
	v_mov_b32_e32 v114, v113
	v_cvt_pk_bf16_f32 v118, v176, v177
	v_cvt_pk_bf16_f32 v119, v174, v175
	v_permlane32_swap_b32_e32 v113, v114
	v_lshl_add_u32 v112, v188, 4, s47
	global_store_dwordx4 v[178:179], v[116:119], off offset:256
	s_and_saveexec_b64 s[0:1], vcc
	v_add_f32_e32 v113, v113, v114
	ds_write_b32 v112, v113
	s_or_b64 exec, exec, s[0:1]
	v_add_u32_e32 v114, 16, v144
	v_ashrrev_i32_e32 v115, 31, v114
	v_lshlrev_b64 v[114:115], 11, v[114:115]
	v_lshl_add_u64 v[114:115], s[12:13], 0, v[114:115]
	v_lshl_add_u64 v[122:123], v[146:147], 1, v[114:115]
	global_load_dwordx4 v[114:117], v[122:123], off nt
	global_load_dwordx4 v[118:121], v[122:123], off offset:256 nt
	s_waitcnt vmcnt(1)
	v_lshlrev_b32_e32 v124, 16, v114
	v_and_b32_e32 v125, 0xffff0000, v114
	v_lshlrev_b32_e32 v114, 16, v115
	v_and_b32_e32 v115, 0xffff0000, v115
	v_lshlrev_b32_e32 v126, 16, v116
	v_and_b32_e32 v127, 0xffff0000, v116
	v_lshlrev_b32_e32 v116, 16, v117
	v_and_b32_e32 v117, 0xffff0000, v117
	s_waitcnt vmcnt(0)
	v_lshlrev_b32_e32 v170, 16, v118
	v_and_b32_e32 v171, 0xffff0000, v118
	v_lshlrev_b32_e32 v118, 16, v119
	v_and_b32_e32 v119, 0xffff0000, v119
	v_lshlrev_b32_e32 v172, 16, v120
	v_and_b32_e32 v173, 0xffff0000, v120
	v_lshlrev_b32_e32 v120, 16, v121
	v_and_b32_e32 v121, 0xffff0000, v121
	v_pk_add_f32 v[110:111], v[110:111], v[114:115]
	v_pk_add_f32 v[108:109], v[108:109], v[124:125]
	v_pk_add_f32 v[106:107], v[106:107], v[116:117]
	v_pk_add_f32 v[114:115], v[102:103], v[118:119]
	v_pk_add_f32 v[116:117], v[100:101], v[170:171]
	v_pk_add_f32 v[104:105], v[104:105], v[126:127]
	v_pk_add_f32 v[118:119], v[98:99], v[120:121]
	v_pk_add_f32 v[120:121], v[96:97], v[172:173]
	v_cvt_pk_bf16_f32 v96, v108, v109
	v_cvt_pk_bf16_f32 v97, v110, v111
	v_mul_f32_e32 v109, v109, v109
	v_mul_f32_e32 v111, v111, v111
	v_cvt_pk_bf16_f32 v101, v114, v115
	v_mul_f32_e32 v113, v117, v117
	v_mul_f32_e32 v115, v115, v115
	v_cvt_pk_bf16_f32 v98, v104, v105
	v_cvt_pk_bf16_f32 v99, v106, v107
	v_mul_f32_e32 v105, v105, v105
	v_cvt_pk_bf16_f32 v100, v116, v117
	v_mul_f32_e32 v117, v121, v121
	v_fmac_f32_e32 v109, v108, v108
	v_fmac_f32_e32 v111, v110, v110
	v_fmac_f32_e32 v113, v116, v116
	v_fmac_f32_e32 v115, v114, v114
	v_mul_f32_e32 v107, v107, v107
	v_cvt_pk_bf16_f32 v103, v118, v119
	v_mul_f32_e32 v119, v119, v119
	global_store_dwordx4 v[122:123], v[96:99], off
	v_fmac_f32_e32 v105, v104, v104
	v_fmac_f32_e32 v117, v120, v120
	v_add_f32_e32 v96, v109, v111
	v_add_f32_e32 v97, v113, v115
	v_fmac_f32_e32 v107, v106, v106
	v_fmac_f32_e32 v119, v118, v118
	v_add_f32_e32 v96, v105, v96
	v_add_f32_e32 v97, v117, v97
	v_add_f32_e32 v96, v107, v96
	v_add_f32_e32 v97, v119, v97
	v_add_f32_e32 v96, v96, v97
	v_mov_b32_e32 v97, v96
	s_nop 1
	v_permlane16_swap_b32_e32 v96, v97
	v_add_f32_e32 v96, v96, v97
	v_mov_b32_e32 v97, v96
	v_cvt_pk_bf16_f32 v102, v120, v121
	s_nop 0
	v_permlane32_swap_b32_e32 v96, v97
	global_store_dwordx4 v[122:123], v[100:103], off offset:256
	s_and_saveexec_b64 s[0:1], vcc
	v_add_f32_e32 v96, v96, v97
	ds_write_b32 v112, v96 offset:256
	s_or_b64 exec, exec, s[0:1]
	v_add_u32_e32 v96, 32, v144
	v_ashrrev_i32_e32 v97, 31, v96
	v_lshlrev_b64 v[96:97], 11, v[96:97]
	v_lshl_add_u64 v[96:97], s[12:13], 0, v[96:97]
	v_lshl_add_u64 v[104:105], v[146:147], 1, v[96:97]
	global_load_dwordx4 v[96:99], v[104:105], off nt
	global_load_dwordx4 v[100:103], v[104:105], off offset:256 nt
	s_waitcnt vmcnt(1)
; __device__ __forceinline__ unsigned pk2(float lo, float hi) { f32x2_t v = {lo, hi}; bf16x2_t b = __builtin_convertvector(v, bf16x2_t); return __builtin_bit_cast(unsigned, b); }
; __device__ __forceinline__ float xor16_sum(float v) { const auto r = __builtin_amdgcn_permlane16_swap(__float_as_uint(v), __float_as_uint(v), false, false); return __uint_as_float(r[0]) + __uint_as_float(r[1]); }
; __device__ __forceinline__ float xor32_sum(float v) { const auto r = __builtin_amdgcn_permlane32_swap(__float_as_uint(v), __float_as_uint(v), false, false); return __uint_as_float(r[0]) + __uint_as_float(r[1]); }
; #define BF16_LO(w) __uint_as_float((w) << 16)
; #define BF16_HI(w) __uint_as_float((w) & 0xffff0000u)
;     __device__ __forceinline__ void operator()(const f32x4 (&acc)[2][2][4][2], const Unit& u, int wr, int wc, int fr_in, int fq_in) const {
;     ...
; #pragma unroll
;         for (int ai = 0; ai < 2; ++ai)
; #pragma unroll
;             for (int m = 0; m < 4; ++m) {
;                 const int row = u.pm * BM + ai * 128 + wr * 64 + m * 16 + fr;
;                 float s = 0.f;
; #pragma unroll
;                 for (int bj = 0; bj < 2; ++bj) {
;                     const size_t off = (size_t)row * DM + u.pn * BM + bj * HALF + wc * 32 + 8 * fq;
;                     f32x4 b0, b1;
;                     if (xbase) { b0 = *(const f32x4*)(xbase + off); b1 = *(const f32x4*)(xbase + off + 4); }
;                     else { const u32x4 q = *(const u32x4*)(hb + off);
;                         b0 = (f32x4){BF16_LO(q.x), BF16_HI(q.x), BF16_LO(q.y), BF16_HI(q.y)}; b1 = (f32x4){BF16_LO(q.z), BF16_HI(q.z), BF16_LO(q.w), BF16_HI(q.w)}; }
;                     const f32x4 h0 = b0 + acc[ai][bj][m][0], h1 = b1 + acc[ai][bj][m][1];
;                     u32x4 w; w.x = pk2(h0[0], h0[1]); w.y = pk2(h0[2], h0[3]); w.z = pk2(h1[0], h1[1]); w.w = pk2(h1[2], h1[3]);
;                     *(u32x4*)(hb + off) = w;
;                     s += (h0[0] * h0[0] + h0[1] * h0[1]) + (h0[2] * h0[2] + h0[3] * h0[3]) + (h1[0] * h1[0] + h1[1] * h1[1]) + (h1[2] * h1[2] + h1[3] * h1[3]);
;                 }
;                 s = xor32_sum(xor16_sum(s));
;                 if (fq == 0) xch[(ai * 128 + wr * 64 + m * 16 + fr) * 4 + wc] = s;
	v_lshlrev_b32_e32 v106, 16, v96
	v_and_b32_e32 v107, 0xffff0000, v96
	v_lshlrev_b32_e32 v96, 16, v97
	v_and_b32_e32 v97, 0xffff0000, v97
	v_lshlrev_b32_e32 v108, 16, v98
	v_and_b32_e32 v109, 0xffff0000, v98
	v_lshlrev_b32_e32 v98, 16, v99
	v_and_b32_e32 v99, 0xffff0000, v99
	s_waitcnt vmcnt(0)
	v_lshlrev_b32_e32 v110, 16, v100
	v_and_b32_e32 v111, 0xffff0000, v100
	v_lshlrev_b32_e32 v100, 16, v101
	v_and_b32_e32 v101, 0xffff0000, v101
	v_lshlrev_b32_e32 v114, 16, v102
	v_and_b32_e32 v115, 0xffff0000, v102
	v_lshlrev_b32_e32 v102, 16, v103
	v_and_b32_e32 v103, 0xffff0000, v103
	v_pk_add_f32 v[94:95], v[94:95], v[96:97]
	v_pk_add_f32 v[92:93], v[92:93], v[106:107]
	v_pk_add_f32 v[90:91], v[90:91], v[98:99]
	v_pk_add_f32 v[96:97], v[86:87], v[100:101]
	v_pk_add_f32 v[98:99], v[84:85], v[110:111]
	v_pk_add_f32 v[88:89], v[88:89], v[108:109]
	v_pk_add_f32 v[100:101], v[82:83], v[102:103]
	v_pk_add_f32 v[102:103], v[80:81], v[114:115]
	v_cvt_pk_bf16_f32 v80, v92, v93
	v_cvt_pk_bf16_f32 v81, v94, v95
	v_mul_f32_e32 v93, v93, v93
	v_mul_f32_e32 v95, v95, v95
	v_cvt_pk_bf16_f32 v84, v98, v99
	v_cvt_pk_bf16_f32 v85, v96, v97
	v_mul_f32_e32 v99, v99, v99
	v_mul_f32_e32 v97, v97, v97
	v_cvt_pk_bf16_f32 v82, v88, v89
	v_cvt_pk_bf16_f32 v83, v90, v91
	v_mul_f32_e32 v89, v89, v89
	v_cvt_pk_bf16_f32 v86, v102, v103
	v_mul_f32_e32 v103, v103, v103
	v_fmac_f32_e32 v93, v92, v92
	v_fmac_f32_e32 v95, v94, v94
	v_fmac_f32_e32 v99, v98, v98
	v_fmac_f32_e32 v97, v96, v96
	v_mul_f32_e32 v91, v91, v91
	v_cvt_pk_bf16_f32 v87, v100, v101
	v_mul_f32_e32 v101, v101, v101
	global_store_dwordx4 v[104:105], v[80:83], off
	v_fmac_f32_e32 v89, v88, v88
	v_fmac_f32_e32 v103, v102, v102
	v_add_f32_e32 v80, v93, v95
	v_add_f32_e32 v81, v99, v97
	v_fmac_f32_e32 v91, v90, v90
	v_fmac_f32_e32 v101, v100, v100
	v_add_f32_e32 v80, v89, v80
	v_add_f32_e32 v81, v103, v81
	v_add_f32_e32 v80, v91, v80
	v_add_f32_e32 v81, v101, v81
	v_add_f32_e32 v80, v80, v81
	v_mov_b32_e32 v81, v80
	s_nop 1
	v_permlane16_swap_b32_e32 v80, v81
	v_add_f32_e32 v80, v80, v81
	v_mov_b32_e32 v81, v80
	s_nop 1
	v_permlane32_swap_b32_e32 v80, v81
	global_store_dwordx4 v[104:105], v[84:87], off offset:256
	s_and_saveexec_b64 s[0:1], vcc
	v_add_f32_e32 v80, v80, v81
	ds_write_b32 v112, v80 offset:512
	s_or_b64 exec, exec, s[0:1]
	v_add_u32_e32 v80, 48, v144
	v_ashrrev_i32_e32 v81, 31, v80
	v_lshlrev_b64 v[80:81], 11, v[80:81]
	v_lshl_add_u64 v[80:81], s[12:13], 0, v[80:81]
	v_lshl_add_u64 v[88:89], v[146:147], 1, v[80:81]
	global_load_dwordx4 v[80:83], v[88:89], off nt
	global_load_dwordx4 v[84:87], v[88:89], off offset:256 nt
	s_waitcnt vmcnt(1)
	v_lshlrev_b32_e32 v90, 16, v80
	v_and_b32_e32 v91, 0xffff0000, v80
	v_lshlrev_b32_e32 v80, 16, v81
	v_and_b32_e32 v81, 0xffff0000, v81
	v_lshlrev_b32_e32 v92, 16, v82
	v_and_b32_e32 v93, 0xffff0000, v82
	v_lshlrev_b32_e32 v82, 16, v83
	v_and_b32_e32 v83, 0xffff0000, v83
	s_waitcnt vmcnt(0)
	v_lshlrev_b32_e32 v94, 16, v84
	v_and_b32_e32 v95, 0xffff0000, v84
	v_lshlrev_b32_e32 v84, 16, v85
	v_and_b32_e32 v85, 0xffff0000, v85
	v_lshlrev_b32_e32 v96, 16, v86
	v_and_b32_e32 v97, 0xffff0000, v86
	v_lshlrev_b32_e32 v86, 16, v87
	v_and_b32_e32 v87, 0xffff0000, v87
	v_pk_add_f32 v[78:79], v[78:79], v[80:81]
	v_pk_add_f32 v[76:77], v[76:77], v[90:91]
	v_pk_add_f32 v[74:75], v[74:75], v[82:83]
	v_pk_add_f32 v[80:81], v[70:71], v[84:85]
	v_pk_add_f32 v[82:83], v[68:69], v[94:95]
	v_pk_add_f32 v[72:73], v[72:73], v[92:93]
	v_pk_add_f32 v[84:85], v[66:67], v[86:87]
	v_pk_add_f32 v[86:87], v[64:65], v[96:97]
	v_cvt_pk_bf16_f32 v64, v76, v77
	v_cvt_pk_bf16_f32 v65, v78, v79
	v_mul_f32_e32 v77, v77, v77
	v_mul_f32_e32 v79, v79, v79
	v_cvt_pk_bf16_f32 v68, v82, v83
	v_cvt_pk_bf16_f32 v69, v80, v81
	v_mul_f32_e32 v83, v83, v83
	v_mul_f32_e32 v81, v81, v81
	v_cvt_pk_bf16_f32 v66, v72, v73
	v_cvt_pk_bf16_f32 v67, v74, v75
	v_mul_f32_e32 v73, v73, v73
	v_cvt_pk_bf16_f32 v70, v86, v87
	v_mul_f32_e32 v87, v87, v87
	v_fmac_f32_e32 v77, v76, v76
	v_fmac_f32_e32 v79, v78, v78
	v_fmac_f32_e32 v83, v82, v82
	v_fmac_f32_e32 v81, v80, v80
	v_mul_f32_e32 v75, v75, v75
	v_cvt_pk_bf16_f32 v71, v84, v85
	v_mul_f32_e32 v85, v85, v85
	global_store_dwordx4 v[88:89], v[64:67], off
	v_fmac_f32_e32 v73, v72, v72
	v_fmac_f32_e32 v87, v86, v86
	v_add_f32_e32 v64, v77, v79
	v_add_f32_e32 v65, v83, v81
	v_fmac_f32_e32 v75, v74, v74
	v_fmac_f32_e32 v85, v84, v84
	v_add_f32_e32 v64, v73, v64
	v_add_f32_e32 v65, v87, v65
	v_add_f32_e32 v64, v75, v64
	v_add_f32_e32 v65, v85, v65
	v_add_f32_e32 v64, v64, v65
	v_mov_b32_e32 v65, v64
	s_nop 1
	v_permlane16_swap_b32_e32 v64, v65
	v_add_f32_e32 v64, v64, v65
	v_mov_b32_e32 v65, v64
	s_nop 1
	v_permlane32_swap_b32_e32 v64, v65
	global_store_dwordx4 v[88:89], v[68:71], off offset:256
	s_and_saveexec_b64 s[0:1], vcc
	v_add_f32_e32 v64, v64, v65
	ds_write_b32 v112, v64 offset:768
	s_or_b64 exec, exec, s[0:1]
	v_add_u32_e32 v64, 0x80, v144
	v_ashrrev_i32_e32 v65, 31, v64
	v_lshlrev_b64 v[64:65], 11, v[64:65]
	v_lshl_add_u64 v[64:65], s[12:13], 0, v[64:65]
	v_lshl_add_u64 v[72:73], v[146:147], 1, v[64:65]
	global_load_dwordx4 v[64:67], v[72:73], off nt
	global_load_dwordx4 v[68:71], v[72:73], off offset:256 nt
	s_waitcnt vmcnt(1)
	v_lshlrev_b32_e32 v74, 16, v64
	v_and_b32_e32 v75, 0xffff0000, v64
	v_lshlrev_b32_e32 v64, 16, v65
	v_and_b32_e32 v65, 0xffff0000, v65
	v_lshlrev_b32_e32 v76, 16, v66
	v_and_b32_e32 v77, 0xffff0000, v66
	v_lshlrev_b32_e32 v66, 16, v67
	v_and_b32_e32 v67, 0xffff0000, v67
	s_waitcnt vmcnt(0)
; __device__ __forceinline__ unsigned pk2(float lo, float hi) { f32x2_t v = {lo, hi}; bf16x2_t b = __builtin_convertvector(v, bf16x2_t); return __builtin_bit_cast(unsigned, b); }
; __device__ __forceinline__ float xor16_sum(float v) { const auto r = __builtin_amdgcn_permlane16_swap(__float_as_uint(v), __float_as_uint(v), false, false); return __uint_as_float(r[0]) + __uint_as_float(r[1]); }
; __device__ __forceinline__ float xor32_sum(float v) { const auto r = __builtin_amdgcn_permlane32_swap(__float_as_uint(v), __float_as_uint(v), false, false); return __uint_as_float(r[0]) + __uint_as_float(r[1]); }
; #define BF16_LO(w) __uint_as_float((w) << 16)
; #define BF16_HI(w) __uint_as_float((w) & 0xffff0000u)
;     __device__ __forceinline__ void operator()(const f32x4 (&acc)[2][2][4][2], const Unit& u, int wr, int wc, int fr_in, int fq_in) const {
;     ...
; #pragma unroll
;         for (int ai = 0; ai < 2; ++ai)
; #pragma unroll
;             for (int m = 0; m < 4; ++m) {
;                 const int row = u.pm * BM + ai * 128 + wr * 64 + m * 16 + fr;
;                 float s = 0.f;
; #pragma unroll
;                 for (int bj = 0; bj < 2; ++bj) {
;                     const size_t off = (size_t)row * DM + u.pn * BM + bj * HALF + wc * 32 + 8 * fq;
;                     f32x4 b0, b1;
;                     if (xbase) { b0 = *(const f32x4*)(xbase + off); b1 = *(const f32x4*)(xbase + off + 4); }
;                     else { const u32x4 q = *(const u32x4*)(hb + off);
;                         b0 = (f32x4){BF16_LO(q.x), BF16_HI(q.x), BF16_LO(q.y), BF16_HI(q.y)}; b1 = (f32x4){BF16_LO(q.z), BF16_HI(q.z), BF16_LO(q.w), BF16_HI(q.w)}; }
;                     const f32x4 h0 = b0 + acc[ai][bj][m][0], h1 = b1 + acc[ai][bj][m][1];
;                     u32x4 w; w.x = pk2(h0[0], h0[1]); w.y = pk2(h0[2], h0[3]); w.z = pk2(h1[0], h1[1]); w.w = pk2(h1[2], h1[3]);
;                     *(u32x4*)(hb + off) = w;
;                     s += (h0[0] * h0[0] + h0[1] * h0[1]) + (h0[2] * h0[2] + h0[3] * h0[3]) + (h1[0] * h1[0] + h1[1] * h1[1]) + (h1[2] * h1[2] + h1[3] * h1[3]);
;                 }
;                 s = xor32_sum(xor16_sum(s));
;                 if (fq == 0) xch[(ai * 128 + wr * 64 + m * 16 + fr) * 4 + wc] = s;
	v_lshlrev_b32_e32 v78, 16, v68
	v_and_b32_e32 v79, 0xffff0000, v68
	v_lshlrev_b32_e32 v68, 16, v69
	v_and_b32_e32 v69, 0xffff0000, v69
	v_lshlrev_b32_e32 v80, 16, v70
	v_and_b32_e32 v81, 0xffff0000, v70
	v_lshlrev_b32_e32 v70, 16, v71
	v_and_b32_e32 v71, 0xffff0000, v71
	v_pk_add_f32 v[62:63], v[62:63], v[64:65]
	v_pk_add_f32 v[60:61], v[60:61], v[74:75]
	v_pk_add_f32 v[58:59], v[58:59], v[66:67]
	v_pk_add_f32 v[64:65], v[54:55], v[68:69]
	v_pk_add_f32 v[66:67], v[52:53], v[78:79]
	v_pk_add_f32 v[56:57], v[56:57], v[76:77]
	v_pk_add_f32 v[68:69], v[50:51], v[70:71]
	v_pk_add_f32 v[70:71], v[48:49], v[80:81]
	v_cvt_pk_bf16_f32 v48, v60, v61
	v_cvt_pk_bf16_f32 v49, v62, v63
	v_mul_f32_e32 v61, v61, v61
	v_mul_f32_e32 v63, v63, v63
	v_cvt_pk_bf16_f32 v52, v66, v67
	v_cvt_pk_bf16_f32 v53, v64, v65
	v_mul_f32_e32 v67, v67, v67
	v_mul_f32_e32 v65, v65, v65
	v_cvt_pk_bf16_f32 v50, v56, v57
	v_cvt_pk_bf16_f32 v51, v58, v59
	v_mul_f32_e32 v57, v57, v57
	v_cvt_pk_bf16_f32 v54, v70, v71
	v_mul_f32_e32 v71, v71, v71
	v_fmac_f32_e32 v61, v60, v60
	v_fmac_f32_e32 v63, v62, v62
	v_fmac_f32_e32 v67, v66, v66
	v_fmac_f32_e32 v65, v64, v64
	v_mul_f32_e32 v59, v59, v59
	v_cvt_pk_bf16_f32 v55, v68, v69
	v_mul_f32_e32 v69, v69, v69
	global_store_dwordx4 v[72:73], v[48:51], off
	v_fmac_f32_e32 v57, v56, v56
	v_fmac_f32_e32 v71, v70, v70
	v_add_f32_e32 v48, v61, v63
	v_add_f32_e32 v49, v67, v65
	v_fmac_f32_e32 v59, v58, v58
	v_fmac_f32_e32 v69, v68, v68
	v_add_f32_e32 v48, v57, v48
	v_add_f32_e32 v49, v71, v49
	v_add_f32_e32 v48, v59, v48
	v_add_f32_e32 v49, v69, v49
	v_add_f32_e32 v48, v48, v49
	v_mov_b32_e32 v49, v48
	s_nop 1
	v_permlane16_swap_b32_e32 v48, v49
	v_add_f32_e32 v48, v48, v49
	v_mov_b32_e32 v49, v48
	s_nop 1
	v_permlane32_swap_b32_e32 v48, v49
	global_store_dwordx4 v[72:73], v[52:55], off offset:256
	s_and_saveexec_b64 s[0:1], vcc
	v_add_f32_e32 v48, v48, v49
	ds_write_b32 v112, v48 offset:2048
	s_or_b64 exec, exec, s[0:1]
	v_add_u32_e32 v48, 0x90, v144
	v_ashrrev_i32_e32 v49, 31, v48
	v_lshlrev_b64 v[48:49], 11, v[48:49]
	v_lshl_add_u64 v[48:49], s[12:13], 0, v[48:49]
	v_lshl_add_u64 v[56:57], v[146:147], 1, v[48:49]
	global_load_dwordx4 v[48:51], v[56:57], off nt
	global_load_dwordx4 v[52:55], v[56:57], off offset:256 nt
	s_waitcnt vmcnt(1)
	v_lshlrev_b32_e32 v58, 16, v48
	v_and_b32_e32 v59, 0xffff0000, v48
	v_lshlrev_b32_e32 v48, 16, v49
	v_and_b32_e32 v49, 0xffff0000, v49
	v_lshlrev_b32_e32 v60, 16, v50
	v_and_b32_e32 v61, 0xffff0000, v50
	v_lshlrev_b32_e32 v50, 16, v51
	v_and_b32_e32 v51, 0xffff0000, v51
	s_waitcnt vmcnt(0)
	v_lshlrev_b32_e32 v62, 16, v52
	v_and_b32_e32 v63, 0xffff0000, v52
	v_lshlrev_b32_e32 v52, 16, v53
	v_and_b32_e32 v53, 0xffff0000, v53
	v_lshlrev_b32_e32 v64, 16, v54
	v_and_b32_e32 v65, 0xffff0000, v54
	v_lshlrev_b32_e32 v54, 16, v55
	v_and_b32_e32 v55, 0xffff0000, v55
	v_pk_add_f32 v[46:47], v[46:47], v[48:49]
	v_pk_add_f32 v[44:45], v[44:45], v[58:59]
	v_pk_add_f32 v[42:43], v[42:43], v[50:51]
	v_pk_add_f32 v[48:49], v[38:39], v[52:53]
	v_pk_add_f32 v[50:51], v[36:37], v[62:63]
	v_pk_add_f32 v[40:41], v[40:41], v[60:61]
	v_pk_add_f32 v[52:53], v[34:35], v[54:55]
	v_pk_add_f32 v[54:55], v[32:33], v[64:65]
	v_cvt_pk_bf16_f32 v32, v44, v45
	v_cvt_pk_bf16_f32 v33, v46, v47
	v_mul_f32_e32 v45, v45, v45
	v_mul_f32_e32 v47, v47, v47
	v_cvt_pk_bf16_f32 v36, v50, v51
	v_cvt_pk_bf16_f32 v37, v48, v49
	v_mul_f32_e32 v51, v51, v51
	v_mul_f32_e32 v49, v49, v49
	v_cvt_pk_bf16_f32 v34, v40, v41
	v_cvt_pk_bf16_f32 v35, v42, v43
	v_mul_f32_e32 v41, v41, v41
	v_cvt_pk_bf16_f32 v38, v54, v55
	v_mul_f32_e32 v55, v55, v55
	v_fmac_f32_e32 v45, v44, v44
	v_fmac_f32_e32 v47, v46, v46
	v_fmac_f32_e32 v51, v50, v50
	v_fmac_f32_e32 v49, v48, v48
	v_mul_f32_e32 v43, v43, v43
	v_cvt_pk_bf16_f32 v39, v52, v53
	v_mul_f32_e32 v53, v53, v53
	global_store_dwordx4 v[56:57], v[32:35], off
	v_fmac_f32_e32 v41, v40, v40
	v_fmac_f32_e32 v55, v54, v54
	v_add_f32_e32 v32, v45, v47
	v_add_f32_e32 v33, v51, v49
	v_fmac_f32_e32 v43, v42, v42
	v_fmac_f32_e32 v53, v52, v52
	v_add_f32_e32 v32, v41, v32
	v_add_f32_e32 v33, v55, v33
	v_add_f32_e32 v32, v43, v32
	v_add_f32_e32 v33, v53, v33
	v_add_f32_e32 v32, v32, v33
	v_mov_b32_e32 v33, v32
	s_nop 1
	v_permlane16_swap_b32_e32 v32, v33
	v_add_f32_e32 v32, v32, v33
	v_mov_b32_e32 v33, v32
	s_nop 1
	v_permlane32_swap_b32_e32 v32, v33
	global_store_dwordx4 v[56:57], v[36:39], off offset:256
	s_and_saveexec_b64 s[0:1], vcc
	v_add_f32_e32 v32, v32, v33
	ds_write_b32 v112, v32 offset:2304
	s_or_b64 exec, exec, s[0:1]
	v_add_u32_e32 v32, 0xa0, v144
	v_ashrrev_i32_e32 v33, 31, v32
	v_lshlrev_b64 v[32:33], 11, v[32:33]
	v_lshl_add_u64 v[32:33], s[12:13], 0, v[32:33]
	v_lshl_add_u64 v[40:41], v[146:147], 1, v[32:33]
	global_load_dwordx4 v[32:35], v[40:41], off nt
	global_load_dwordx4 v[36:39], v[40:41], off offset:256 nt
	s_waitcnt vmcnt(1)
	v_lshlrev_b32_e32 v42, 16, v32
	v_and_b32_e32 v43, 0xffff0000, v32
	v_lshlrev_b32_e32 v32, 16, v33
	v_and_b32_e32 v33, 0xffff0000, v33
	v_lshlrev_b32_e32 v44, 16, v34
	v_and_b32_e32 v45, 0xffff0000, v34
	v_lshlrev_b32_e32 v34, 16, v35
	v_and_b32_e32 v35, 0xffff0000, v35
	s_waitcnt vmcnt(0)
; __device__ __forceinline__ unsigned pk2(float lo, float hi) { f32x2_t v = {lo, hi}; bf16x2_t b = __builtin_convertvector(v, bf16x2_t); return __builtin_bit_cast(unsigned, b); }
; __device__ __forceinline__ float xor16_sum(float v) { const auto r = __builtin_amdgcn_permlane16_swap(__float_as_uint(v), __float_as_uint(v), false, false); return __uint_as_float(r[0]) + __uint_as_float(r[1]); }
; __device__ __forceinline__ float xor32_sum(float v) { const auto r = __builtin_amdgcn_permlane32_swap(__float_as_uint(v), __float_as_uint(v), false, false); return __uint_as_float(r[0]) + __uint_as_float(r[1]); }
; #define BF16_LO(w) __uint_as_float((w) << 16)
;     __device__ __forceinline__ void operator()(const f32x4 (&acc)[2][2][4][2], const Unit& u, int wr, int wc, int fr_in, int fq_in) const {
;     ...
;                 for (int bj = 0; bj < 2; ++bj) {
;                     const size_t off = (size_t)row * DM + u.pn * BM + bj * HALF + wc * 32 + 8 * fq;
;                     f32x4 b0, b1;
;                     if (xbase) { b0 = *(const f32x4*)(xbase + off); b1 = *(const f32x4*)(xbase + off + 4); }
;                     else { const u32x4 q = *(const u32x4*)(hb + off);
;                         b0 = (f32x4){BF16_LO(q.x), BF16_HI(q.x), BF16_LO(q.y), BF16_HI(q.y)}; b1 = (f32x4){BF16_LO(q.z), BF16_HI(q.z), BF16_LO(q.w), BF16_HI(q.w)}; }
;                     const f32x4 h0 = b0 + acc[ai][bj][m][0], h1 = b1 + acc[ai][bj][m][1];
;                     u32x4 w; w.x = pk2(h0[0], h0[1]); w.y = pk2(h0[2], h0[3]); w.z = pk2(h1[0], h1[1]); w.w = pk2(h1[2], h1[3]);
;                     *(u32x4*)(hb + off) = w;
;                     s += (h0[0] * h0[0] + h0[1] * h0[1]) + (h0[2] * h0[2] + h0[3] * h0[3]) + (h1[0] * h1[0] + h1[1] * h1[1]) + (h1[2] * h1[2] + h1[3] * h1[3]);
;                 }
;                 s = xor32_sum(xor16_sum(s));
;                 if (fq == 0) xch[(ai * 128 + wr * 64 + m * 16 + fr) * 4 + wc] = s;
;                 if (m == 3) asm volatile("" ::: "memory");
;             }
;         PG8_EPI_BAR();
;         if (fq == 0) {
; #pragma unroll
;             for (int ai = 0; ai < 2; ++ai) {
;                 const int rl = ai * 128 + wr * 64 + wc * 16 + fr;
;                 const f32x4 p = *(const PG8_LAS f32x4*)(xch + rl * 4);
;                 const float t = (p[0] + p[1]) + (p[2] + p[3]);
;                 atomicAdd(rsq + u.pm * BM + rl, (u64_t)(t * 16777216.0f));
	v_lshlrev_b32_e32 v46, 16, v36
	v_and_b32_e32 v47, 0xffff0000, v36
	v_lshlrev_b32_e32 v36, 16, v37
	v_and_b32_e32 v37, 0xffff0000, v37
	v_lshlrev_b32_e32 v48, 16, v38
	v_and_b32_e32 v49, 0xffff0000, v38
	v_lshlrev_b32_e32 v38, 16, v39
	v_and_b32_e32 v39, 0xffff0000, v39
	v_pk_add_f32 v[30:31], v[30:31], v[32:33]
	v_pk_add_f32 v[28:29], v[28:29], v[42:43]
	v_pk_add_f32 v[26:27], v[26:27], v[34:35]
	v_pk_add_f32 v[32:33], v[22:23], v[36:37]
	v_pk_add_f32 v[34:35], v[20:21], v[46:47]
	v_pk_add_f32 v[24:25], v[24:25], v[44:45]
	v_pk_add_f32 v[36:37], v[18:19], v[38:39]
	v_pk_add_f32 v[38:39], v[16:17], v[48:49]
	v_cvt_pk_bf16_f32 v16, v28, v29
	v_cvt_pk_bf16_f32 v17, v30, v31
	v_mul_f32_e32 v29, v29, v29
	v_mul_f32_e32 v31, v31, v31
	v_cvt_pk_bf16_f32 v20, v34, v35
	v_cvt_pk_bf16_f32 v21, v32, v33
	v_mul_f32_e32 v35, v35, v35
	v_mul_f32_e32 v33, v33, v33
	v_cvt_pk_bf16_f32 v18, v24, v25
	v_cvt_pk_bf16_f32 v19, v26, v27
	v_mul_f32_e32 v25, v25, v25
	v_cvt_pk_bf16_f32 v22, v38, v39
	v_mul_f32_e32 v39, v39, v39
	v_fmac_f32_e32 v29, v28, v28
	v_fmac_f32_e32 v31, v30, v30
	v_fmac_f32_e32 v35, v34, v34
	v_fmac_f32_e32 v33, v32, v32
	v_mul_f32_e32 v27, v27, v27
	v_cvt_pk_bf16_f32 v23, v36, v37
	v_mul_f32_e32 v37, v37, v37
	global_store_dwordx4 v[40:41], v[16:19], off
	v_fmac_f32_e32 v25, v24, v24
	v_fmac_f32_e32 v39, v38, v38
	v_add_f32_e32 v16, v29, v31
	v_add_f32_e32 v17, v35, v33
	v_fmac_f32_e32 v27, v26, v26
	v_fmac_f32_e32 v37, v36, v36
	v_add_f32_e32 v16, v25, v16
	v_add_f32_e32 v17, v39, v17
	v_add_f32_e32 v16, v27, v16
	v_add_f32_e32 v17, v37, v17
	v_add_f32_e32 v16, v16, v17
	v_mov_b32_e32 v17, v16
	s_nop 1
	v_permlane16_swap_b32_e32 v16, v17
	v_add_f32_e32 v16, v16, v17
	v_mov_b32_e32 v17, v16
	s_nop 1
	v_permlane32_swap_b32_e32 v16, v17
	global_store_dwordx4 v[40:41], v[20:23], off offset:256
	s_and_saveexec_b64 s[0:1], vcc
	v_add_f32_e32 v16, v16, v17
	ds_write_b32 v112, v16 offset:2560
	s_or_b64 exec, exec, s[0:1]
	v_add_u32_e32 v16, 0xb0, v144
	v_ashrrev_i32_e32 v17, 31, v16
	v_lshlrev_b64 v[16:17], 11, v[16:17]
	v_lshl_add_u64 v[16:17], s[12:13], 0, v[16:17]
	v_lshl_add_u64 v[24:25], v[146:147], 1, v[16:17]
	global_load_dwordx4 v[16:19], v[24:25], off nt
	global_load_dwordx4 v[20:23], v[24:25], off offset:256 nt
	s_waitcnt vmcnt(1)
	v_lshlrev_b32_e32 v26, 16, v16
	v_and_b32_e32 v27, 0xffff0000, v16
	v_lshlrev_b32_e32 v16, 16, v17
	v_and_b32_e32 v17, 0xffff0000, v17
	v_lshlrev_b32_e32 v28, 16, v18
	v_and_b32_e32 v29, 0xffff0000, v18
	v_lshlrev_b32_e32 v18, 16, v19
	v_and_b32_e32 v19, 0xffff0000, v19
	s_waitcnt vmcnt(0)
	v_lshlrev_b32_e32 v30, 16, v20
	v_and_b32_e32 v31, 0xffff0000, v20
	v_lshlrev_b32_e32 v20, 16, v21
	v_and_b32_e32 v21, 0xffff0000, v21
	v_lshlrev_b32_e32 v32, 16, v22
	v_and_b32_e32 v33, 0xffff0000, v22
	v_lshlrev_b32_e32 v22, 16, v23
	v_and_b32_e32 v23, 0xffff0000, v23
	v_pk_add_f32 v[14:15], v[14:15], v[16:17]
	v_pk_add_f32 v[12:13], v[12:13], v[26:27]
	v_pk_add_f32 v[10:11], v[10:11], v[18:19]
	v_pk_add_f32 v[16:17], v[6:7], v[20:21]
	v_pk_add_f32 v[18:19], v[4:5], v[30:31]
	v_pk_add_f32 v[8:9], v[8:9], v[28:29]
	v_pk_add_f32 v[20:21], v[2:3], v[22:23]
	v_pk_add_f32 v[22:23], v[0:1], v[32:33]
	v_cvt_pk_bf16_f32 v0, v12, v13
	v_cvt_pk_bf16_f32 v1, v14, v15
	v_mul_f32_e32 v13, v13, v13
	v_mul_f32_e32 v15, v15, v15
	v_cvt_pk_bf16_f32 v4, v18, v19
	v_cvt_pk_bf16_f32 v5, v16, v17
	v_mul_f32_e32 v19, v19, v19
	v_mul_f32_e32 v17, v17, v17
	v_cvt_pk_bf16_f32 v2, v8, v9
	v_cvt_pk_bf16_f32 v3, v10, v11
	v_mul_f32_e32 v9, v9, v9
	v_cvt_pk_bf16_f32 v6, v22, v23
	v_mul_f32_e32 v23, v23, v23
	v_fmac_f32_e32 v13, v12, v12
	v_fmac_f32_e32 v15, v14, v14
	v_fmac_f32_e32 v19, v18, v18
	v_fmac_f32_e32 v17, v16, v16
	v_mul_f32_e32 v11, v11, v11
	v_cvt_pk_bf16_f32 v7, v20, v21
	v_mul_f32_e32 v21, v21, v21
	global_store_dwordx4 v[24:25], v[0:3], off
	v_fmac_f32_e32 v9, v8, v8
	v_fmac_f32_e32 v23, v22, v22
	v_add_f32_e32 v0, v13, v15
	v_add_f32_e32 v1, v19, v17
	v_fmac_f32_e32 v11, v10, v10
	v_fmac_f32_e32 v21, v20, v20
	v_add_f32_e32 v0, v9, v0
	v_add_f32_e32 v1, v23, v1
	v_add_f32_e32 v0, v11, v0
	v_add_f32_e32 v1, v21, v1
	v_add_f32_e32 v0, v0, v1
	v_mov_b32_e32 v1, v0
	s_nop 1
	v_permlane16_swap_b32_e32 v0, v1
	v_add_f32_e32 v0, v0, v1
	v_mov_b32_e32 v1, v0
	s_nop 1
	v_permlane32_swap_b32_e32 v0, v1
	global_store_dwordx4 v[24:25], v[4:7], off offset:256
	s_and_saveexec_b64 s[0:1], vcc
	v_add_f32_e32 v0, v0, v1
	ds_write_b32 v112, v0 offset:2816
	s_or_b64 exec, exec, s[0:1]
	s_waitcnt lgkmcnt(0)
	s_barrier
	s_and_saveexec_b64 s[0:1], vcc
	s_cbranch_execz .LBB0_1754
	v_add_u32_e32 v4, s46, v168
	v_lshl_add_u32 v6, v4, 4, v167
	ds_read_b128 v[0:3], v6
	s_ashr_i32 s5, s4, 31
	s_lshl_b64 s[4:5], s[4:5], 3
	s_add_u32 s4, s37, s4
	s_addc_u32 s5, s38, s5
	s_waitcnt lgkmcnt(0)
	v_add_f32_e32 v0, v0, v1
	v_add_f32_e32 v1, v2, v3
	v_add_f32_e32 v0, v0, v1
	v_mul_f32_e32 v0, 0x4b800000, v0
	v_trunc_f32_e32 v0, v0
	v_mul_f32_e32 v1, 0x2f800000, v0
	v_floor_f32_e32 v1, v1
	v_fmac_f32_e32 v0, 0xcf800000, v1
	v_cvt_u32_f32_e32 v0, v0
	v_cvt_u32_f32_e32 v1, v1
	v_ashrrev_i32_e32 v5, 31, v4
	v_lshl_add_u64 v[4:5], v[4:5], 3, s[4:5]
	global_atomic_add_x2 v[4:5], v[0:1], off
	ds_read_b128 v[0:3], v6 offset:2048
	s_waitcnt lgkmcnt(0)
	v_add_f32_e32 v0, v0, v1
	v_add_f32_e32 v1, v2, v3
	v_add_f32_e32 v0, v0, v1
	v_mul_f32_e32 v0, 0x4b800000, v0
	v_trunc_f32_e32 v0, v0
	v_mul_f32_e32 v1, 0x2f800000, v0
	v_floor_f32_e32 v1, v1
	v_fmac_f32_e32 v0, 0xcf800000, v1
	v_cvt_u32_f32_e32 v0, v0
	v_cvt_u32_f32_e32 v1, v1
	global_atomic_add_x2 v[4:5], v[0:1], off offset:1024

; __device__ __forceinline__ unsigned pk2(float lo, float hi) { f32x2_t v = {lo, hi}; bf16x2_t b = __builtin_convertvector(v, bf16x2_t); return __builtin_bit_cast(unsigned, b); }
; #define BF16_LO(w) __uint_as_float((w) << 16)
; #define BF16_HI(w) __uint_as_float((w) & 0xffff0000u)
;     __device__ __forceinline__ void operator()(const f32x4 (&acc)[2][2][4][2], const Unit& u, int wr, int wc, int fr_in, int fq_in) const {
;     ...
; #pragma unroll
;         for (int ai = 0; ai < 2; ++ai)
; #pragma unroll
;             for (int m = 0; m < 4; ++m)
; #pragma unroll
;                 for (int bj = 0; bj < 2; ++bj) {
;                     const size_t off = (size_t)(u.pm * BM + ai * 128 + wr * 64 + m * 16 + fr) * DM + u.pn * BM + bj * HALF + wc * 32 + 8 * fq;
;                     const u32x4 s = *(const u32x4*)(SG + off), q = *(const u32x4*)(hb + off);
;                     const f32x4 s0 = {BF16_LO(s.x), BF16_HI(s.x), BF16_LO(s.y), BF16_HI(s.y)}, s1 = {BF16_LO(s.z), BF16_HI(s.z), BF16_LO(s.w), BF16_HI(s.w)};
;                     const f32x4 b0 = {BF16_LO(q.x), BF16_HI(q.x), BF16_LO(q.y), BF16_HI(q.y)}, b1 = {BF16_LO(q.z), BF16_HI(q.z), BF16_LO(q.w), BF16_HI(q.w)};
;                     const f32x4 h0 = b0 + acc[ai][bj][m][0] * s0, h1 = b1 + acc[ai][bj][m][1] * s1;
;                     if (outf) { *(f32x4*)(outf + off) = h0; *(f32x4*)(outf + off + 4) = h1; }
;                     else { u32x4 w; w.x = pk2(h0[0], h0[1]); w.y = pk2(h0[2], h0[3]); w.z = pk2(h1[0], h1[1]); w.w = pk2(h1[2], h1[3]); *(u32x4*)(hb + off) = w; }
.LBB0_1914:
	v_mov_b32_e32 v144, v155
	v_mov_b32_e32 v145, v154
	s_lshl_b32 s3, s3, 8
	s_add_i32 s3, s3, s56
	s_lshl_b32 s2, s2, 8
	v_add_u32_e32 v144, s3, v144
	s_ashr_i32 s3, s2, 31
	v_lshlrev_b32_e32 v146, 3, v145
	v_ashrrev_i32_e32 v147, 31, v146
	s_or_b64 s[2:3], s[2:3], s[22:23]
	v_ashrrev_i32_e32 v145, 31, v144
	v_lshl_add_u64 v[146:147], s[2:3], 0, v[146:147]
	v_lshlrev_b64 v[148:149], 10, v[144:145]
	v_lshl_add_u64 v[152:153], v[146:147], 0, v[148:149]
	v_lshlrev_b64 v[148:149], 1, v[152:153]
	v_lshl_add_u64 v[150:151], s[8:9], 0, v[148:149]
	v_lshl_add_u64 v[148:149], s[18:19], 0, v[148:149]
	global_load_dwordx4 v[174:177], v[150:151], off nt
	global_load_dwordx4 v[178:181], v[148:149], off nt
	v_cndmask_b32_e64 v145, 0, 1, s[26:27]
	v_cmp_ne_u32_e64 s[6:7], 1, v145
	s_andn2_b64 vcc, exec, s[26:27]
	v_lshl_add_u64 v[152:153], v[152:153], 2, s[10:11]
	s_waitcnt vmcnt(0)
	v_lshlrev_b32_e32 v182, 16, v174
	v_and_b32_e32 v183, 0xffff0000, v174
	v_lshlrev_b32_e32 v174, 16, v175
	v_and_b32_e32 v175, 0xffff0000, v175
	v_lshlrev_b32_e32 v184, 16, v176
	v_and_b32_e32 v185, 0xffff0000, v176
	v_lshlrev_b32_e32 v176, 16, v177
	v_and_b32_e32 v177, 0xffff0000, v177
	v_lshlrev_b32_e32 v186, 16, v178
	v_and_b32_e32 v187, 0xffff0000, v178
	v_lshlrev_b32_e32 v178, 16, v179
	v_and_b32_e32 v179, 0xffff0000, v179
	v_lshlrev_b32_e32 v188, 16, v180
	v_and_b32_e32 v189, 0xffff0000, v180
	v_lshlrev_b32_e32 v180, 16, v181
	v_and_b32_e32 v181, 0xffff0000, v181
	v_pk_fma_f32 v[126:127], v[126:127], v[174:175], v[178:179]
	v_pk_fma_f32 v[124:125], v[124:125], v[182:183], v[186:187]
	v_pk_fma_f32 v[122:123], v[122:123], v[176:177], v[180:181]
	v_pk_fma_f32 v[120:121], v[120:121], v[184:185], v[188:189]
	s_cbranch_vccnz .LBB0_1965
	global_store_dwordx4 v[152:153], v[124:127], off
	global_store_dwordx4 v[152:153], v[120:123], off offset:16
	s_cbranch_execnz .LBB0_1917

; __device__ __forceinline__ unsigned pk2(float lo, float hi) { f32x2_t v = {lo, hi}; bf16x2_t b = __builtin_convertvector(v, bf16x2_t); return __builtin_bit_cast(unsigned, b); }
; #define BF16_LO(w) __uint_as_float((w) << 16)
; #define BF16_HI(w) __uint_as_float((w) & 0xffff0000u)
;     __device__ __forceinline__ void operator()(const f32x4 (&acc)[2][2][4][2], const Unit& u, int wr, int wc, int fr_in, int fq_in) const {
;     ...
;                 for (int bj = 0; bj < 2; ++bj) {
;                     const size_t off = (size_t)(u.pm * BM + ai * 128 + wr * 64 + m * 16 + fr) * DM + u.pn * BM + bj * HALF + wc * 32 + 8 * fq;
;                     const u32x4 s = *(const u32x4*)(SG + off), q = *(const u32x4*)(hb + off);
;                     const f32x4 s0 = {BF16_LO(s.x), BF16_HI(s.x), BF16_LO(s.y), BF16_HI(s.y)}, s1 = {BF16_LO(s.z), BF16_HI(s.z), BF16_LO(s.w), BF16_HI(s.w)};
;                     const f32x4 b0 = {BF16_LO(q.x), BF16_HI(q.x), BF16_LO(q.y), BF16_HI(q.y)}, b1 = {BF16_LO(q.z), BF16_HI(q.z), BF16_LO(q.w), BF16_HI(q.w)};
;                     const f32x4 h0 = b0 + acc[ai][bj][m][0] * s0, h1 = b1 + acc[ai][bj][m][1] * s1;
;                     if (outf) { *(f32x4*)(outf + off) = h0; *(f32x4*)(outf + off + 4) = h1; }
;                     else { u32x4 w; w.x = pk2(h0[0], h0[1]); w.y = pk2(h0[2], h0[3]); w.z = pk2(h1[0], h1[1]); w.w = pk2(h1[2], h1[3]); *(u32x4*)(hb + off) = w; }
.LBB0_1917:
	global_load_dwordx4 v[120:123], v[150:151], off offset:256 nt
	s_nop 0
	global_load_dwordx4 v[124:127], v[148:149], off offset:256 nt
	s_and_b64 vcc, exec, s[6:7]
	s_waitcnt vmcnt(0)
	v_lshlrev_b32_e32 v150, 16, v120
	v_and_b32_e32 v151, 0xffff0000, v120
	v_lshlrev_b32_e32 v120, 16, v121
	v_and_b32_e32 v121, 0xffff0000, v121
	v_lshlrev_b32_e32 v174, 16, v122
	v_and_b32_e32 v175, 0xffff0000, v122
	v_lshlrev_b32_e32 v122, 16, v123
	v_and_b32_e32 v123, 0xffff0000, v123
	v_lshlrev_b32_e32 v176, 16, v124
	v_and_b32_e32 v177, 0xffff0000, v124
	v_lshlrev_b32_e32 v124, 16, v125
	v_and_b32_e32 v125, 0xffff0000, v125
	v_lshlrev_b32_e32 v178, 16, v126
	v_and_b32_e32 v179, 0xffff0000, v126
	v_lshlrev_b32_e32 v126, 16, v127
	v_and_b32_e32 v127, 0xffff0000, v127
	v_pk_fma_f32 v[118:119], v[118:119], v[120:121], v[124:125]
	v_pk_fma_f32 v[116:117], v[116:117], v[150:151], v[176:177]
	v_pk_fma_f32 v[114:115], v[114:115], v[122:123], v[126:127]
	v_pk_fma_f32 v[112:113], v[112:113], v[174:175], v[178:179]
	s_cbranch_vccnz .LBB0_1966
	global_store_dwordx4 v[152:153], v[116:119], off offset:512
	global_store_dwordx4 v[152:153], v[112:115], off offset:528
	s_cbranch_execnz .LBB0_1920

; __device__ __forceinline__ unsigned pk2(float lo, float hi) { f32x2_t v = {lo, hi}; bf16x2_t b = __builtin_convertvector(v, bf16x2_t); return __builtin_bit_cast(unsigned, b); }
; #define BF16_LO(w) __uint_as_float((w) << 16)
; #define BF16_HI(w) __uint_as_float((w) & 0xffff0000u)
;     __device__ __forceinline__ void operator()(const f32x4 (&acc)[2][2][4][2], const Unit& u, int wr, int wc, int fr_in, int fq_in) const {
;     ...
;                 for (int bj = 0; bj < 2; ++bj) {
;                     const size_t off = (size_t)(u.pm * BM + ai * 128 + wr * 64 + m * 16 + fr) * DM + u.pn * BM + bj * HALF + wc * 32 + 8 * fq;
;                     const u32x4 s = *(const u32x4*)(SG + off), q = *(const u32x4*)(hb + off);
;                     const f32x4 s0 = {BF16_LO(s.x), BF16_HI(s.x), BF16_LO(s.y), BF16_HI(s.y)}, s1 = {BF16_LO(s.z), BF16_HI(s.z), BF16_LO(s.w), BF16_HI(s.w)};
;                     const f32x4 b0 = {BF16_LO(q.x), BF16_HI(q.x), BF16_LO(q.y), BF16_HI(q.y)}, b1 = {BF16_LO(q.z), BF16_HI(q.z), BF16_LO(q.w), BF16_HI(q.w)};
;                     const f32x4 h0 = b0 + acc[ai][bj][m][0] * s0, h1 = b1 + acc[ai][bj][m][1] * s1;
;                     if (outf) { *(f32x4*)(outf + off) = h0; *(f32x4*)(outf + off + 4) = h1; }
;                     else { u32x4 w; w.x = pk2(h0[0], h0[1]); w.y = pk2(h0[2], h0[3]); w.z = pk2(h1[0], h1[1]); w.w = pk2(h1[2], h1[3]); *(u32x4*)(hb + off) = w; }
.LBB0_1920:
	s_nop 0
	v_add_u32_e32 v112, 16, v144
	v_ashrrev_i32_e32 v113, 31, v112
	v_lshlrev_b64 v[112:113], 10, v[112:113]
	v_lshl_add_u64 v[114:115], v[112:113], 0, v[146:147]
	v_lshlrev_b64 v[112:113], 1, v[114:115]
	v_lshl_add_u64 v[116:117], s[8:9], 0, v[112:113]
	v_lshl_add_u64 v[112:113], s[18:19], 0, v[112:113]
	global_load_dwordx4 v[118:121], v[116:117], off nt
	global_load_dwordx4 v[122:125], v[112:113], off nt
	s_and_b64 vcc, exec, s[6:7]
	v_lshl_add_u64 v[114:115], v[114:115], 2, s[10:11]
	s_waitcnt vmcnt(0)
	v_lshlrev_b32_e32 v126, 16, v118
	v_and_b32_e32 v127, 0xffff0000, v118
	v_lshlrev_b32_e32 v118, 16, v119
	v_and_b32_e32 v119, 0xffff0000, v119
	v_lshlrev_b32_e32 v148, 16, v120
	v_and_b32_e32 v149, 0xffff0000, v120
	v_lshlrev_b32_e32 v120, 16, v121
	v_and_b32_e32 v121, 0xffff0000, v121
	v_lshlrev_b32_e32 v150, 16, v122
	v_and_b32_e32 v151, 0xffff0000, v122
	v_lshlrev_b32_e32 v122, 16, v123
	v_and_b32_e32 v123, 0xffff0000, v123
	v_lshlrev_b32_e32 v152, 16, v124
	v_and_b32_e32 v153, 0xffff0000, v124
	v_lshlrev_b32_e32 v124, 16, v125
	v_and_b32_e32 v125, 0xffff0000, v125
	v_pk_fma_f32 v[110:111], v[110:111], v[118:119], v[122:123]
	v_pk_fma_f32 v[108:109], v[108:109], v[126:127], v[150:151]
	v_pk_fma_f32 v[106:107], v[106:107], v[120:121], v[124:125]
	v_pk_fma_f32 v[104:105], v[104:105], v[148:149], v[152:153]
	s_cbranch_vccnz .LBB0_1967
	global_store_dwordx4 v[114:115], v[108:111], off
	global_store_dwordx4 v[114:115], v[104:107], off offset:16
	s_cbranch_execnz .LBB0_1923

; __device__ __forceinline__ unsigned pk2(float lo, float hi) { f32x2_t v = {lo, hi}; bf16x2_t b = __builtin_convertvector(v, bf16x2_t); return __builtin_bit_cast(unsigned, b); }
; #define BF16_LO(w) __uint_as_float((w) << 16)
; #define BF16_HI(w) __uint_as_float((w) & 0xffff0000u)
;     __device__ __forceinline__ void operator()(const f32x4 (&acc)[2][2][4][2], const Unit& u, int wr, int wc, int fr_in, int fq_in) const {
;     ...
;                 for (int bj = 0; bj < 2; ++bj) {
;                     const size_t off = (size_t)(u.pm * BM + ai * 128 + wr * 64 + m * 16 + fr) * DM + u.pn * BM + bj * HALF + wc * 32 + 8 * fq;
;                     const u32x4 s = *(const u32x4*)(SG + off), q = *(const u32x4*)(hb + off);
;                     const f32x4 s0 = {BF16_LO(s.x), BF16_HI(s.x), BF16_LO(s.y), BF16_HI(s.y)}, s1 = {BF16_LO(s.z), BF16_HI(s.z), BF16_LO(s.w), BF16_HI(s.w)};
;                     const f32x4 b0 = {BF16_LO(q.x), BF16_HI(q.x), BF16_LO(q.y), BF16_HI(q.y)}, b1 = {BF16_LO(q.z), BF16_HI(q.z), BF16_LO(q.w), BF16_HI(q.w)};
;                     const f32x4 h0 = b0 + acc[ai][bj][m][0] * s0, h1 = b1 + acc[ai][bj][m][1] * s1;
;                     if (outf) { *(f32x4*)(outf + off) = h0; *(f32x4*)(outf + off + 4) = h1; }
;                     else { u32x4 w; w.x = pk2(h0[0], h0[1]); w.y = pk2(h0[2], h0[3]); w.z = pk2(h1[0], h1[1]); w.w = pk2(h1[2], h1[3]); *(u32x4*)(hb + off) = w; }
.LBB0_1923:
	global_load_dwordx4 v[104:107], v[116:117], off offset:256 nt
	s_nop 0
	global_load_dwordx4 v[108:111], v[112:113], off offset:256 nt
	s_and_b64 vcc, exec, s[6:7]
	s_waitcnt vmcnt(0)
	v_lshlrev_b32_e32 v116, 16, v104
	v_and_b32_e32 v117, 0xffff0000, v104
	v_lshlrev_b32_e32 v104, 16, v105
	v_and_b32_e32 v105, 0xffff0000, v105
	v_lshlrev_b32_e32 v118, 16, v106
	v_and_b32_e32 v119, 0xffff0000, v106
	v_lshlrev_b32_e32 v106, 16, v107
	v_and_b32_e32 v107, 0xffff0000, v107
	v_lshlrev_b32_e32 v120, 16, v108
	v_and_b32_e32 v121, 0xffff0000, v108
	v_lshlrev_b32_e32 v108, 16, v109
	v_and_b32_e32 v109, 0xffff0000, v109
	v_lshlrev_b32_e32 v122, 16, v110
	v_and_b32_e32 v123, 0xffff0000, v110
	v_lshlrev_b32_e32 v110, 16, v111
	v_and_b32_e32 v111, 0xffff0000, v111
	v_pk_fma_f32 v[102:103], v[102:103], v[104:105], v[108:109]
	v_pk_fma_f32 v[100:101], v[100:101], v[116:117], v[120:121]
	v_pk_fma_f32 v[98:99], v[98:99], v[106:107], v[110:111]
	v_pk_fma_f32 v[96:97], v[96:97], v[118:119], v[122:123]
	s_cbranch_vccnz .LBB0_1968
	global_store_dwordx4 v[114:115], v[100:103], off offset:512
	global_store_dwordx4 v[114:115], v[96:99], off offset:528
	s_cbranch_execnz .LBB0_1926

; __device__ __forceinline__ unsigned pk2(float lo, float hi) { f32x2_t v = {lo, hi}; bf16x2_t b = __builtin_convertvector(v, bf16x2_t); return __builtin_bit_cast(unsigned, b); }
; #define BF16_LO(w) __uint_as_float((w) << 16)
; #define BF16_HI(w) __uint_as_float((w) & 0xffff0000u)
;     __device__ __forceinline__ void operator()(const f32x4 (&acc)[2][2][4][2], const Unit& u, int wr, int wc, int fr_in, int fq_in) const {
;     ...
;                 for (int bj = 0; bj < 2; ++bj) {
;                     const size_t off = (size_t)(u.pm * BM + ai * 128 + wr * 64 + m * 16 + fr) * DM + u.pn * BM + bj * HALF + wc * 32 + 8 * fq;
;                     const u32x4 s = *(const u32x4*)(SG + off), q = *(const u32x4*)(hb + off);
;                     const f32x4 s0 = {BF16_LO(s.x), BF16_HI(s.x), BF16_LO(s.y), BF16_HI(s.y)}, s1 = {BF16_LO(s.z), BF16_HI(s.z), BF16_LO(s.w), BF16_HI(s.w)};
;                     const f32x4 b0 = {BF16_LO(q.x), BF16_HI(q.x), BF16_LO(q.y), BF16_HI(q.y)}, b1 = {BF16_LO(q.z), BF16_HI(q.z), BF16_LO(q.w), BF16_HI(q.w)};
;                     const f32x4 h0 = b0 + acc[ai][bj][m][0] * s0, h1 = b1 + acc[ai][bj][m][1] * s1;
;                     if (outf) { *(f32x4*)(outf + off) = h0; *(f32x4*)(outf + off + 4) = h1; }
;                     else { u32x4 w; w.x = pk2(h0[0], h0[1]); w.y = pk2(h0[2], h0[3]); w.z = pk2(h1[0], h1[1]); w.w = pk2(h1[2], h1[3]); *(u32x4*)(hb + off) = w; }
.LBB0_1926:
	s_nop 0
	v_add_u32_e32 v96, 32, v144
	v_ashrrev_i32_e32 v97, 31, v96
	v_lshlrev_b64 v[96:97], 10, v[96:97]
	v_lshl_add_u64 v[98:99], v[96:97], 0, v[146:147]
	v_lshlrev_b64 v[96:97], 1, v[98:99]
	v_lshl_add_u64 v[100:101], s[8:9], 0, v[96:97]
	v_lshl_add_u64 v[96:97], s[18:19], 0, v[96:97]
	global_load_dwordx4 v[102:105], v[100:101], off nt
	global_load_dwordx4 v[106:109], v[96:97], off nt
	s_and_b64 vcc, exec, s[6:7]
	v_lshl_add_u64 v[98:99], v[98:99], 2, s[10:11]
	s_waitcnt vmcnt(0)
	v_lshlrev_b32_e32 v110, 16, v102
	v_and_b32_e32 v111, 0xffff0000, v102
	v_lshlrev_b32_e32 v102, 16, v103
	v_and_b32_e32 v103, 0xffff0000, v103
	v_lshlrev_b32_e32 v112, 16, v104
	v_and_b32_e32 v113, 0xffff0000, v104
	v_lshlrev_b32_e32 v104, 16, v105
	v_and_b32_e32 v105, 0xffff0000, v105
	v_lshlrev_b32_e32 v114, 16, v106
	v_and_b32_e32 v115, 0xffff0000, v106
	v_lshlrev_b32_e32 v106, 16, v107
	v_and_b32_e32 v107, 0xffff0000, v107
	v_lshlrev_b32_e32 v116, 16, v108
	v_and_b32_e32 v117, 0xffff0000, v108
	v_lshlrev_b32_e32 v108, 16, v109
	v_and_b32_e32 v109, 0xffff0000, v109
	v_pk_fma_f32 v[94:95], v[94:95], v[102:103], v[106:107]
	v_pk_fma_f32 v[92:93], v[92:93], v[110:111], v[114:115]
	v_pk_fma_f32 v[90:91], v[90:91], v[104:105], v[108:109]
	v_pk_fma_f32 v[88:89], v[88:89], v[112:113], v[116:117]
	s_cbranch_vccnz .LBB0_1969
	global_store_dwordx4 v[98:99], v[92:95], off
	global_store_dwordx4 v[98:99], v[88:91], off offset:16
	s_cbranch_execnz .LBB0_1929

; __device__ __forceinline__ unsigned pk2(float lo, float hi) { f32x2_t v = {lo, hi}; bf16x2_t b = __builtin_convertvector(v, bf16x2_t); return __builtin_bit_cast(unsigned, b); }
; #define BF16_LO(w) __uint_as_float((w) << 16)
; #define BF16_HI(w) __uint_as_float((w) & 0xffff0000u)
;     __device__ __forceinline__ void operator()(const f32x4 (&acc)[2][2][4][2], const Unit& u, int wr, int wc, int fr_in, int fq_in) const {
;     ...
;                 for (int bj = 0; bj < 2; ++bj) {
;                     const size_t off = (size_t)(u.pm * BM + ai * 128 + wr * 64 + m * 16 + fr) * DM + u.pn * BM + bj * HALF + wc * 32 + 8 * fq;
;                     const u32x4 s = *(const u32x4*)(SG + off), q = *(const u32x4*)(hb + off);
;                     const f32x4 s0 = {BF16_LO(s.x), BF16_HI(s.x), BF16_LO(s.y), BF16_HI(s.y)}, s1 = {BF16_LO(s.z), BF16_HI(s.z), BF16_LO(s.w), BF16_HI(s.w)};
;                     const f32x4 b0 = {BF16_LO(q.x), BF16_HI(q.x), BF16_LO(q.y), BF16_HI(q.y)}, b1 = {BF16_LO(q.z), BF16_HI(q.z), BF16_LO(q.w), BF16_HI(q.w)};
;                     const f32x4 h0 = b0 + acc[ai][bj][m][0] * s0, h1 = b1 + acc[ai][bj][m][1] * s1;
;                     if (outf) { *(f32x4*)(outf + off) = h0; *(f32x4*)(outf + off + 4) = h1; }
;                     else { u32x4 w; w.x = pk2(h0[0], h0[1]); w.y = pk2(h0[2], h0[3]); w.z = pk2(h1[0], h1[1]); w.w = pk2(h1[2], h1[3]); *(u32x4*)(hb + off) = w; }
.LBB0_1929:
	global_load_dwordx4 v[88:91], v[100:101], off offset:256 nt
	s_nop 0
	global_load_dwordx4 v[92:95], v[96:97], off offset:256 nt
	s_and_b64 vcc, exec, s[6:7]
	s_waitcnt vmcnt(0)
	v_lshlrev_b32_e32 v100, 16, v88
	v_and_b32_e32 v101, 0xffff0000, v88
	v_lshlrev_b32_e32 v88, 16, v89
	v_and_b32_e32 v89, 0xffff0000, v89
	v_lshlrev_b32_e32 v102, 16, v90
	v_and_b32_e32 v103, 0xffff0000, v90
	v_lshlrev_b32_e32 v90, 16, v91
	v_and_b32_e32 v91, 0xffff0000, v91
	v_lshlrev_b32_e32 v104, 16, v92
	v_and_b32_e32 v105, 0xffff0000, v92
	v_lshlrev_b32_e32 v92, 16, v93
	v_and_b32_e32 v93, 0xffff0000, v93
	v_lshlrev_b32_e32 v106, 16, v94
	v_and_b32_e32 v107, 0xffff0000, v94
	v_lshlrev_b32_e32 v94, 16, v95
	v_and_b32_e32 v95, 0xffff0000, v95
	v_pk_fma_f32 v[86:87], v[86:87], v[88:89], v[92:93]
	v_pk_fma_f32 v[84:85], v[84:85], v[100:101], v[104:105]
	v_pk_fma_f32 v[82:83], v[82:83], v[90:91], v[94:95]
	v_pk_fma_f32 v[80:81], v[80:81], v[102:103], v[106:107]
	s_cbranch_vccnz .LBB0_1970
	global_store_dwordx4 v[98:99], v[84:87], off offset:512
	global_store_dwordx4 v[98:99], v[80:83], off offset:528
	s_cbranch_execnz .LBB0_1932

; __device__ __forceinline__ unsigned pk2(float lo, float hi) { f32x2_t v = {lo, hi}; bf16x2_t b = __builtin_convertvector(v, bf16x2_t); return __builtin_bit_cast(unsigned, b); }
; #define BF16_LO(w) __uint_as_float((w) << 16)
; #define BF16_HI(w) __uint_as_float((w) & 0xffff0000u)
;     __device__ __forceinline__ void operator()(const f32x4 (&acc)[2][2][4][2], const Unit& u, int wr, int wc, int fr_in, int fq_in) const {
;     ...
;                 for (int bj = 0; bj < 2; ++bj) {
;                     const size_t off = (size_t)(u.pm * BM + ai * 128 + wr * 64 + m * 16 + fr) * DM + u.pn * BM + bj * HALF + wc * 32 + 8 * fq;
;                     const u32x4 s = *(const u32x4*)(SG + off), q = *(const u32x4*)(hb + off);
;                     const f32x4 s0 = {BF16_LO(s.x), BF16_HI(s.x), BF16_LO(s.y), BF16_HI(s.y)}, s1 = {BF16_LO(s.z), BF16_HI(s.z), BF16_LO(s.w), BF16_HI(s.w)};
;                     const f32x4 b0 = {BF16_LO(q.x), BF16_HI(q.x), BF16_LO(q.y), BF16_HI(q.y)}, b1 = {BF16_LO(q.z), BF16_HI(q.z), BF16_LO(q.w), BF16_HI(q.w)};
;                     const f32x4 h0 = b0 + acc[ai][bj][m][0] * s0, h1 = b1 + acc[ai][bj][m][1] * s1;
;                     if (outf) { *(f32x4*)(outf + off) = h0; *(f32x4*)(outf + off + 4) = h1; }
;                     else { u32x4 w; w.x = pk2(h0[0], h0[1]); w.y = pk2(h0[2], h0[3]); w.z = pk2(h1[0], h1[1]); w.w = pk2(h1[2], h1[3]); *(u32x4*)(hb + off) = w; }
.LBB0_1932:
	s_nop 0
	v_add_u32_e32 v80, 48, v144
	v_ashrrev_i32_e32 v81, 31, v80
	v_lshlrev_b64 v[80:81], 10, v[80:81]
	v_lshl_add_u64 v[82:83], v[80:81], 0, v[146:147]
	v_lshlrev_b64 v[80:81], 1, v[82:83]
	v_lshl_add_u64 v[84:85], s[8:9], 0, v[80:81]
	v_lshl_add_u64 v[80:81], s[18:19], 0, v[80:81]
	global_load_dwordx4 v[86:89], v[84:85], off nt
	global_load_dwordx4 v[90:93], v[80:81], off nt
	s_and_b64 vcc, exec, s[6:7]
	v_lshl_add_u64 v[82:83], v[82:83], 2, s[10:11]
	s_waitcnt vmcnt(0)
	v_lshlrev_b32_e32 v94, 16, v86
	v_and_b32_e32 v95, 0xffff0000, v86
	v_lshlrev_b32_e32 v86, 16, v87
	v_and_b32_e32 v87, 0xffff0000, v87
	v_lshlrev_b32_e32 v96, 16, v88
	v_and_b32_e32 v97, 0xffff0000, v88
	v_lshlrev_b32_e32 v88, 16, v89
	v_and_b32_e32 v89, 0xffff0000, v89
	v_lshlrev_b32_e32 v98, 16, v90
	v_and_b32_e32 v99, 0xffff0000, v90
	v_lshlrev_b32_e32 v90, 16, v91
	v_and_b32_e32 v91, 0xffff0000, v91
	v_lshlrev_b32_e32 v100, 16, v92
	v_and_b32_e32 v101, 0xffff0000, v92
	v_lshlrev_b32_e32 v92, 16, v93
	v_and_b32_e32 v93, 0xffff0000, v93
	v_pk_fma_f32 v[78:79], v[78:79], v[86:87], v[90:91]
	v_pk_fma_f32 v[76:77], v[76:77], v[94:95], v[98:99]
	v_pk_fma_f32 v[74:75], v[74:75], v[88:89], v[92:93]
	v_pk_fma_f32 v[72:73], v[72:73], v[96:97], v[100:101]
	s_cbranch_vccnz .LBB0_1971
	global_store_dwordx4 v[82:83], v[76:79], off
	global_store_dwordx4 v[82:83], v[72:75], off offset:16
	s_cbranch_execnz .LBB0_1935

; __device__ __forceinline__ unsigned pk2(float lo, float hi) { f32x2_t v = {lo, hi}; bf16x2_t b = __builtin_convertvector(v, bf16x2_t); return __builtin_bit_cast(unsigned, b); }
; #define BF16_LO(w) __uint_as_float((w) << 16)
; #define BF16_HI(w) __uint_as_float((w) & 0xffff0000u)
;     __device__ __forceinline__ void operator()(const f32x4 (&acc)[2][2][4][2], const Unit& u, int wr, int wc, int fr_in, int fq_in) const {
;     ...
;                 for (int bj = 0; bj < 2; ++bj) {
;                     const size_t off = (size_t)(u.pm * BM + ai * 128 + wr * 64 + m * 16 + fr) * DM + u.pn * BM + bj * HALF + wc * 32 + 8 * fq;
;                     const u32x4 s = *(const u32x4*)(SG + off), q = *(const u32x4*)(hb + off);
;                     const f32x4 s0 = {BF16_LO(s.x), BF16_HI(s.x), BF16_LO(s.y), BF16_HI(s.y)}, s1 = {BF16_LO(s.z), BF16_HI(s.z), BF16_LO(s.w), BF16_HI(s.w)};
;                     const f32x4 b0 = {BF16_LO(q.x), BF16_HI(q.x), BF16_LO(q.y), BF16_HI(q.y)}, b1 = {BF16_LO(q.z), BF16_HI(q.z), BF16_LO(q.w), BF16_HI(q.w)};
;                     const f32x4 h0 = b0 + acc[ai][bj][m][0] * s0, h1 = b1 + acc[ai][bj][m][1] * s1;
;                     if (outf) { *(f32x4*)(outf + off) = h0; *(f32x4*)(outf + off + 4) = h1; }
;                     else { u32x4 w; w.x = pk2(h0[0], h0[1]); w.y = pk2(h0[2], h0[3]); w.z = pk2(h1[0], h1[1]); w.w = pk2(h1[2], h1[3]); *(u32x4*)(hb + off) = w; }
.LBB0_1935:
	global_load_dwordx4 v[72:75], v[84:85], off offset:256 nt
	s_nop 0
	global_load_dwordx4 v[76:79], v[80:81], off offset:256 nt
	s_and_b64 vcc, exec, s[6:7]
	s_waitcnt vmcnt(0)
	v_lshlrev_b32_e32 v84, 16, v72
	v_and_b32_e32 v85, 0xffff0000, v72
	v_lshlrev_b32_e32 v72, 16, v73
	v_and_b32_e32 v73, 0xffff0000, v73
	v_lshlrev_b32_e32 v86, 16, v74
	v_and_b32_e32 v87, 0xffff0000, v74
	v_lshlrev_b32_e32 v74, 16, v75
	v_and_b32_e32 v75, 0xffff0000, v75
	v_lshlrev_b32_e32 v88, 16, v76
	v_and_b32_e32 v89, 0xffff0000, v76
	v_lshlrev_b32_e32 v76, 16, v77
	v_and_b32_e32 v77, 0xffff0000, v77
	v_lshlrev_b32_e32 v90, 16, v78
	v_and_b32_e32 v91, 0xffff0000, v78
	v_lshlrev_b32_e32 v78, 16, v79
	v_and_b32_e32 v79, 0xffff0000, v79
	v_pk_fma_f32 v[70:71], v[70:71], v[72:73], v[76:77]
	v_pk_fma_f32 v[68:69], v[68:69], v[84:85], v[88:89]
	v_pk_fma_f32 v[66:67], v[66:67], v[74:75], v[78:79]
	v_pk_fma_f32 v[64:65], v[64:65], v[86:87], v[90:91]
	s_cbranch_vccnz .LBB0_1972
	global_store_dwordx4 v[82:83], v[68:71], off offset:512
	global_store_dwordx4 v[82:83], v[64:67], off offset:528
	s_cbranch_execnz .LBB0_1938

; __device__ __forceinline__ unsigned pk2(float lo, float hi) { f32x2_t v = {lo, hi}; bf16x2_t b = __builtin_convertvector(v, bf16x2_t); return __builtin_bit_cast(unsigned, b); }
; #define BF16_LO(w) __uint_as_float((w) << 16)
; #define BF16_HI(w) __uint_as_float((w) & 0xffff0000u)
;     __device__ __forceinline__ void operator()(const f32x4 (&acc)[2][2][4][2], const Unit& u, int wr, int wc, int fr_in, int fq_in) const {
;     ...
;                 for (int bj = 0; bj < 2; ++bj) {
;                     const size_t off = (size_t)(u.pm * BM + ai * 128 + wr * 64 + m * 16 + fr) * DM + u.pn * BM + bj * HALF + wc * 32 + 8 * fq;
;                     const u32x4 s = *(const u32x4*)(SG + off), q = *(const u32x4*)(hb + off);
;                     const f32x4 s0 = {BF16_LO(s.x), BF16_HI(s.x), BF16_LO(s.y), BF16_HI(s.y)}, s1 = {BF16_LO(s.z), BF16_HI(s.z), BF16_LO(s.w), BF16_HI(s.w)};
;                     const f32x4 b0 = {BF16_LO(q.x), BF16_HI(q.x), BF16_LO(q.y), BF16_HI(q.y)}, b1 = {BF16_LO(q.z), BF16_HI(q.z), BF16_LO(q.w), BF16_HI(q.w)};
;                     const f32x4 h0 = b0 + acc[ai][bj][m][0] * s0, h1 = b1 + acc[ai][bj][m][1] * s1;
;                     if (outf) { *(f32x4*)(outf + off) = h0; *(f32x4*)(outf + off + 4) = h1; }
;                     else { u32x4 w; w.x = pk2(h0[0], h0[1]); w.y = pk2(h0[2], h0[3]); w.z = pk2(h1[0], h1[1]); w.w = pk2(h1[2], h1[3]); *(u32x4*)(hb + off) = w; }
.LBB0_1938:
	s_nop 0
	v_add_u32_e32 v64, 0x80, v144
	v_ashrrev_i32_e32 v65, 31, v64
	v_lshlrev_b64 v[64:65], 10, v[64:65]
	v_lshl_add_u64 v[66:67], v[64:65], 0, v[146:147]
	v_lshlrev_b64 v[64:65], 1, v[66:67]
	v_lshl_add_u64 v[68:69], s[8:9], 0, v[64:65]
	v_lshl_add_u64 v[64:65], s[18:19], 0, v[64:65]
	global_load_dwordx4 v[70:73], v[68:69], off nt
	global_load_dwordx4 v[74:77], v[64:65], off nt
	s_and_b64 vcc, exec, s[6:7]
	v_lshl_add_u64 v[66:67], v[66:67], 2, s[10:11]
	s_waitcnt vmcnt(0)
	v_lshlrev_b32_e32 v78, 16, v70
	v_and_b32_e32 v79, 0xffff0000, v70
	v_lshlrev_b32_e32 v70, 16, v71
	v_and_b32_e32 v71, 0xffff0000, v71
	v_lshlrev_b32_e32 v80, 16, v72
	v_and_b32_e32 v81, 0xffff0000, v72
	v_lshlrev_b32_e32 v72, 16, v73
	v_and_b32_e32 v73, 0xffff0000, v73
	v_lshlrev_b32_e32 v82, 16, v74
	v_and_b32_e32 v83, 0xffff0000, v74
	v_lshlrev_b32_e32 v74, 16, v75
	v_and_b32_e32 v75, 0xffff0000, v75
	v_lshlrev_b32_e32 v84, 16, v76
	v_and_b32_e32 v85, 0xffff0000, v76
	v_lshlrev_b32_e32 v76, 16, v77
	v_and_b32_e32 v77, 0xffff0000, v77
	v_pk_fma_f32 v[62:63], v[62:63], v[70:71], v[74:75]
	v_pk_fma_f32 v[60:61], v[60:61], v[78:79], v[82:83]
	v_pk_fma_f32 v[58:59], v[58:59], v[72:73], v[76:77]
	v_pk_fma_f32 v[56:57], v[56:57], v[80:81], v[84:85]
	s_cbranch_vccnz .LBB0_1973
	global_store_dwordx4 v[66:67], v[60:63], off
	global_store_dwordx4 v[66:67], v[56:59], off offset:16
	s_cbranch_execnz .LBB0_1941

; __device__ __forceinline__ unsigned pk2(float lo, float hi) { f32x2_t v = {lo, hi}; bf16x2_t b = __builtin_convertvector(v, bf16x2_t); return __builtin_bit_cast(unsigned, b); }
; #define BF16_LO(w) __uint_as_float((w) << 16)
; #define BF16_HI(w) __uint_as_float((w) & 0xffff0000u)
;     __device__ __forceinline__ void operator()(const f32x4 (&acc)[2][2][4][2], const Unit& u, int wr, int wc, int fr_in, int fq_in) const {
;     ...
;                 for (int bj = 0; bj < 2; ++bj) {
;                     const size_t off = (size_t)(u.pm * BM + ai * 128 + wr * 64 + m * 16 + fr) * DM + u.pn * BM + bj * HALF + wc * 32 + 8 * fq;
;                     const u32x4 s = *(const u32x4*)(SG + off), q = *(const u32x4*)(hb + off);
;                     const f32x4 s0 = {BF16_LO(s.x), BF16_HI(s.x), BF16_LO(s.y), BF16_HI(s.y)}, s1 = {BF16_LO(s.z), BF16_HI(s.z), BF16_LO(s.w), BF16_HI(s.w)};
;                     const f32x4 b0 = {BF16_LO(q.x), BF16_HI(q.x), BF16_LO(q.y), BF16_HI(q.y)}, b1 = {BF16_LO(q.z), BF16_HI(q.z), BF16_LO(q.w), BF16_HI(q.w)};
;                     const f32x4 h0 = b0 + acc[ai][bj][m][0] * s0, h1 = b1 + acc[ai][bj][m][1] * s1;
;                     if (outf) { *(f32x4*)(outf + off) = h0; *(f32x4*)(outf + off + 4) = h1; }
;                     else { u32x4 w; w.x = pk2(h0[0], h0[1]); w.y = pk2(h0[2], h0[3]); w.z = pk2(h1[0], h1[1]); w.w = pk2(h1[2], h1[3]); *(u32x4*)(hb + off) = w; }
.LBB0_1941:
	global_load_dwordx4 v[56:59], v[68:69], off offset:256 nt
	s_nop 0
	global_load_dwordx4 v[60:63], v[64:65], off offset:256 nt
	s_and_b64 vcc, exec, s[6:7]
	s_waitcnt vmcnt(0)
	v_lshlrev_b32_e32 v68, 16, v56
	v_and_b32_e32 v69, 0xffff0000, v56
	v_lshlrev_b32_e32 v56, 16, v57
	v_and_b32_e32 v57, 0xffff0000, v57
	v_lshlrev_b32_e32 v70, 16, v58
	v_and_b32_e32 v71, 0xffff0000, v58
	v_lshlrev_b32_e32 v58, 16, v59
	v_and_b32_e32 v59, 0xffff0000, v59
	v_lshlrev_b32_e32 v72, 16, v60
	v_and_b32_e32 v73, 0xffff0000, v60
	v_lshlrev_b32_e32 v60, 16, v61
	v_and_b32_e32 v61, 0xffff0000, v61
	v_lshlrev_b32_e32 v74, 16, v62
	v_and_b32_e32 v75, 0xffff0000, v62
	v_lshlrev_b32_e32 v62, 16, v63
	v_and_b32_e32 v63, 0xffff0000, v63
	v_pk_fma_f32 v[54:55], v[54:55], v[56:57], v[60:61]
	v_pk_fma_f32 v[52:53], v[52:53], v[68:69], v[72:73]
	v_pk_fma_f32 v[50:51], v[50:51], v[58:59], v[62:63]
	v_pk_fma_f32 v[48:49], v[48:49], v[70:71], v[74:75]
	s_cbranch_vccnz .LBB0_1974
	global_store_dwordx4 v[66:67], v[52:55], off offset:512
	global_store_dwordx4 v[66:67], v[48:51], off offset:528
	s_cbranch_execnz .LBB0_1944

; __device__ __forceinline__ unsigned pk2(float lo, float hi) { f32x2_t v = {lo, hi}; bf16x2_t b = __builtin_convertvector(v, bf16x2_t); return __builtin_bit_cast(unsigned, b); }
; #define BF16_LO(w) __uint_as_float((w) << 16)
; #define BF16_HI(w) __uint_as_float((w) & 0xffff0000u)
;     __device__ __forceinline__ void operator()(const f32x4 (&acc)[2][2][4][2], const Unit& u, int wr, int wc, int fr_in, int fq_in) const {
;     ...
;                 for (int bj = 0; bj < 2; ++bj) {
;                     const size_t off = (size_t)(u.pm * BM + ai * 128 + wr * 64 + m * 16 + fr) * DM + u.pn * BM + bj * HALF + wc * 32 + 8 * fq;
;                     const u32x4 s = *(const u32x4*)(SG + off), q = *(const u32x4*)(hb + off);
;                     const f32x4 s0 = {BF16_LO(s.x), BF16_HI(s.x), BF16_LO(s.y), BF16_HI(s.y)}, s1 = {BF16_LO(s.z), BF16_HI(s.z), BF16_LO(s.w), BF16_HI(s.w)};
;                     const f32x4 b0 = {BF16_LO(q.x), BF16_HI(q.x), BF16_LO(q.y), BF16_HI(q.y)}, b1 = {BF16_LO(q.z), BF16_HI(q.z), BF16_LO(q.w), BF16_HI(q.w)};
;                     const f32x4 h0 = b0 + acc[ai][bj][m][0] * s0, h1 = b1 + acc[ai][bj][m][1] * s1;
;                     if (outf) { *(f32x4*)(outf + off) = h0; *(f32x4*)(outf + off + 4) = h1; }
;                     else { u32x4 w; w.x = pk2(h0[0], h0[1]); w.y = pk2(h0[2], h0[3]); w.z = pk2(h1[0], h1[1]); w.w = pk2(h1[2], h1[3]); *(u32x4*)(hb + off) = w; }
.LBB0_1944:
	s_nop 0
	v_add_u32_e32 v48, 0x90, v144
	v_ashrrev_i32_e32 v49, 31, v48
	v_lshlrev_b64 v[48:49], 10, v[48:49]
	v_lshl_add_u64 v[50:51], v[48:49], 0, v[146:147]
	v_lshlrev_b64 v[48:49], 1, v[50:51]
	v_lshl_add_u64 v[52:53], s[8:9], 0, v[48:49]
	v_lshl_add_u64 v[48:49], s[18:19], 0, v[48:49]
	global_load_dwordx4 v[54:57], v[52:53], off nt
	global_load_dwordx4 v[58:61], v[48:49], off nt
	s_and_b64 vcc, exec, s[6:7]
	v_lshl_add_u64 v[50:51], v[50:51], 2, s[10:11]
	s_waitcnt vmcnt(0)
	v_lshlrev_b32_e32 v62, 16, v54
	v_and_b32_e32 v63, 0xffff0000, v54
	v_lshlrev_b32_e32 v54, 16, v55
	v_and_b32_e32 v55, 0xffff0000, v55
	v_lshlrev_b32_e32 v64, 16, v56
	v_and_b32_e32 v65, 0xffff0000, v56
	v_lshlrev_b32_e32 v56, 16, v57
	v_and_b32_e32 v57, 0xffff0000, v57
	v_lshlrev_b32_e32 v66, 16, v58
	v_and_b32_e32 v67, 0xffff0000, v58
	v_lshlrev_b32_e32 v58, 16, v59
	v_and_b32_e32 v59, 0xffff0000, v59
	v_lshlrev_b32_e32 v68, 16, v60
	v_and_b32_e32 v69, 0xffff0000, v60
	v_lshlrev_b32_e32 v60, 16, v61
	v_and_b32_e32 v61, 0xffff0000, v61
	v_pk_fma_f32 v[46:47], v[46:47], v[54:55], v[58:59]
	v_pk_fma_f32 v[44:45], v[44:45], v[62:63], v[66:67]
	v_pk_fma_f32 v[42:43], v[42:43], v[56:57], v[60:61]
	v_pk_fma_f32 v[40:41], v[40:41], v[64:65], v[68:69]
	s_cbranch_vccnz .LBB0_1975
	global_store_dwordx4 v[50:51], v[44:47], off
	global_store_dwordx4 v[50:51], v[40:43], off offset:16
	s_cbranch_execnz .LBB0_1947

; __device__ __forceinline__ unsigned pk2(float lo, float hi) { f32x2_t v = {lo, hi}; bf16x2_t b = __builtin_convertvector(v, bf16x2_t); return __builtin_bit_cast(unsigned, b); }
; #define BF16_LO(w) __uint_as_float((w) << 16)
; #define BF16_HI(w) __uint_as_float((w) & 0xffff0000u)
;     __device__ __forceinline__ void operator()(const f32x4 (&acc)[2][2][4][2], const Unit& u, int wr, int wc, int fr_in, int fq_in) const {
;     ...
;                 for (int bj = 0; bj < 2; ++bj) {
;                     const size_t off = (size_t)(u.pm * BM + ai * 128 + wr * 64 + m * 16 + fr) * DM + u.pn * BM + bj * HALF + wc * 32 + 8 * fq;
;                     const u32x4 s = *(const u32x4*)(SG + off), q = *(const u32x4*)(hb + off);
;                     const f32x4 s0 = {BF16_LO(s.x), BF16_HI(s.x), BF16_LO(s.y), BF16_HI(s.y)}, s1 = {BF16_LO(s.z), BF16_HI(s.z), BF16_LO(s.w), BF16_HI(s.w)};
;                     const f32x4 b0 = {BF16_LO(q.x), BF16_HI(q.x), BF16_LO(q.y), BF16_HI(q.y)}, b1 = {BF16_LO(q.z), BF16_HI(q.z), BF16_LO(q.w), BF16_HI(q.w)};
;                     const f32x4 h0 = b0 + acc[ai][bj][m][0] * s0, h1 = b1 + acc[ai][bj][m][1] * s1;
;                     if (outf) { *(f32x4*)(outf + off) = h0; *(f32x4*)(outf + off + 4) = h1; }
;                     else { u32x4 w; w.x = pk2(h0[0], h0[1]); w.y = pk2(h0[2], h0[3]); w.z = pk2(h1[0], h1[1]); w.w = pk2(h1[2], h1[3]); *(u32x4*)(hb + off) = w; }
.LBB0_1947:
	global_load_dwordx4 v[40:43], v[52:53], off offset:256 nt
	s_nop 0
	global_load_dwordx4 v[44:47], v[48:49], off offset:256 nt
	s_and_b64 vcc, exec, s[6:7]
	s_waitcnt vmcnt(0)
	v_lshlrev_b32_e32 v52, 16, v40
	v_and_b32_e32 v53, 0xffff0000, v40
	v_lshlrev_b32_e32 v40, 16, v41
	v_and_b32_e32 v41, 0xffff0000, v41
	v_lshlrev_b32_e32 v54, 16, v42
	v_and_b32_e32 v55, 0xffff0000, v42
	v_lshlrev_b32_e32 v42, 16, v43
	v_and_b32_e32 v43, 0xffff0000, v43
	v_lshlrev_b32_e32 v56, 16, v44
	v_and_b32_e32 v57, 0xffff0000, v44
	v_lshlrev_b32_e32 v44, 16, v45
	v_and_b32_e32 v45, 0xffff0000, v45
	v_lshlrev_b32_e32 v58, 16, v46
	v_and_b32_e32 v59, 0xffff0000, v46
	v_lshlrev_b32_e32 v46, 16, v47
	v_and_b32_e32 v47, 0xffff0000, v47
	v_pk_fma_f32 v[38:39], v[38:39], v[40:41], v[44:45]
	v_pk_fma_f32 v[36:37], v[36:37], v[52:53], v[56:57]
	v_pk_fma_f32 v[34:35], v[34:35], v[42:43], v[46:47]
	v_pk_fma_f32 v[32:33], v[32:33], v[54:55], v[58:59]
	s_cbranch_vccnz .LBB0_1976
	global_store_dwordx4 v[50:51], v[36:39], off offset:512
	global_store_dwordx4 v[50:51], v[32:35], off offset:528
	s_cbranch_execnz .LBB0_1950

; __device__ __forceinline__ unsigned pk2(float lo, float hi) { f32x2_t v = {lo, hi}; bf16x2_t b = __builtin_convertvector(v, bf16x2_t); return __builtin_bit_cast(unsigned, b); }
; #define BF16_LO(w) __uint_as_float((w) << 16)
; #define BF16_HI(w) __uint_as_float((w) & 0xffff0000u)
;     __device__ __forceinline__ void operator()(const f32x4 (&acc)[2][2][4][2], const Unit& u, int wr, int wc, int fr_in, int fq_in) const {
;     ...
;                 for (int bj = 0; bj < 2; ++bj) {
;                     const size_t off = (size_t)(u.pm * BM + ai * 128 + wr * 64 + m * 16 + fr) * DM + u.pn * BM + bj * HALF + wc * 32 + 8 * fq;
;                     const u32x4 s = *(const u32x4*)(SG + off), q = *(const u32x4*)(hb + off);
;                     const f32x4 s0 = {BF16_LO(s.x), BF16_HI(s.x), BF16_LO(s.y), BF16_HI(s.y)}, s1 = {BF16_LO(s.z), BF16_HI(s.z), BF16_LO(s.w), BF16_HI(s.w)};
;                     const f32x4 b0 = {BF16_LO(q.x), BF16_HI(q.x), BF16_LO(q.y), BF16_HI(q.y)}, b1 = {BF16_LO(q.z), BF16_HI(q.z), BF16_LO(q.w), BF16_HI(q.w)};
;                     const f32x4 h0 = b0 + acc[ai][bj][m][0] * s0, h1 = b1 + acc[ai][bj][m][1] * s1;
;                     if (outf) { *(f32x4*)(outf + off) = h0; *(f32x4*)(outf + off + 4) = h1; }
;                     else { u32x4 w; w.x = pk2(h0[0], h0[1]); w.y = pk2(h0[2], h0[3]); w.z = pk2(h1[0], h1[1]); w.w = pk2(h1[2], h1[3]); *(u32x4*)(hb + off) = w; }
.LBB0_1950:
	s_nop 0
	v_add_u32_e32 v32, 0xa0, v144
	v_ashrrev_i32_e32 v33, 31, v32
	v_lshlrev_b64 v[32:33], 10, v[32:33]
	v_lshl_add_u64 v[34:35], v[32:33], 0, v[146:147]
	v_lshlrev_b64 v[32:33], 1, v[34:35]
	v_lshl_add_u64 v[36:37], s[8:9], 0, v[32:33]
	v_lshl_add_u64 v[32:33], s[18:19], 0, v[32:33]
	global_load_dwordx4 v[38:41], v[36:37], off nt
	global_load_dwordx4 v[42:45], v[32:33], off nt
	s_and_b64 vcc, exec, s[6:7]
	v_lshl_add_u64 v[34:35], v[34:35], 2, s[10:11]
	s_waitcnt vmcnt(0)
	v_lshlrev_b32_e32 v46, 16, v38
	v_and_b32_e32 v47, 0xffff0000, v38
	v_lshlrev_b32_e32 v38, 16, v39
	v_and_b32_e32 v39, 0xffff0000, v39
	v_lshlrev_b32_e32 v48, 16, v40
	v_and_b32_e32 v49, 0xffff0000, v40
	v_lshlrev_b32_e32 v40, 16, v41
	v_and_b32_e32 v41, 0xffff0000, v41
	v_lshlrev_b32_e32 v50, 16, v42
	v_and_b32_e32 v51, 0xffff0000, v42
	v_lshlrev_b32_e32 v42, 16, v43
	v_and_b32_e32 v43, 0xffff0000, v43
	v_lshlrev_b32_e32 v52, 16, v44
	v_and_b32_e32 v53, 0xffff0000, v44
	v_lshlrev_b32_e32 v44, 16, v45
	v_and_b32_e32 v45, 0xffff0000, v45
	v_pk_fma_f32 v[30:31], v[30:31], v[38:39], v[42:43]
	v_pk_fma_f32 v[28:29], v[28:29], v[46:47], v[50:51]
	v_pk_fma_f32 v[26:27], v[26:27], v[40:41], v[44:45]
	v_pk_fma_f32 v[24:25], v[24:25], v[48:49], v[52:53]
	s_cbranch_vccnz .LBB0_1977
	global_store_dwordx4 v[34:35], v[28:31], off
	global_store_dwordx4 v[34:35], v[24:27], off offset:16
	s_cbranch_execnz .LBB0_1953

; __device__ __forceinline__ unsigned pk2(float lo, float hi) { f32x2_t v = {lo, hi}; bf16x2_t b = __builtin_convertvector(v, bf16x2_t); return __builtin_bit_cast(unsigned, b); }
; #define BF16_LO(w) __uint_as_float((w) << 16)
; #define BF16_HI(w) __uint_as_float((w) & 0xffff0000u)
;     __device__ __forceinline__ void operator()(const f32x4 (&acc)[2][2][4][2], const Unit& u, int wr, int wc, int fr_in, int fq_in) const {
;     ...
;                 for (int bj = 0; bj < 2; ++bj) {
;                     const size_t off = (size_t)(u.pm * BM + ai * 128 + wr * 64 + m * 16 + fr) * DM + u.pn * BM + bj * HALF + wc * 32 + 8 * fq;
;                     const u32x4 s = *(const u32x4*)(SG + off), q = *(const u32x4*)(hb + off);
;                     const f32x4 s0 = {BF16_LO(s.x), BF16_HI(s.x), BF16_LO(s.y), BF16_HI(s.y)}, s1 = {BF16_LO(s.z), BF16_HI(s.z), BF16_LO(s.w), BF16_HI(s.w)};
;                     const f32x4 b0 = {BF16_LO(q.x), BF16_HI(q.x), BF16_LO(q.y), BF16_HI(q.y)}, b1 = {BF16_LO(q.z), BF16_HI(q.z), BF16_LO(q.w), BF16_HI(q.w)};
;                     const f32x4 h0 = b0 + acc[ai][bj][m][0] * s0, h1 = b1 + acc[ai][bj][m][1] * s1;
;                     if (outf) { *(f32x4*)(outf + off) = h0; *(f32x4*)(outf + off + 4) = h1; }
;                     else { u32x4 w; w.x = pk2(h0[0], h0[1]); w.y = pk2(h0[2], h0[3]); w.z = pk2(h1[0], h1[1]); w.w = pk2(h1[2], h1[3]); *(u32x4*)(hb + off) = w; }
.LBB0_1953:
	global_load_dwordx4 v[24:27], v[36:37], off offset:256 nt
	s_nop 0
	global_load_dwordx4 v[28:31], v[32:33], off offset:256 nt
	s_and_b64 vcc, exec, s[6:7]
	s_waitcnt vmcnt(0)
	v_lshlrev_b32_e32 v36, 16, v24
	v_and_b32_e32 v37, 0xffff0000, v24
	v_lshlrev_b32_e32 v24, 16, v25
	v_and_b32_e32 v25, 0xffff0000, v25
	v_lshlrev_b32_e32 v38, 16, v26
	v_and_b32_e32 v39, 0xffff0000, v26
	v_lshlrev_b32_e32 v26, 16, v27
	v_and_b32_e32 v27, 0xffff0000, v27
	v_lshlrev_b32_e32 v40, 16, v28
	v_and_b32_e32 v41, 0xffff0000, v28
	v_lshlrev_b32_e32 v28, 16, v29
	v_and_b32_e32 v29, 0xffff0000, v29
	v_lshlrev_b32_e32 v42, 16, v30
	v_and_b32_e32 v43, 0xffff0000, v30
	v_lshlrev_b32_e32 v30, 16, v31
	v_and_b32_e32 v31, 0xffff0000, v31
	v_pk_fma_f32 v[22:23], v[22:23], v[24:25], v[28:29]
	v_pk_fma_f32 v[20:21], v[20:21], v[36:37], v[40:41]
	v_pk_fma_f32 v[18:19], v[18:19], v[26:27], v[30:31]
	v_pk_fma_f32 v[16:17], v[16:17], v[38:39], v[42:43]
	s_cbranch_vccnz .LBB0_1978
	global_store_dwordx4 v[34:35], v[20:23], off offset:512
	global_store_dwordx4 v[34:35], v[16:19], off offset:528
	s_cbranch_execnz .LBB0_1956

; __device__ __forceinline__ unsigned pk2(float lo, float hi) { f32x2_t v = {lo, hi}; bf16x2_t b = __builtin_convertvector(v, bf16x2_t); return __builtin_bit_cast(unsigned, b); }
; #define BF16_LO(w) __uint_as_float((w) << 16)
; #define BF16_HI(w) __uint_as_float((w) & 0xffff0000u)
;     __device__ __forceinline__ void operator()(const f32x4 (&acc)[2][2][4][2], const Unit& u, int wr, int wc, int fr_in, int fq_in) const {
;     ...
;                 for (int bj = 0; bj < 2; ++bj) {
;                     const size_t off = (size_t)(u.pm * BM + ai * 128 + wr * 64 + m * 16 + fr) * DM + u.pn * BM + bj * HALF + wc * 32 + 8 * fq;
;                     const u32x4 s = *(const u32x4*)(SG + off), q = *(const u32x4*)(hb + off);
;                     const f32x4 s0 = {BF16_LO(s.x), BF16_HI(s.x), BF16_LO(s.y), BF16_HI(s.y)}, s1 = {BF16_LO(s.z), BF16_HI(s.z), BF16_LO(s.w), BF16_HI(s.w)};
;                     const f32x4 b0 = {BF16_LO(q.x), BF16_HI(q.x), BF16_LO(q.y), BF16_HI(q.y)}, b1 = {BF16_LO(q.z), BF16_HI(q.z), BF16_LO(q.w), BF16_HI(q.w)};
;                     const f32x4 h0 = b0 + acc[ai][bj][m][0] * s0, h1 = b1 + acc[ai][bj][m][1] * s1;
;                     if (outf) { *(f32x4*)(outf + off) = h0; *(f32x4*)(outf + off + 4) = h1; }
;                     else { u32x4 w; w.x = pk2(h0[0], h0[1]); w.y = pk2(h0[2], h0[3]); w.z = pk2(h1[0], h1[1]); w.w = pk2(h1[2], h1[3]); *(u32x4*)(hb + off) = w; }
.LBB0_1956:
	s_nop 0
	v_add_u32_e32 v16, 0xb0, v144
	v_ashrrev_i32_e32 v17, 31, v16
	v_lshlrev_b64 v[16:17], 10, v[16:17]
	v_lshl_add_u64 v[18:19], v[16:17], 0, v[146:147]
	v_lshlrev_b64 v[16:17], 1, v[18:19]
	v_lshl_add_u64 v[20:21], s[8:9], 0, v[16:17]
	v_lshl_add_u64 v[16:17], s[18:19], 0, v[16:17]
	global_load_dwordx4 v[22:25], v[20:21], off nt
	global_load_dwordx4 v[26:29], v[16:17], off nt
	s_and_b64 vcc, exec, s[6:7]
	v_lshl_add_u64 v[18:19], v[18:19], 2, s[10:11]
	s_waitcnt vmcnt(0)
	v_lshlrev_b32_e32 v30, 16, v22
	v_and_b32_e32 v31, 0xffff0000, v22
	v_lshlrev_b32_e32 v22, 16, v23
	v_and_b32_e32 v23, 0xffff0000, v23
	v_lshlrev_b32_e32 v32, 16, v24
	v_and_b32_e32 v33, 0xffff0000, v24
	v_lshlrev_b32_e32 v24, 16, v25
	v_and_b32_e32 v25, 0xffff0000, v25
	v_lshlrev_b32_e32 v34, 16, v26
	v_and_b32_e32 v35, 0xffff0000, v26
	v_lshlrev_b32_e32 v26, 16, v27
	v_and_b32_e32 v27, 0xffff0000, v27
	v_lshlrev_b32_e32 v36, 16, v28
	v_and_b32_e32 v37, 0xffff0000, v28
	v_lshlrev_b32_e32 v28, 16, v29
	v_and_b32_e32 v29, 0xffff0000, v29
	v_pk_fma_f32 v[14:15], v[14:15], v[22:23], v[26:27]
	v_pk_fma_f32 v[12:13], v[12:13], v[30:31], v[34:35]
	v_pk_fma_f32 v[10:11], v[10:11], v[24:25], v[28:29]
	v_pk_fma_f32 v[8:9], v[8:9], v[32:33], v[36:37]
	s_cbranch_vccnz .LBB0_1979
	global_store_dwordx4 v[18:19], v[12:15], off
	global_store_dwordx4 v[18:19], v[8:11], off offset:16
	s_cbranch_execnz .LBB0_1959

; __device__ __forceinline__ unsigned pk2(float lo, float hi) { f32x2_t v = {lo, hi}; bf16x2_t b = __builtin_convertvector(v, bf16x2_t); return __builtin_bit_cast(unsigned, b); }
; #define BF16_LO(w) __uint_as_float((w) << 16)
; #define BF16_HI(w) __uint_as_float((w) & 0xffff0000u)
;     __device__ __forceinline__ void operator()(const f32x4 (&acc)[2][2][4][2], const Unit& u, int wr, int wc, int fr_in, int fq_in) const {
;     ...
;                 for (int bj = 0; bj < 2; ++bj) {
;                     const size_t off = (size_t)(u.pm * BM + ai * 128 + wr * 64 + m * 16 + fr) * DM + u.pn * BM + bj * HALF + wc * 32 + 8 * fq;
;                     const u32x4 s = *(const u32x4*)(SG + off), q = *(const u32x4*)(hb + off);
;                     const f32x4 s0 = {BF16_LO(s.x), BF16_HI(s.x), BF16_LO(s.y), BF16_HI(s.y)}, s1 = {BF16_LO(s.z), BF16_HI(s.z), BF16_LO(s.w), BF16_HI(s.w)};
;                     const f32x4 b0 = {BF16_LO(q.x), BF16_HI(q.x), BF16_LO(q.y), BF16_HI(q.y)}, b1 = {BF16_LO(q.z), BF16_HI(q.z), BF16_LO(q.w), BF16_HI(q.w)};
;                     const f32x4 h0 = b0 + acc[ai][bj][m][0] * s0, h1 = b1 + acc[ai][bj][m][1] * s1;
;                     if (outf) { *(f32x4*)(outf + off) = h0; *(f32x4*)(outf + off + 4) = h1; }
;                     else { u32x4 w; w.x = pk2(h0[0], h0[1]); w.y = pk2(h0[2], h0[3]); w.z = pk2(h1[0], h1[1]); w.w = pk2(h1[2], h1[3]); *(u32x4*)(hb + off) = w; }
.LBB0_1959:
	global_load_dwordx4 v[8:11], v[20:21], off offset:256 nt
	s_nop 0
	global_load_dwordx4 v[12:15], v[16:17], off offset:256 nt
	s_and_b64 vcc, exec, s[6:7]
	s_waitcnt vmcnt(0)
	v_lshlrev_b32_e32 v20, 16, v8
	v_and_b32_e32 v21, 0xffff0000, v8
	v_lshlrev_b32_e32 v8, 16, v9
	v_and_b32_e32 v9, 0xffff0000, v9
	v_lshlrev_b32_e32 v22, 16, v10
	v_and_b32_e32 v23, 0xffff0000, v10
	v_lshlrev_b32_e32 v10, 16, v11
	v_and_b32_e32 v11, 0xffff0000, v11
	v_lshlrev_b32_e32 v24, 16, v12
	v_and_b32_e32 v25, 0xffff0000, v12
	v_lshlrev_b32_e32 v12, 16, v13
	v_and_b32_e32 v13, 0xffff0000, v13
	v_lshlrev_b32_e32 v26, 16, v14
	v_and_b32_e32 v27, 0xffff0000, v14
	v_lshlrev_b32_e32 v14, 16, v15
	v_and_b32_e32 v15, 0xffff0000, v15
	v_pk_fma_f32 v[6:7], v[6:7], v[8:9], v[12:13]
	v_pk_fma_f32 v[4:5], v[4:5], v[20:21], v[24:25]
	v_pk_fma_f32 v[2:3], v[2:3], v[10:11], v[14:15]
	v_pk_fma_f32 v[0:1], v[0:1], v[22:23], v[26:27]
	s_cbranch_vccnz .LBB0_1980
	global_store_dwordx4 v[18:19], v[4:7], off offset:512
	global_store_dwordx4 v[18:19], v[0:3], off offset:528
	s_cbranch_execnz .LBB0_1962
